# stack of small edits on v41: EpiProj log chains interleaved, row-scale fills unrolled, P3 out-gain via LDS, publish after attention, DMA scalar-base form, K-loop SALU before barrier
# speedup vs baseline: 1.0033x; 1.0033x over previous
; #define LAS __attribute__((address_space(3)))
; template <bool COOP>
; __global__ void __launch_bounds__(NWAVES * 64, 2) fwd(Args args) {
;     ...
;         LAS float* rsc1 = (LAS float*)(F.lds + 131072 + 1024); const int rbase1 = (int)(blockIdx.x & 7) * 2048; const bool rs1_cached = (F.G == 256);
;         if (rs1_cached) { for (int r = F.tid; r < 2048; r += NWAVES * 64) rsc1[r] = F.RSTD1[rbase1 + r]; __syncthreads(); }
.LBB0_97:
	v_lshl_add_u64 v[6:7], s[4:5], 1, v[2:3]
	global_load_dword v5, v[2:3], off
	global_load_dword v8, v[2:3], off offset:2048
	global_load_dword v9, v[6:7], off
	global_load_dword v11, v[6:7], off offset:2048
	s_waitcnt vmcnt(3)
	ds_write_b32 v4, v5
	s_waitcnt vmcnt(2)
	ds_write_b32 v4, v8 offset:2048
	s_waitcnt vmcnt(1)
	ds_write_b32 v4, v9 offset:4096
	s_waitcnt vmcnt(0)
	ds_write_b32 v4, v11 offset:6144
	s_or_b64 exec, exec, s[0:1]
	s_add_i32 s86, 0, 0x20400
	s_waitcnt lgkmcnt(0)
	s_barrier

; #define PG8_STAGE(bufoff, gbase, voff) do { _Pragma("unroll") for (int _i = 0; _i < 2; ++_i) \
;         __builtin_amdgcn_global_load_lds((const unsigned*)((const char*)(gbase) + (voff)[_i]), (PG8_LAS unsigned*)(lds + (bufoff) + ldsw + _i * 8192), 16, 0, 0); } while (0)
; #define PG8_LDA(dst, b, h) do { _Pragma("unroll") for (int m = 0; m < 4; ++m) _Pragma("unroll") for (int k = 0; k < 2; ++k) dst[m][k] = *(const PG8_LAS bf16x8*)(lds + PG8_SA(b, h) + aoff + m * 2048 + k * 1024); } while (0)
; #define PG8_LDB(dst, b, h) do { _Pragma("unroll") for (int n = 0; n < 2; ++n) _Pragma("unroll") for (int k = 0; k < 2; ++k) dst[n][k] = *(const PG8_LAS bf16x8*)(lds + PG8_SB(b, h) + boff + n * 2048 + k * 1024); } while (0)
; #define PG8_MMA(ai, bj, At, Bt) do { __builtin_amdgcn_s_setprio(1); _Pragma("unroll") for (int m = 0; m < 4; ++m) _Pragma("unroll") for (int n = 0; n < 2; ++n) _Pragma("unroll") for (int k = 0; k < 2; ++k) \
;         acc[ai][bj][m][n] = __builtin_amdgcn_mfma_f32_16x16x32_bf16(Bt[n][k], At[m][k], acc[ai][bj][m][n], 0, 0, 0); __builtin_amdgcn_s_setprio(0); } while (0)
; #define PG8_WAIT_V(n) asm volatile("s_waitcnt vmcnt(" #n ")" ::: "memory")
; #define PG8_WAIT_L(n) asm volatile("s_waitcnt lgkmcnt(" #n ")" ::: "memory")
; #define PG8_BAR __builtin_amdgcn_s_barrier()
; #define PG8_SCHED __builtin_amdgcn_sched_barrier(0)
; template <class Epi, class Sched, bool ALIGN_EPI = false, bool SP2 = false>
; __device__ __forceinline__ void gemm_phase(PG8_LAS unsigned char* lds, const Gemm g, const Sched& S, const Epi& E) {
;     ...
;             PG8_LDB(B0, 0, 0); PG8_LDB(B1, 0, 1); PG8_SCHED; PG8_LDA(At, 0, 0); PG8_STAGE(PG8_SA(1, 1), a1 + hstep, voffA);
;             PG8_WAIT_V(8); PG8_WAIT_L(0); PG8_BAR; PG8_MMA(0, 0, At, B0); PG8_MMA(0, 1, At, B1); PG8_BAR; PG8_SCHED;
;             PG8_LDA(At, 0, 1); PG8_STAGE(PG8_SB(0, 0), b2, voffB); PG8_STAGE(PG8_SB(0, 1), b2 + hstep, voffB); PG8_STAGE(PG8_SA(0, 0), a2, voffA);
;             PG8_WAIT_V(8); PG8_WAIT_L(0); PG8_BAR; PG8_MMA(1, 0, At, B0); PG8_MMA(1, 1, At, B1); PG8_BAR; PG8_SCHED;
.LBB0_110:
	ds_read_b128 v[146:149], v160
	ds_read_b128 v[150:153], v160 offset:1024
	ds_read_b128 v[154:157], v160 offset:2048
	ds_read_b128 v[166:169], v160 offset:3072
	ds_read_b128 v[170:173], v161
	ds_read_b128 v[174:177], v161 offset:1024
	ds_read_b128 v[178:181], v161 offset:2048
	ds_read_b128 v[182:185], v161 offset:3072
	s_add_u32 s8, s6, 0xfffc0080
	s_addc_u32 s9, s7, -1
	s_cmp_eq_u32 s84, 12
	s_cselect_b32 s83, s1, s9
	s_cselect_b32 s82, s33, s8
	s_cselect_b32 s9, s60, s75
	s_cselect_b32 s8, s61, s73
	v_lshl_add_u64 v[220:221], s[6:7], 0, v[138:139]
	s_add_i32 m0, s81, 0xc000
	ds_read_b128 v[186:189], v162
	ds_read_b128 v[190:193], v162 offset:1024
	ds_read_b128 v[194:197], v162 offset:2048
	ds_read_b128 v[198:201], v162 offset:3072
	ds_read_b128 v[202:205], v162 offset:4096
	ds_read_b128 v[208:211], v162 offset:5120
	ds_read_b128 v[212:215], v162 offset:6144
	ds_read_b128 v[216:219], v162 offset:7168
	global_load_lds_dwordx4 v[220:221], off
	v_lshl_add_u64 v[220:221], s[6:7], 0, v[140:141]
	s_add_i32 m0, s81, 0xe000
	s_nop 0
	global_load_lds_dwordx4 v[220:221], off
	s_waitcnt vmcnt(8)
	s_waitcnt lgkmcnt(0)
	s_barrier
	s_setprio 1
	s_waitcnt lgkmcnt(0)
	v_mfma_f32_16x16x32_bf16 v[126:129], v[146:149], v[186:189], v[126:129]
	v_mfma_f32_16x16x32_bf16 v[122:125], v[154:157], v[186:189], v[122:125]
	v_mfma_f32_16x16x32_bf16 v[118:121], v[146:149], v[194:197], v[118:121]
	v_mfma_f32_16x16x32_bf16 v[114:117], v[154:157], v[194:197], v[114:117]
	v_mfma_f32_16x16x32_bf16 v[110:113], v[146:149], v[202:205], v[110:113]
	v_mfma_f32_16x16x32_bf16 v[106:109], v[154:157], v[202:205], v[106:109]
	v_mfma_f32_16x16x32_bf16 v[102:105], v[146:149], v[212:215], v[102:105]
	v_mfma_f32_16x16x32_bf16 v[98:101], v[154:157], v[212:215], v[98:101]
	v_mfma_f32_16x16x32_bf16 v[126:129], v[150:153], v[190:193], v[126:129]
	v_mfma_f32_16x16x32_bf16 v[122:125], v[166:169], v[190:193], v[122:125]
	v_mfma_f32_16x16x32_bf16 v[118:121], v[150:153], v[198:201], v[118:121]
	v_mfma_f32_16x16x32_bf16 v[114:117], v[166:169], v[198:201], v[114:117]
	v_mfma_f32_16x16x32_bf16 v[110:113], v[150:153], v[208:211], v[110:113]
	v_mfma_f32_16x16x32_bf16 v[106:109], v[166:169], v[208:211], v[106:109]
	v_mfma_f32_16x16x32_bf16 v[102:105], v[150:153], v[216:219], v[102:105]
	v_mfma_f32_16x16x32_bf16 v[98:101], v[166:169], v[216:219], v[98:101]
	s_setprio 0
	s_setprio 1
	v_mfma_f32_16x16x32_bf16 v[62:65], v[170:173], v[186:189], v[62:65]
	v_mfma_f32_16x16x32_bf16 v[58:61], v[178:181], v[186:189], v[58:61]
	v_mfma_f32_16x16x32_bf16 v[54:57], v[170:173], v[194:197], v[54:57]
	v_mfma_f32_16x16x32_bf16 v[50:53], v[178:181], v[194:197], v[50:53]
	v_mfma_f32_16x16x32_bf16 v[46:49], v[170:173], v[202:205], v[46:49]
	v_mfma_f32_16x16x32_bf16 v[42:45], v[178:181], v[202:205], v[42:45]
	v_mfma_f32_16x16x32_bf16 v[38:41], v[170:173], v[212:215], v[38:41]
	v_mfma_f32_16x16x32_bf16 v[34:37], v[178:181], v[212:215], v[34:37]
	v_mfma_f32_16x16x32_bf16 v[62:65], v[174:177], v[190:193], v[62:65]
	v_mfma_f32_16x16x32_bf16 v[58:61], v[182:185], v[190:193], v[58:61]
	v_mfma_f32_16x16x32_bf16 v[54:57], v[174:177], v[198:201], v[54:57]
	v_mfma_f32_16x16x32_bf16 v[50:53], v[182:185], v[198:201], v[50:53]
	v_mfma_f32_16x16x32_bf16 v[46:49], v[174:177], v[208:211], v[46:49]
	v_mfma_f32_16x16x32_bf16 v[42:45], v[182:185], v[208:211], v[42:45]
	v_mfma_f32_16x16x32_bf16 v[38:41], v[174:177], v[216:219], v[38:41]
	v_mfma_f32_16x16x32_bf16 v[34:37], v[182:185], v[216:219], v[34:37]
	s_setprio 0
	s_barrier
	s_add_i32 s85, s30, s87
	s_mov_b32 m0, s85
	ds_read_b128 v[186:189], v162 offset:16384
	ds_read_b128 v[190:193], v162 offset:17408
	ds_read_b128 v[194:197], v162 offset:18432
	ds_read_b128 v[198:201], v162 offset:19456
	ds_read_b128 v[202:205], v162 offset:20480
	ds_read_b128 v[208:211], v162 offset:21504
	ds_read_b128 v[212:215], v162 offset:22528
	ds_read_b128 v[216:219], v162 offset:23552
	global_load_lds_dwordx4 v132, s[8:9]
	s_add_i32 m0, s85, 0x2000
	s_add_u32 vcc_lo, s8, 0x40000
	v_lshl_add_u64 v[222:223], s[8:9], 0, v[136:137]
	s_addc_u32 vcc_hi, s9, 0
	s_add_i32 s85, s31, s87
	global_load_lds_dwordx4 v136, s[8:9]
	s_mov_b32 m0, s85
	v_lshl_add_u64 v[226:227], s[82:83], 0, v[134:135]
	global_load_lds_dwordx4 v132, vcc
	s_add_i32 m0, s85, 0x2000
	s_nop 0
	global_load_lds_dwordx4 v136, vcc
	v_lshl_add_u64 v[224:225], s[82:83], 0, v[130:131]
	s_mov_b32 m0, s81
	s_nop 0
	global_load_lds_dwordx4 v130, s[82:83]
	s_mov_b32 m0, s88
	s_nop 0
	global_load_lds_dwordx4 v134, s[82:83]
	s_waitcnt vmcnt(8)
	s_waitcnt lgkmcnt(0)
	s_barrier
; #define PG8_STAGE(bufoff, gbase, voff) do { _Pragma("unroll") for (int _i = 0; _i < 2; ++_i) \
;         __builtin_amdgcn_global_load_lds((const unsigned*)((const char*)(gbase) + (voff)[_i]), (PG8_LAS unsigned*)(lds + (bufoff) + ldsw + _i * 8192), 16, 0, 0); } while (0)
; #define PG8_LDA(dst, b, h) do { _Pragma("unroll") for (int m = 0; m < 4; ++m) _Pragma("unroll") for (int k = 0; k < 2; ++k) dst[m][k] = *(const PG8_LAS bf16x8*)(lds + PG8_SA(b, h) + aoff + m * 2048 + k * 1024); } while (0)
; #define PG8_LDB(dst, b, h) do { _Pragma("unroll") for (int n = 0; n < 2; ++n) _Pragma("unroll") for (int k = 0; k < 2; ++k) dst[n][k] = *(const PG8_LAS bf16x8*)(lds + PG8_SB(b, h) + boff + n * 2048 + k * 1024); } while (0)
; #define PG8_MMA(ai, bj, At, Bt) do { __builtin_amdgcn_s_setprio(1); _Pragma("unroll") for (int m = 0; m < 4; ++m) _Pragma("unroll") for (int n = 0; n < 2; ++n) _Pragma("unroll") for (int k = 0; k < 2; ++k) \
;         acc[ai][bj][m][n] = __builtin_amdgcn_mfma_f32_16x16x32_bf16(Bt[n][k], At[m][k], acc[ai][bj][m][n], 0, 0, 0); __builtin_amdgcn_s_setprio(0); } while (0)
; #define PG8_WAIT_V(n) asm volatile("s_waitcnt vmcnt(" #n ")" ::: "memory")
; #define PG8_WAIT_L(n) asm volatile("s_waitcnt lgkmcnt(" #n ")" ::: "memory")
; #define PG8_BAR __builtin_amdgcn_s_barrier()
; #define PG8_SCHED __builtin_amdgcn_sched_barrier(0)
; template <class Epi, class Sched, bool ALIGN_EPI = false, bool SP2 = false>
; __device__ __forceinline__ void gemm_phase(PG8_LAS unsigned char* lds, const Gemm g, const Sched& S, const Epi& E) {
;     ...
;             PG8_WAIT_V(8); PG8_WAIT_L(0); PG8_BAR; PG8_MMA(1, 0, At, B0); PG8_MMA(1, 1, At, B1); PG8_BAR; PG8_SCHED;
;             PG8_LDB(B0, 1, 0); PG8_LDB(B1, 1, 1); PG8_SCHED; PG8_LDA(At, 1, 0); PG8_STAGE(PG8_SA(0, 1), a2 + hstep, voffA);
;             PG8_WAIT_V(8); PG8_WAIT_L(0); PG8_BAR; PG8_MMA(0, 0, At, B0); PG8_MMA(0, 1, At, B1); PG8_BAR; PG8_SCHED;
	s_setprio 1
	s_waitcnt lgkmcnt(0)
	v_mfma_f32_16x16x32_bf16 v[94:97], v[146:149], v[186:189], v[94:97]
	v_mfma_f32_16x16x32_bf16 v[90:93], v[154:157], v[186:189], v[90:93]
	v_mfma_f32_16x16x32_bf16 v[86:89], v[146:149], v[194:197], v[86:89]
	v_mfma_f32_16x16x32_bf16 v[82:85], v[154:157], v[194:197], v[82:85]
	v_mfma_f32_16x16x32_bf16 v[78:81], v[146:149], v[202:205], v[78:81]
	v_mfma_f32_16x16x32_bf16 v[74:77], v[154:157], v[202:205], v[74:77]
	v_mfma_f32_16x16x32_bf16 v[70:73], v[146:149], v[212:215], v[70:73]
	v_mfma_f32_16x16x32_bf16 v[66:69], v[154:157], v[212:215], v[66:69]
	v_mfma_f32_16x16x32_bf16 v[94:97], v[150:153], v[190:193], v[94:97]
	v_mfma_f32_16x16x32_bf16 v[90:93], v[166:169], v[190:193], v[90:93]
	v_mfma_f32_16x16x32_bf16 v[86:89], v[150:153], v[198:201], v[86:89]
	v_mfma_f32_16x16x32_bf16 v[82:85], v[166:169], v[198:201], v[82:85]
	v_mfma_f32_16x16x32_bf16 v[78:81], v[150:153], v[208:211], v[78:81]
	v_mfma_f32_16x16x32_bf16 v[74:77], v[166:169], v[208:211], v[74:77]
	v_mfma_f32_16x16x32_bf16 v[70:73], v[150:153], v[216:219], v[70:73]
	v_mfma_f32_16x16x32_bf16 v[66:69], v[166:169], v[216:219], v[66:69]
	s_setprio 0
	s_setprio 1
	v_mfma_f32_16x16x32_bf16 v[30:33], v[170:173], v[186:189], v[30:33]
	v_mfma_f32_16x16x32_bf16 v[26:29], v[178:181], v[186:189], v[26:29]
	v_mfma_f32_16x16x32_bf16 v[22:25], v[170:173], v[194:197], v[22:25]
	v_mfma_f32_16x16x32_bf16 v[18:21], v[178:181], v[194:197], v[18:21]
	v_mfma_f32_16x16x32_bf16 v[14:17], v[170:173], v[202:205], v[14:17]
	v_mfma_f32_16x16x32_bf16 v[10:13], v[178:181], v[202:205], v[10:13]
	v_mfma_f32_16x16x32_bf16 v[6:9], v[170:173], v[212:215], v[6:9]
	v_mfma_f32_16x16x32_bf16 v[2:5], v[178:181], v[212:215], v[2:5]
	v_mfma_f32_16x16x32_bf16 v[30:33], v[174:177], v[190:193], v[30:33]
	v_mfma_f32_16x16x32_bf16 v[26:29], v[182:185], v[190:193], v[26:29]
	v_mfma_f32_16x16x32_bf16 v[22:25], v[174:177], v[198:201], v[22:25]
	v_mfma_f32_16x16x32_bf16 v[18:21], v[182:185], v[198:201], v[18:21]
	v_mfma_f32_16x16x32_bf16 v[14:17], v[174:177], v[208:211], v[14:17]
	v_mfma_f32_16x16x32_bf16 v[10:13], v[182:185], v[208:211], v[10:13]
	v_mfma_f32_16x16x32_bf16 v[6:9], v[174:177], v[216:219], v[6:9]
	v_mfma_f32_16x16x32_bf16 v[2:5], v[182:185], v[216:219], v[2:5]
	s_setprio 0
	s_barrier
	s_add_i32 s85, 0, 0x18000
	v_add_u32_e32 v165, s85, v158
	s_add_i32 vcc_lo, 0, 0x1c000
	ds_read_b128 v[146:149], v165
	ds_read_b128 v[150:153], v165 offset:1024
	ds_read_b128 v[154:157], v165 offset:2048
	ds_read_b128 v[166:169], v165 offset:3072
	v_add_u32_e32 v165, vcc_lo, v158
	ds_read_b128 v[170:173], v165
	ds_read_b128 v[174:177], v165 offset:1024
	ds_read_b128 v[178:181], v165 offset:2048
	ds_read_b128 v[182:185], v165 offset:3072
	s_add_u32 s82, s82, 0x40000
	s_addc_u32 s83, s83, 0
	s_mov_b32 m0, s89
	ds_read_b128 v[186:189], v162 offset:32768
	ds_read_b128 v[190:193], v162 offset:33792
	ds_read_b128 v[194:197], v162 offset:34816
	ds_read_b128 v[198:201], v162 offset:35840
	ds_read_b128 v[202:205], v162 offset:36864
	ds_read_b128 v[208:211], v162 offset:37888
	ds_read_b128 v[212:215], v162 offset:38912
	ds_read_b128 v[216:219], v162 offset:39936
	global_load_lds_dwordx4 v130, s[82:83]
	s_mov_b32 m0, s90
	s_nop 0
	global_load_lds_dwordx4 v134, s[82:83]
	s_waitcnt vmcnt(8)
	s_waitcnt lgkmcnt(0)
	s_barrier
	s_setprio 1
	s_waitcnt lgkmcnt(0)
	v_mfma_f32_16x16x32_bf16 v[126:129], v[146:149], v[186:189], v[126:129]
	v_mfma_f32_16x16x32_bf16 v[122:125], v[154:157], v[186:189], v[122:125]
	v_mfma_f32_16x16x32_bf16 v[118:121], v[146:149], v[194:197], v[118:121]
	v_mfma_f32_16x16x32_bf16 v[114:117], v[154:157], v[194:197], v[114:117]
	v_mfma_f32_16x16x32_bf16 v[110:113], v[146:149], v[202:205], v[110:113]
	v_mfma_f32_16x16x32_bf16 v[106:109], v[154:157], v[202:205], v[106:109]
	v_mfma_f32_16x16x32_bf16 v[102:105], v[146:149], v[212:215], v[102:105]
	v_mfma_f32_16x16x32_bf16 v[98:101], v[154:157], v[212:215], v[98:101]
	v_mfma_f32_16x16x32_bf16 v[126:129], v[150:153], v[190:193], v[126:129]
	v_mfma_f32_16x16x32_bf16 v[122:125], v[166:169], v[190:193], v[122:125]
	v_mfma_f32_16x16x32_bf16 v[118:121], v[150:153], v[198:201], v[118:121]
	v_mfma_f32_16x16x32_bf16 v[114:117], v[166:169], v[198:201], v[114:117]
	v_mfma_f32_16x16x32_bf16 v[110:113], v[150:153], v[208:211], v[110:113]
	v_mfma_f32_16x16x32_bf16 v[106:109], v[166:169], v[208:211], v[106:109]
	v_mfma_f32_16x16x32_bf16 v[102:105], v[150:153], v[216:219], v[102:105]
	v_mfma_f32_16x16x32_bf16 v[98:101], v[166:169], v[216:219], v[98:101]
	s_setprio 0
	s_setprio 1
	v_mfma_f32_16x16x32_bf16 v[62:65], v[170:173], v[186:189], v[62:65]
	v_mfma_f32_16x16x32_bf16 v[58:61], v[178:181], v[186:189], v[58:61]
	v_mfma_f32_16x16x32_bf16 v[54:57], v[170:173], v[194:197], v[54:57]
	v_mfma_f32_16x16x32_bf16 v[50:53], v[178:181], v[194:197], v[50:53]
	v_mfma_f32_16x16x32_bf16 v[46:49], v[170:173], v[202:205], v[46:49]
	v_mfma_f32_16x16x32_bf16 v[42:45], v[178:181], v[202:205], v[42:45]
	v_mfma_f32_16x16x32_bf16 v[38:41], v[170:173], v[212:215], v[38:41]
	v_mfma_f32_16x16x32_bf16 v[34:37], v[178:181], v[212:215], v[34:37]
	v_mfma_f32_16x16x32_bf16 v[62:65], v[174:177], v[190:193], v[62:65]
	v_mfma_f32_16x16x32_bf16 v[58:61], v[182:185], v[190:193], v[58:61]
	v_mfma_f32_16x16x32_bf16 v[54:57], v[174:177], v[198:201], v[54:57]
	v_mfma_f32_16x16x32_bf16 v[50:53], v[182:185], v[198:201], v[50:53]
	v_mfma_f32_16x16x32_bf16 v[46:49], v[174:177], v[208:211], v[46:49]
	v_mfma_f32_16x16x32_bf16 v[42:45], v[182:185], v[208:211], v[42:45]
	v_mfma_f32_16x16x32_bf16 v[38:41], v[174:177], v[216:219], v[38:41]
	v_mfma_f32_16x16x32_bf16 v[34:37], v[182:185], v[216:219], v[34:37]
	s_setprio 0
	s_barrier
; #define PG8_STAGE(bufoff, gbase, voff) do { _Pragma("unroll") for (int _i = 0; _i < 2; ++_i) \
;         __builtin_amdgcn_global_load_lds((const unsigned*)((const char*)(gbase) + (voff)[_i]), (PG8_LAS unsigned*)(lds + (bufoff) + ldsw + _i * 8192), 16, 0, 0); } while (0)
; #define PG8_LDA(dst, b, h) do { _Pragma("unroll") for (int m = 0; m < 4; ++m) _Pragma("unroll") for (int k = 0; k < 2; ++k) dst[m][k] = *(const PG8_LAS bf16x8*)(lds + PG8_SA(b, h) + aoff + m * 2048 + k * 1024); } while (0)
; #define PG8_MMA(ai, bj, At, Bt) do { __builtin_amdgcn_s_setprio(1); _Pragma("unroll") for (int m = 0; m < 4; ++m) _Pragma("unroll") for (int n = 0; n < 2; ++n) _Pragma("unroll") for (int k = 0; k < 2; ++k) \
;         acc[ai][bj][m][n] = __builtin_amdgcn_mfma_f32_16x16x32_bf16(Bt[n][k], At[m][k], acc[ai][bj][m][n], 0, 0, 0); __builtin_amdgcn_s_setprio(0); } while (0)
; #define PG8_WAIT_V(n) asm volatile("s_waitcnt vmcnt(" #n ")" ::: "memory")
; #define PG8_WAIT_L(n) asm volatile("s_waitcnt lgkmcnt(" #n ")" ::: "memory")
; #define PG8_BAR __builtin_amdgcn_s_barrier()
; #define PG8_SCHED __builtin_amdgcn_sched_barrier(0)
; template <class Epi, class Sched, bool ALIGN_EPI = false, bool SP2 = false>
; __device__ __forceinline__ void gemm_phase(PG8_LAS unsigned char* lds, const Gemm g, const Sched& S, const Epi& E) {
;     ...
;         for (int t = 0; t < nt; t += 2) {
;     ...
;             PG8_LDA(At, 1, 1); PG8_STAGE(PG8_SB(1, 0), b3, voffB); PG8_STAGE(PG8_SB(1, 1), b3 + hstep, voffB); PG8_STAGE(PG8_SA(1, 0), a3, voffA);
;             PG8_WAIT_V(8); PG8_WAIT_L(0); PG8_BAR; PG8_MMA(1, 0, At, B0); PG8_MMA(1, 1, At, B1); PG8_BAR; PG8_SCHED;
	s_add_i32 s82, s85, s87
	s_mov_b32 m0, s82
	ds_read_b128 v[186:189], v162 offset:49152
	ds_read_b128 v[190:193], v162 offset:50176
	ds_read_b128 v[194:197], v162 offset:51200
	ds_read_b128 v[198:201], v162 offset:52224
	ds_read_b128 v[202:205], v162 offset:53248
	ds_read_b128 v[208:211], v162 offset:54272
	ds_read_b128 v[212:215], v162 offset:55296
	ds_read_b128 v[216:219], v162 offset:56320
	s_add_u32 s98, s8, s26
	s_addc_u32 s99, s9, s27
	global_load_lds_dwordx4 v132, s[98:99]
	s_add_i32 m0, s82, 0x2000
	s_add_u32 s8, s8, 0x40080
	v_lshl_add_u64 v[220:221], v[222:223], 0, s[26:27]
	s_addc_u32 s9, s9, 0
	s_add_i32 s82, vcc_lo, s87
	global_load_lds_dwordx4 v[220:221], off
	s_mov_b32 m0, s82
	s_nop 0
	global_load_lds_dwordx4 v132, s[8:9]
	s_add_i32 m0, s82, 0x2000
	s_nop 0
	global_load_lds_dwordx4 v136, s[8:9]
	v_lshl_add_u64 v[220:221], v[224:225], 0, s[26:27]
	s_mov_b32 m0, s92
	s_nop 0
	global_load_lds_dwordx4 v[220:221], off
	v_lshl_add_u64 v[220:221], v[226:227], 0, s[26:27]
	s_mov_b32 m0, s93
	s_nop 0
	global_load_lds_dwordx4 v[220:221], off
	s_waitcnt vmcnt(8)
	s_waitcnt lgkmcnt(0)
	s_barrier
	s_setprio 1
	s_waitcnt lgkmcnt(0)
	v_mfma_f32_16x16x32_bf16 v[94:97], v[146:149], v[186:189], v[94:97]
	v_mfma_f32_16x16x32_bf16 v[90:93], v[154:157], v[186:189], v[90:93]
	v_mfma_f32_16x16x32_bf16 v[86:89], v[146:149], v[194:197], v[86:89]
	v_mfma_f32_16x16x32_bf16 v[82:85], v[154:157], v[194:197], v[82:85]
	v_mfma_f32_16x16x32_bf16 v[78:81], v[146:149], v[202:205], v[78:81]
	v_mfma_f32_16x16x32_bf16 v[74:77], v[154:157], v[202:205], v[74:77]
	v_mfma_f32_16x16x32_bf16 v[70:73], v[146:149], v[212:215], v[70:73]
	v_mfma_f32_16x16x32_bf16 v[66:69], v[154:157], v[212:215], v[66:69]
	v_mfma_f32_16x16x32_bf16 v[94:97], v[150:153], v[190:193], v[94:97]
	v_mfma_f32_16x16x32_bf16 v[90:93], v[166:169], v[190:193], v[90:93]
	v_mfma_f32_16x16x32_bf16 v[86:89], v[150:153], v[198:201], v[86:89]
	v_mfma_f32_16x16x32_bf16 v[82:85], v[166:169], v[198:201], v[82:85]
	v_mfma_f32_16x16x32_bf16 v[78:81], v[150:153], v[208:211], v[78:81]
	v_mfma_f32_16x16x32_bf16 v[74:77], v[166:169], v[208:211], v[74:77]
	v_mfma_f32_16x16x32_bf16 v[70:73], v[150:153], v[216:219], v[70:73]
	v_mfma_f32_16x16x32_bf16 v[66:69], v[166:169], v[216:219], v[66:69]
	s_setprio 0
	s_setprio 1
	v_mfma_f32_16x16x32_bf16 v[30:33], v[170:173], v[186:189], v[30:33]
	v_mfma_f32_16x16x32_bf16 v[26:29], v[178:181], v[186:189], v[26:29]
	v_mfma_f32_16x16x32_bf16 v[22:25], v[170:173], v[194:197], v[22:25]
	v_mfma_f32_16x16x32_bf16 v[18:21], v[178:181], v[194:197], v[18:21]
	v_mfma_f32_16x16x32_bf16 v[14:17], v[170:173], v[202:205], v[14:17]
	v_mfma_f32_16x16x32_bf16 v[10:13], v[178:181], v[202:205], v[10:13]
	v_mfma_f32_16x16x32_bf16 v[6:9], v[170:173], v[212:215], v[6:9]
	v_mfma_f32_16x16x32_bf16 v[2:5], v[178:181], v[212:215], v[2:5]
	v_mfma_f32_16x16x32_bf16 v[30:33], v[174:177], v[190:193], v[30:33]
	v_mfma_f32_16x16x32_bf16 v[26:29], v[182:185], v[190:193], v[26:29]
	v_mfma_f32_16x16x32_bf16 v[22:25], v[174:177], v[198:201], v[22:25]
	v_mfma_f32_16x16x32_bf16 v[18:21], v[182:185], v[198:201], v[18:21]
	v_mfma_f32_16x16x32_bf16 v[14:17], v[174:177], v[208:211], v[14:17]
	v_mfma_f32_16x16x32_bf16 v[10:13], v[182:185], v[208:211], v[10:13]
	v_mfma_f32_16x16x32_bf16 v[6:9], v[174:177], v[216:219], v[6:9]
	v_mfma_f32_16x16x32_bf16 v[2:5], v[182:185], v[216:219], v[2:5]
	s_setprio 0
	s_add_i32 s84, s84, 2
	s_add_u32 s6, s6, 0x100
	s_addc_u32 s7, s7, 0
	s_add_u32 s73, s73, 0x100
	s_addc_u32 s75, s75, 0
	s_cmp_gt_u32 s84, 13
	s_barrier
	s_cbranch_scc0 .LBB0_110
	s_and_b64 vcc, exec, s[68:69]
	s_cbranch_vccz .LBB0_113
	s_barrier

;     __device__ __forceinline__ void operator()(const f32x4 (&acc)[2][2][4][2], const Unit& u, int wr, int wc, int fr, int fq) const {
;     ...
;                 for (int m = 0; m < 4; ++m) {
;                     const int row = row0 + ai * HALF + m * 16; const float rs = rsc ? rsc[row - rbase] : rstd[row];
;                     float v[8];
; #pragma unroll
;                     for (int i = 0; i < 4; ++i) { v[i] = acc[ai][bj][m][0][i] * rs; v[4 + i] = acc[ai][bj][m][1][i] * rs; }
;                     if (seg == 0) {
; #pragma unroll
;                         for (int i = 0; i < 8; ++i) v[i] = v[i] * __builtin_amdgcn_rcpf(1.0f + __expf(-v[i])) * 0.08838834764831845f;
;                     } else if (seg == 1) {
; #pragma unroll
;                         for (int i = 0; i < 8; ++i) { const float s = __builtin_amdgcn_rcpf(1.0f + __expf(-v[i])); v[i] = __logf(lb[i] + (1.0f - lb[i]) * s); }
.LBB0_124:
	v_mul_f32_e32 v174, 0xbfb8aa3b, v126
	v_sub_f32_e32 v175, 1.0, v173
	v_sub_f32_e32 v176, 1.0, v172
	v_sub_f32_e32 v177, 1.0, v171
	v_sub_f32_e32 v178, 1.0, v170
	v_sub_f32_e32 v179, 1.0, v169
	v_sub_f32_e32 v180, 1.0, v168
	v_sub_f32_e32 v181, 1.0, v167
	v_sub_f32_e32 v182, 1.0, v166
	v_mul_f32_e32 v185, 0xbfb8aa3b, v127
	v_mul_f32_e32 v188, 0xbfb8aa3b, v128
	v_mul_f32_e32 v191, 0xbfb8aa3b, v129
	v_mul_f32_e32 v194, 0xbfb8aa3b, v122
	v_mul_f32_e32 v197, 0xbfb8aa3b, v123
	v_mul_f32_e32 v200, 0xbfb8aa3b, v124
	v_mul_f32_e32 v147, 0xbfb8aa3b, v125
	v_exp_f32_e32 v174, v174
	v_exp_f32_e32 v185, v185
	v_exp_f32_e32 v188, v188
	v_exp_f32_e32 v191, v191
	v_exp_f32_e32 v194, v194
	v_exp_f32_e32 v197, v197
	v_exp_f32_e32 v200, v200
	v_exp_f32_e32 v147, v147
	v_add_f32_e32 v174, 1.0, v174
	v_add_f32_e32 v185, 1.0, v185
	v_add_f32_e32 v188, 1.0, v188
	v_add_f32_e32 v191, 1.0, v191
	v_add_f32_e32 v194, 1.0, v194
	v_add_f32_e32 v197, 1.0, v197
	v_add_f32_e32 v200, 1.0, v200
	v_add_f32_e32 v147, 1.0, v147
	v_rcp_f32_e32 v174, v174
	v_rcp_f32_e32 v185, v185
	v_rcp_f32_e32 v188, v188
	v_rcp_f32_e32 v191, v191
	v_rcp_f32_e32 v194, v194
	v_rcp_f32_e32 v197, v197
	v_rcp_f32_e32 v200, v200
	v_rcp_f32_e32 v147, v147
	v_fma_f32 v174, v175, v174, v173
	v_fma_f32 v185, v176, v185, v172
	v_fma_f32 v188, v177, v188, v171
	v_fma_f32 v191, v178, v191, v170
	v_fma_f32 v194, v179, v194, v169
	v_fma_f32 v197, v180, v197, v168
	v_fma_f32 v200, v181, v200, v167
	v_fma_f32 v147, v182, v147, v166
	v_cmp_gt_f32_e64 s[0:1], s62, v174
	v_cmp_gt_f32_e64 s[8:9], s62, v185
	v_cmp_gt_f32_e64 s[32:33], s62, v188
	v_cmp_gt_f32_e64 s[60:61], s62, v191
	v_cndmask_b32_e64 v183, 0, 32, s[0:1]
	v_cndmask_b32_e64 v150, 0, v163, s[0:1]
	v_cmp_gt_f32_e64 s[0:1], s62, v194
	v_cndmask_b32_e64 v186, 0, 32, s[8:9]
	v_cndmask_b32_e64 v151, 0, v163, s[8:9]
	v_cmp_gt_f32_e64 s[8:9], s62, v197
	v_cndmask_b32_e64 v189, 0, 32, s[32:33]
	v_cndmask_b32_e64 v152, 0, v163, s[32:33]
	v_cmp_gt_f32_e64 s[32:33], s62, v200
	v_cndmask_b32_e64 v192, 0, 32, s[60:61]
	v_cndmask_b32_e64 v153, 0, v163, s[60:61]
	v_cmp_gt_f32_e64 s[60:61], s62, v147
	v_ldexp_f32 v174, v174, v183
	v_cndmask_b32_e64 v195, 0, 32, s[0:1]
	v_cndmask_b32_e64 v154, 0, v163, s[0:1]
	v_ldexp_f32 v185, v185, v186
	v_cndmask_b32_e64 v198, 0, 32, s[8:9]
	v_cndmask_b32_e64 v155, 0, v163, s[8:9]
	v_ldexp_f32 v188, v188, v189
	v_cndmask_b32_e64 v201, 0, 32, s[32:33]
	v_cndmask_b32_e64 v156, 0, v163, s[32:33]
	v_ldexp_f32 v191, v191, v192
	v_cndmask_b32_e64 v203, 0, 32, s[60:61]
	v_cndmask_b32_e64 v157, 0, v163, s[60:61]
	v_log_f32_e32 v174, v174
	v_ldexp_f32 v194, v194, v195
	v_log_f32_e32 v185, v185
	v_ldexp_f32 v197, v197, v198
	v_log_f32_e32 v188, v188
	v_ldexp_f32 v200, v200, v201
	v_log_f32_e32 v191, v191
	v_ldexp_f32 v147, v147, v203
	v_mul_f32_e32 v184, 0x3f317217, v174
	v_cmp_lt_f32_e64 s[0:1], |v174|, s66
	v_log_f32_e32 v194, v194
	v_mul_f32_e32 v187, 0x3f317217, v185
	v_cmp_lt_f32_e64 s[8:9], |v185|, s66
	v_log_f32_e32 v197, v197
	v_mul_f32_e32 v190, 0x3f317217, v188
	v_cmp_lt_f32_e64 s[32:33], |v188|, s66
	v_log_f32_e32 v200, v200
	v_mul_f32_e32 v193, 0x3f317217, v191
	v_cmp_lt_f32_e64 s[60:61], |v191|, s66
	v_log_f32_e32 v147, v147
	v_fma_f32 v184, v174, s63, -v184
	v_mul_f32_e32 v196, 0x3f317217, v194
	v_fma_f32 v187, v185, s63, -v187
	v_mul_f32_e32 v199, 0x3f317217, v197
	v_fma_f32 v190, v188, s63, -v190
	v_mul_f32_e32 v202, 0x3f317217, v200
	v_fma_f32 v193, v191, s63, -v193
	v_mul_f32_e32 v204, 0x3f317217, v147
	v_fmac_f32_e32 v184, 0x3377d1cf, v174
	v_fma_f32 v196, v194, s63, -v196
	v_fmac_f32_e32 v187, 0x3377d1cf, v185
	v_fma_f32 v199, v197, s63, -v199
	v_fmac_f32_e32 v190, 0x3377d1cf, v188
	v_fma_f32 v202, v200, s63, -v202
	v_fmac_f32_e32 v193, 0x3377d1cf, v191
	v_fma_f32 v204, v147, s63, -v204
	v_fmac_f32_e32 v184, 0x3f317217, v174
	v_fmac_f32_e32 v196, 0x3377d1cf, v194
	v_fmac_f32_e32 v187, 0x3f317217, v185
	v_fmac_f32_e32 v199, 0x3377d1cf, v197
	v_fmac_f32_e32 v190, 0x3f317217, v188
	v_fmac_f32_e32 v202, 0x3377d1cf, v200
	v_fmac_f32_e32 v193, 0x3f317217, v191
	v_fmac_f32_e32 v204, 0x3377d1cf, v147
	v_cndmask_b32_e64 v174, v174, v184, s[0:1]
	v_cmp_lt_f32_e64 s[0:1], |v194|, s66
	v_fmac_f32_e32 v196, 0x3f317217, v194
	v_cndmask_b32_e64 v185, v185, v187, s[8:9]
	v_cmp_lt_f32_e64 s[8:9], |v197|, s66
	v_fmac_f32_e32 v199, 0x3f317217, v197
	v_cndmask_b32_e64 v188, v188, v190, s[32:33]
	v_cmp_lt_f32_e64 s[32:33], |v200|, s66
	v_fmac_f32_e32 v202, 0x3f317217, v200
	v_cndmask_b32_e64 v191, v191, v193, s[60:61]
	v_cmp_lt_f32_e64 s[60:61], |v147|, s66
	v_fmac_f32_e32 v204, 0x3f317217, v147
	v_sub_f32_e32 v150, v174, v150
	v_cndmask_b32_e64 v194, v194, v196, s[0:1]
	v_sub_f32_e32 v151, v185, v151
	v_cndmask_b32_e64 v197, v197, v199, s[8:9]
	v_sub_f32_e32 v152, v188, v152
	v_cndmask_b32_e64 v200, v200, v202, s[32:33]
	v_sub_f32_e32 v153, v191, v153
	v_cndmask_b32_e64 v147, v147, v204, s[60:61]
	v_sub_f32_e32 v154, v194, v154
	v_sub_f32_e32 v155, v197, v155
	v_sub_f32_e32 v156, v200, v156
	v_sub_f32_e32 v157, v147, v157

;     __device__ __forceinline__ void operator()(const f32x4 (&acc)[2][2][4][2], const Unit& u, int wr, int wc, int fr, int fq) const {
;     ...
;                 for (int m = 0; m < 4; ++m) {
;                     const int row = row0 + ai * HALF + m * 16; const float rs = rsc ? rsc[row - rbase] : rstd[row];
;                     float v[8];
; #pragma unroll
;                     for (int i = 0; i < 4; ++i) { v[i] = acc[ai][bj][m][0][i] * rs; v[4 + i] = acc[ai][bj][m][1][i] * rs; }
;                     if (seg == 0) {
; #pragma unroll
;                         for (int i = 0; i < 8; ++i) v[i] = v[i] * __builtin_amdgcn_rcpf(1.0f + __expf(-v[i])) * 0.08838834764831845f;
;                     } else if (seg == 1) {
; #pragma unroll
;                         for (int i = 0; i < 8; ++i) { const float s = __builtin_amdgcn_rcpf(1.0f + __expf(-v[i])); v[i] = __logf(lb[i] + (1.0f - lb[i]) * s); }
.LBB0_137:
	v_mul_f32_e32 v126, 0xbfb8aa3b, v118
	v_sub_f32_e32 v174, 1.0, v173
	v_sub_f32_e32 v175, 1.0, v172
	v_sub_f32_e32 v176, 1.0, v171
	v_sub_f32_e32 v177, 1.0, v170
	v_sub_f32_e32 v178, 1.0, v169
	v_sub_f32_e32 v179, 1.0, v168
	v_sub_f32_e32 v180, 1.0, v167
	v_sub_f32_e32 v181, 1.0, v166
	v_mul_f32_e32 v127, 0xbfb8aa3b, v119
	v_mul_f32_e32 v128, 0xbfb8aa3b, v120
	v_mul_f32_e32 v129, 0xbfb8aa3b, v121
	v_mul_f32_e32 v150, 0xbfb8aa3b, v114
	v_mul_f32_e32 v151, 0xbfb8aa3b, v115
	v_mul_f32_e32 v152, 0xbfb8aa3b, v116
	v_mul_f32_e32 v153, 0xbfb8aa3b, v117
	v_exp_f32_e32 v126, v126
	v_exp_f32_e32 v127, v127
	v_exp_f32_e32 v128, v128
	v_exp_f32_e32 v129, v129
	v_exp_f32_e32 v150, v150
	v_exp_f32_e32 v151, v151
	v_exp_f32_e32 v152, v152
	v_exp_f32_e32 v153, v153
	v_add_f32_e32 v126, 1.0, v126
	v_add_f32_e32 v127, 1.0, v127
	v_add_f32_e32 v128, 1.0, v128
	v_add_f32_e32 v129, 1.0, v129
	v_add_f32_e32 v150, 1.0, v150
	v_add_f32_e32 v151, 1.0, v151
	v_add_f32_e32 v152, 1.0, v152
	v_add_f32_e32 v153, 1.0, v153
	v_rcp_f32_e32 v126, v126
	v_rcp_f32_e32 v127, v127
	v_rcp_f32_e32 v128, v128
	v_rcp_f32_e32 v129, v129
	v_rcp_f32_e32 v150, v150
	v_rcp_f32_e32 v151, v151
	v_rcp_f32_e32 v152, v152
	v_rcp_f32_e32 v153, v153
	v_fma_f32 v126, v174, v126, v173
	v_fma_f32 v127, v175, v127, v172
	v_fma_f32 v128, v176, v128, v171
	v_fma_f32 v129, v177, v129, v170
	v_fma_f32 v150, v178, v150, v169
	v_fma_f32 v151, v179, v151, v168
	v_fma_f32 v152, v180, v152, v167
	v_fma_f32 v153, v181, v153, v166
	v_cmp_gt_f32_e64 s[0:1], s62, v126
	v_cmp_gt_f32_e64 s[32:33], s62, v127
	v_cmp_gt_f32_e64 s[60:61], s62, v128
	v_cndmask_b32_e64 v182, 0, 32, s[0:1]
	v_cndmask_b32_e64 v184, 0, v163, s[0:1]
	v_cmp_gt_f32_e64 s[0:1], s62, v129
	v_cndmask_b32_e64 v185, 0, 32, s[32:33]
	v_cndmask_b32_e64 v187, 0, v163, s[32:33]
	v_cmp_gt_f32_e64 s[32:33], s62, v150
	v_cndmask_b32_e64 v188, 0, 32, s[60:61]
	v_cndmask_b32_e64 v190, 0, v163, s[60:61]
	v_cmp_gt_f32_e64 s[60:61], s62, v151
	v_ldexp_f32 v126, v126, v182
	v_cndmask_b32_e64 v191, 0, 32, s[0:1]
	v_cndmask_b32_e64 v193, 0, v163, s[0:1]
	v_cmp_gt_f32_e64 s[0:1], s62, v152
	v_ldexp_f32 v127, v127, v185
	v_cndmask_b32_e64 v194, 0, 32, s[32:33]
	v_cndmask_b32_e64 v196, 0, v163, s[32:33]
	v_cmp_gt_f32_e64 s[32:33], s62, v153
	v_ldexp_f32 v128, v128, v188
	v_cndmask_b32_e64 v197, 0, 32, s[60:61]
	v_cndmask_b32_e64 v199, 0, v163, s[60:61]
	v_log_f32_e32 v126, v126
	v_ldexp_f32 v129, v129, v191
	v_cndmask_b32_e64 v200, 0, 32, s[0:1]
	v_cndmask_b32_e64 v202, 0, v163, s[0:1]
	v_log_f32_e32 v127, v127
	v_ldexp_f32 v150, v150, v194
	v_cndmask_b32_e64 v203, 0, 32, s[32:33]
	v_cndmask_b32_e64 v154, 0, v163, s[32:33]
	v_log_f32_e32 v128, v128
	v_ldexp_f32 v151, v151, v197
	v_mul_f32_e32 v183, 0x3f317217, v126
	v_cmp_lt_f32_e64 s[60:61], |v126|, s66
	v_log_f32_e32 v129, v129
	v_ldexp_f32 v152, v152, v200
	v_mul_f32_e32 v186, 0x3f317217, v127
	v_cmp_lt_f32_e64 s[0:1], |v127|, s66
	v_log_f32_e32 v150, v150
	v_ldexp_f32 v153, v153, v203
	v_mul_f32_e32 v189, 0x3f317217, v128
	v_cmp_lt_f32_e64 s[32:33], |v128|, s66
	v_log_f32_e32 v151, v151
	v_fma_f32 v183, v126, s63, -v183
	v_mul_f32_e32 v192, 0x3f317217, v129
	v_log_f32_e32 v152, v152
	v_fma_f32 v186, v127, s63, -v186
	v_mul_f32_e32 v195, 0x3f317217, v150
	v_log_f32_e32 v153, v153
	v_fma_f32 v189, v128, s63, -v189
	v_mul_f32_e32 v198, 0x3f317217, v151
	v_fmac_f32_e32 v183, 0x3377d1cf, v126
	v_fma_f32 v192, v129, s63, -v192
	v_mul_f32_e32 v201, 0x3f317217, v152
	v_fmac_f32_e32 v186, 0x3377d1cf, v127
	v_fma_f32 v195, v150, s63, -v195
	v_mul_f32_e32 v204, 0x3f317217, v153
	v_fmac_f32_e32 v189, 0x3377d1cf, v128
	v_fma_f32 v198, v151, s63, -v198
	v_fmac_f32_e32 v183, 0x3f317217, v126
	v_fmac_f32_e32 v192, 0x3377d1cf, v129
	v_fma_f32 v201, v152, s63, -v201
	v_fmac_f32_e32 v186, 0x3f317217, v127
	v_fmac_f32_e32 v195, 0x3377d1cf, v150
	v_fma_f32 v204, v153, s63, -v204
	v_fmac_f32_e32 v189, 0x3f317217, v128
	v_fmac_f32_e32 v198, 0x3377d1cf, v151
	v_cndmask_b32_e64 v126, v126, v183, s[60:61]
	v_cmp_lt_f32_e64 s[60:61], |v129|, s66
	v_fmac_f32_e32 v192, 0x3f317217, v129
	v_fmac_f32_e32 v201, 0x3377d1cf, v152
	v_cndmask_b32_e64 v127, v127, v186, s[0:1]
	v_cmp_lt_f32_e64 s[0:1], |v150|, s66
	v_fmac_f32_e32 v195, 0x3f317217, v150
	v_fmac_f32_e32 v204, 0x3377d1cf, v153
	v_cndmask_b32_e64 v128, v128, v189, s[32:33]
	v_cmp_lt_f32_e64 s[32:33], |v151|, s66
	v_fmac_f32_e32 v198, 0x3f317217, v151
	v_sub_f32_e32 v126, v126, v184
	v_cndmask_b32_e64 v129, v129, v192, s[60:61]
	v_cmp_lt_f32_e64 s[60:61], |v152|, s66
	v_fmac_f32_e32 v201, 0x3f317217, v152
	v_sub_f32_e32 v127, v127, v187
	v_cndmask_b32_e64 v150, v150, v195, s[0:1]
	v_cmp_lt_f32_e64 s[0:1], |v153|, s66
	v_fmac_f32_e32 v204, 0x3f317217, v153
	v_sub_f32_e32 v128, v128, v190
	v_cndmask_b32_e64 v151, v151, v198, s[32:33]
	v_sub_f32_e32 v129, v129, v193
	v_cndmask_b32_e64 v152, v152, v201, s[60:61]
	v_sub_f32_e32 v150, v150, v196
	v_cndmask_b32_e64 v153, v153, v204, s[0:1]
	v_sub_f32_e32 v151, v151, v199
	v_sub_f32_e32 v152, v152, v202
	v_sub_f32_e32 v153, v153, v154

;     __device__ __forceinline__ void operator()(const f32x4 (&acc)[2][2][4][2], const Unit& u, int wr, int wc, int fr, int fq) const {
;     ...
;                 for (int m = 0; m < 4; ++m) {
;                     const int row = row0 + ai * HALF + m * 16; const float rs = rsc ? rsc[row - rbase] : rstd[row];
;                     float v[8];
; #pragma unroll
;                     for (int i = 0; i < 4; ++i) { v[i] = acc[ai][bj][m][0][i] * rs; v[4 + i] = acc[ai][bj][m][1][i] * rs; }
;                     if (seg == 0) {
; #pragma unroll
;                         for (int i = 0; i < 8; ++i) v[i] = v[i] * __builtin_amdgcn_rcpf(1.0f + __expf(-v[i])) * 0.08838834764831845f;
;                     } else if (seg == 1) {
; #pragma unroll
;                         for (int i = 0; i < 8; ++i) { const float s = __builtin_amdgcn_rcpf(1.0f + __expf(-v[i])); v[i] = __logf(lb[i] + (1.0f - lb[i]) * s); }
.LBB0_150:
	v_mul_f32_e32 v118, 0xbfb8aa3b, v110
	v_sub_f32_e32 v174, 1.0, v173
	v_sub_f32_e32 v175, 1.0, v172
	v_sub_f32_e32 v176, 1.0, v171
	v_sub_f32_e32 v177, 1.0, v170
	v_sub_f32_e32 v178, 1.0, v169
	v_sub_f32_e32 v179, 1.0, v168
	v_sub_f32_e32 v180, 1.0, v167
	v_sub_f32_e32 v181, 1.0, v166
	v_mul_f32_e32 v119, 0xbfb8aa3b, v111
	v_mul_f32_e32 v120, 0xbfb8aa3b, v112
	v_mul_f32_e32 v121, 0xbfb8aa3b, v113
	v_mul_f32_e32 v126, 0xbfb8aa3b, v106
	v_mul_f32_e32 v127, 0xbfb8aa3b, v107
	v_mul_f32_e32 v128, 0xbfb8aa3b, v108
	v_mul_f32_e32 v129, 0xbfb8aa3b, v109
	v_exp_f32_e32 v118, v118
	v_exp_f32_e32 v119, v119
	v_exp_f32_e32 v120, v120
	v_exp_f32_e32 v121, v121
	v_exp_f32_e32 v126, v126
	v_exp_f32_e32 v127, v127
	v_exp_f32_e32 v128, v128
	v_exp_f32_e32 v129, v129
	v_add_f32_e32 v118, 1.0, v118
	v_add_f32_e32 v119, 1.0, v119
	v_add_f32_e32 v120, 1.0, v120
	v_add_f32_e32 v121, 1.0, v121
	v_add_f32_e32 v126, 1.0, v126
	v_add_f32_e32 v127, 1.0, v127
	v_add_f32_e32 v128, 1.0, v128
	v_add_f32_e32 v129, 1.0, v129
	v_rcp_f32_e32 v118, v118
	v_rcp_f32_e32 v119, v119
	v_rcp_f32_e32 v120, v120
	v_rcp_f32_e32 v121, v121
	v_rcp_f32_e32 v126, v126
	v_rcp_f32_e32 v127, v127
	v_rcp_f32_e32 v128, v128
	v_rcp_f32_e32 v129, v129
	v_fma_f32 v118, v174, v118, v173
	v_fma_f32 v119, v175, v119, v172
	v_fma_f32 v120, v176, v120, v171
	v_fma_f32 v121, v177, v121, v170
	v_fma_f32 v126, v178, v126, v169
	v_fma_f32 v127, v179, v127, v168
	v_fma_f32 v128, v180, v128, v167
	v_fma_f32 v129, v181, v129, v166
	v_cmp_gt_f32_e64 s[0:1], s62, v118
	v_cmp_gt_f32_e64 s[32:33], s62, v119
	v_cmp_gt_f32_e64 s[60:61], s62, v120
	v_cndmask_b32_e64 v182, 0, 32, s[0:1]
	v_cndmask_b32_e64 v184, 0, v163, s[0:1]
	v_cmp_gt_f32_e64 s[0:1], s62, v121
	v_cndmask_b32_e64 v185, 0, 32, s[32:33]
	v_cndmask_b32_e64 v187, 0, v163, s[32:33]
	v_cmp_gt_f32_e64 s[32:33], s62, v126
	v_cndmask_b32_e64 v188, 0, 32, s[60:61]
	v_cndmask_b32_e64 v190, 0, v163, s[60:61]
	v_cmp_gt_f32_e64 s[60:61], s62, v127
	v_ldexp_f32 v118, v118, v182
	v_cndmask_b32_e64 v191, 0, 32, s[0:1]
	v_cndmask_b32_e64 v193, 0, v163, s[0:1]
	v_cmp_gt_f32_e64 s[0:1], s62, v128
	v_ldexp_f32 v119, v119, v185
	v_cndmask_b32_e64 v194, 0, 32, s[32:33]
	v_cndmask_b32_e64 v196, 0, v163, s[32:33]
	v_cmp_gt_f32_e64 s[32:33], s62, v129
	v_ldexp_f32 v120, v120, v188
	v_cndmask_b32_e64 v197, 0, 32, s[60:61]
	v_cndmask_b32_e64 v199, 0, v163, s[60:61]
	v_log_f32_e32 v118, v118
	v_ldexp_f32 v121, v121, v191
	v_cndmask_b32_e64 v200, 0, 32, s[0:1]
	v_cndmask_b32_e64 v202, 0, v163, s[0:1]
	v_log_f32_e32 v119, v119
	v_ldexp_f32 v126, v126, v194
	v_cndmask_b32_e64 v203, 0, 32, s[32:33]
	v_cndmask_b32_e64 v150, 0, v163, s[32:33]
	v_log_f32_e32 v120, v120
	v_ldexp_f32 v127, v127, v197
	v_mul_f32_e32 v183, 0x3f317217, v118
	v_cmp_lt_f32_e64 s[60:61], |v118|, s66
	v_log_f32_e32 v121, v121
	v_ldexp_f32 v128, v128, v200
	v_mul_f32_e32 v186, 0x3f317217, v119
	v_cmp_lt_f32_e64 s[0:1], |v119|, s66
	v_log_f32_e32 v126, v126
	v_ldexp_f32 v129, v129, v203
	v_mul_f32_e32 v189, 0x3f317217, v120
	v_cmp_lt_f32_e64 s[32:33], |v120|, s66
	v_log_f32_e32 v127, v127
	v_fma_f32 v183, v118, s63, -v183
	v_mul_f32_e32 v192, 0x3f317217, v121
	v_log_f32_e32 v128, v128
	v_fma_f32 v186, v119, s63, -v186
	v_mul_f32_e32 v195, 0x3f317217, v126
	v_log_f32_e32 v129, v129
	v_fma_f32 v189, v120, s63, -v189
	v_mul_f32_e32 v198, 0x3f317217, v127
	v_fmac_f32_e32 v183, 0x3377d1cf, v118
	v_fma_f32 v192, v121, s63, -v192
	v_mul_f32_e32 v201, 0x3f317217, v128
	v_fmac_f32_e32 v186, 0x3377d1cf, v119
	v_fma_f32 v195, v126, s63, -v195
	v_mul_f32_e32 v204, 0x3f317217, v129
	v_fmac_f32_e32 v189, 0x3377d1cf, v120
	v_fma_f32 v198, v127, s63, -v198
	v_fmac_f32_e32 v183, 0x3f317217, v118
	v_fmac_f32_e32 v192, 0x3377d1cf, v121
	v_fma_f32 v201, v128, s63, -v201
	v_fmac_f32_e32 v186, 0x3f317217, v119
	v_fmac_f32_e32 v195, 0x3377d1cf, v126
	v_fma_f32 v204, v129, s63, -v204
	v_fmac_f32_e32 v189, 0x3f317217, v120
	v_fmac_f32_e32 v198, 0x3377d1cf, v127
	v_cndmask_b32_e64 v118, v118, v183, s[60:61]
	v_cmp_lt_f32_e64 s[60:61], |v121|, s66
	v_fmac_f32_e32 v192, 0x3f317217, v121
	v_fmac_f32_e32 v201, 0x3377d1cf, v128
	v_cndmask_b32_e64 v119, v119, v186, s[0:1]
	v_cmp_lt_f32_e64 s[0:1], |v126|, s66
	v_fmac_f32_e32 v195, 0x3f317217, v126
	v_fmac_f32_e32 v204, 0x3377d1cf, v129
	v_cndmask_b32_e64 v120, v120, v189, s[32:33]
	v_cmp_lt_f32_e64 s[32:33], |v127|, s66
	v_fmac_f32_e32 v198, 0x3f317217, v127
	v_sub_f32_e32 v118, v118, v184
	v_cndmask_b32_e64 v121, v121, v192, s[60:61]
	v_cmp_lt_f32_e64 s[60:61], |v128|, s66
	v_fmac_f32_e32 v201, 0x3f317217, v128
	v_sub_f32_e32 v119, v119, v187
	v_cndmask_b32_e64 v126, v126, v195, s[0:1]
	v_cmp_lt_f32_e64 s[0:1], |v129|, s66
	v_fmac_f32_e32 v204, 0x3f317217, v129
	v_sub_f32_e32 v120, v120, v190
	v_cndmask_b32_e64 v127, v127, v198, s[32:33]
	v_sub_f32_e32 v121, v121, v193
	v_cndmask_b32_e64 v128, v128, v201, s[60:61]
	v_sub_f32_e32 v126, v126, v196
	v_cndmask_b32_e64 v129, v129, v204, s[0:1]
	v_sub_f32_e32 v127, v127, v199
	v_sub_f32_e32 v128, v128, v202
	v_sub_f32_e32 v129, v129, v150

;     __device__ __forceinline__ void operator()(const f32x4 (&acc)[2][2][4][2], const Unit& u, int wr, int wc, int fr, int fq) const {
;     ...
;                 for (int m = 0; m < 4; ++m) {
;                     const int row = row0 + ai * HALF + m * 16; const float rs = rsc ? rsc[row - rbase] : rstd[row];
;                     float v[8];
; #pragma unroll
;                     for (int i = 0; i < 4; ++i) { v[i] = acc[ai][bj][m][0][i] * rs; v[4 + i] = acc[ai][bj][m][1][i] * rs; }
;                     if (seg == 0) {
; #pragma unroll
;                         for (int i = 0; i < 8; ++i) v[i] = v[i] * __builtin_amdgcn_rcpf(1.0f + __expf(-v[i])) * 0.08838834764831845f;
;                     } else if (seg == 1) {
; #pragma unroll
;                         for (int i = 0; i < 8; ++i) { const float s = __builtin_amdgcn_rcpf(1.0f + __expf(-v[i])); v[i] = __logf(lb[i] + (1.0f - lb[i]) * s); }
.LBB0_163:
	v_mul_f32_e32 v110, 0xbfb8aa3b, v102
	v_sub_f32_e32 v174, 1.0, v173
	v_sub_f32_e32 v175, 1.0, v172
	v_sub_f32_e32 v176, 1.0, v171
	v_sub_f32_e32 v177, 1.0, v170
	v_sub_f32_e32 v178, 1.0, v169
	v_sub_f32_e32 v179, 1.0, v168
	v_sub_f32_e32 v180, 1.0, v167
	v_sub_f32_e32 v181, 1.0, v166
	v_mul_f32_e32 v111, 0xbfb8aa3b, v103
	v_mul_f32_e32 v112, 0xbfb8aa3b, v104
	v_mul_f32_e32 v113, 0xbfb8aa3b, v105
	v_mul_f32_e32 v118, 0xbfb8aa3b, v98
	v_mul_f32_e32 v119, 0xbfb8aa3b, v99
	v_mul_f32_e32 v120, 0xbfb8aa3b, v100
	v_mul_f32_e32 v121, 0xbfb8aa3b, v101
	v_exp_f32_e32 v110, v110
	v_exp_f32_e32 v111, v111
	v_exp_f32_e32 v112, v112
	v_exp_f32_e32 v113, v113
	v_exp_f32_e32 v118, v118
	v_exp_f32_e32 v119, v119
	v_exp_f32_e32 v120, v120
	v_exp_f32_e32 v121, v121
	v_add_f32_e32 v110, 1.0, v110
	v_add_f32_e32 v111, 1.0, v111
	v_add_f32_e32 v112, 1.0, v112
	v_add_f32_e32 v113, 1.0, v113
	v_add_f32_e32 v118, 1.0, v118
	v_add_f32_e32 v119, 1.0, v119
	v_add_f32_e32 v120, 1.0, v120
	v_add_f32_e32 v121, 1.0, v121
	v_rcp_f32_e32 v110, v110
	v_rcp_f32_e32 v111, v111
	v_rcp_f32_e32 v112, v112
	v_rcp_f32_e32 v113, v113
	v_rcp_f32_e32 v118, v118
	v_rcp_f32_e32 v119, v119
	v_rcp_f32_e32 v120, v120
	v_rcp_f32_e32 v121, v121
	v_fma_f32 v110, v174, v110, v173
	v_fma_f32 v111, v175, v111, v172
	v_fma_f32 v112, v176, v112, v171
	v_fma_f32 v113, v177, v113, v170
	v_fma_f32 v118, v178, v118, v169
	v_fma_f32 v119, v179, v119, v168
	v_fma_f32 v120, v180, v120, v167
	v_fma_f32 v121, v181, v121, v166
	v_cmp_gt_f32_e64 s[0:1], s62, v110
	v_cmp_gt_f32_e64 s[32:33], s62, v111
	v_cmp_gt_f32_e64 s[60:61], s62, v112
	v_cndmask_b32_e64 v182, 0, 32, s[0:1]
	v_cndmask_b32_e64 v184, 0, v163, s[0:1]
	v_cmp_gt_f32_e64 s[0:1], s62, v113
	v_cndmask_b32_e64 v185, 0, 32, s[32:33]
	v_cndmask_b32_e64 v187, 0, v163, s[32:33]
	v_cmp_gt_f32_e64 s[32:33], s62, v118
	v_cndmask_b32_e64 v188, 0, 32, s[60:61]
	v_cndmask_b32_e64 v190, 0, v163, s[60:61]
	v_cmp_gt_f32_e64 s[60:61], s62, v119
	v_ldexp_f32 v110, v110, v182
	v_cndmask_b32_e64 v191, 0, 32, s[0:1]
	v_cndmask_b32_e64 v193, 0, v163, s[0:1]
	v_cmp_gt_f32_e64 s[0:1], s62, v120
	v_ldexp_f32 v111, v111, v185
	v_cndmask_b32_e64 v194, 0, 32, s[32:33]
	v_cndmask_b32_e64 v196, 0, v163, s[32:33]
	v_cmp_gt_f32_e64 s[32:33], s62, v121
	v_ldexp_f32 v112, v112, v188
	v_cndmask_b32_e64 v197, 0, 32, s[60:61]
	v_cndmask_b32_e64 v199, 0, v163, s[60:61]
	v_log_f32_e32 v110, v110
	v_ldexp_f32 v113, v113, v191
	v_cndmask_b32_e64 v200, 0, 32, s[0:1]
	v_cndmask_b32_e64 v202, 0, v163, s[0:1]
	v_log_f32_e32 v111, v111
	v_ldexp_f32 v118, v118, v194
	v_cndmask_b32_e64 v203, 0, 32, s[32:33]
	v_cndmask_b32_e64 v126, 0, v163, s[32:33]
	v_log_f32_e32 v112, v112
	v_ldexp_f32 v119, v119, v197
	v_mul_f32_e32 v183, 0x3f317217, v110
	v_cmp_lt_f32_e64 s[60:61], |v110|, s66
	v_log_f32_e32 v113, v113
	v_ldexp_f32 v120, v120, v200
	v_mul_f32_e32 v186, 0x3f317217, v111
	v_cmp_lt_f32_e64 s[0:1], |v111|, s66
	v_log_f32_e32 v118, v118
	v_ldexp_f32 v121, v121, v203
	v_mul_f32_e32 v189, 0x3f317217, v112
	v_cmp_lt_f32_e64 s[32:33], |v112|, s66
	v_log_f32_e32 v119, v119
	v_fma_f32 v183, v110, s63, -v183
	v_mul_f32_e32 v192, 0x3f317217, v113
	v_log_f32_e32 v120, v120
	v_fma_f32 v186, v111, s63, -v186
	v_mul_f32_e32 v195, 0x3f317217, v118
	v_log_f32_e32 v121, v121
	v_fma_f32 v189, v112, s63, -v189
	v_mul_f32_e32 v198, 0x3f317217, v119
	v_fmac_f32_e32 v183, 0x3377d1cf, v110
	v_fma_f32 v192, v113, s63, -v192
	v_mul_f32_e32 v201, 0x3f317217, v120
	v_fmac_f32_e32 v186, 0x3377d1cf, v111
	v_fma_f32 v195, v118, s63, -v195
	v_mul_f32_e32 v204, 0x3f317217, v121
	v_fmac_f32_e32 v189, 0x3377d1cf, v112
	v_fma_f32 v198, v119, s63, -v198
	v_fmac_f32_e32 v183, 0x3f317217, v110
	v_fmac_f32_e32 v192, 0x3377d1cf, v113
	v_fma_f32 v201, v120, s63, -v201
	v_fmac_f32_e32 v186, 0x3f317217, v111
	v_fmac_f32_e32 v195, 0x3377d1cf, v118
	v_fma_f32 v204, v121, s63, -v204
	v_fmac_f32_e32 v189, 0x3f317217, v112
	v_fmac_f32_e32 v198, 0x3377d1cf, v119
	v_cndmask_b32_e64 v110, v110, v183, s[60:61]
	v_cmp_lt_f32_e64 s[60:61], |v113|, s66
	v_fmac_f32_e32 v192, 0x3f317217, v113
	v_fmac_f32_e32 v201, 0x3377d1cf, v120
	v_cndmask_b32_e64 v111, v111, v186, s[0:1]
	v_cmp_lt_f32_e64 s[0:1], |v118|, s66
	v_fmac_f32_e32 v195, 0x3f317217, v118
	v_fmac_f32_e32 v204, 0x3377d1cf, v121
	v_cndmask_b32_e64 v112, v112, v189, s[32:33]
	v_cmp_lt_f32_e64 s[32:33], |v119|, s66
	v_fmac_f32_e32 v198, 0x3f317217, v119
	v_sub_f32_e32 v110, v110, v184
	v_cndmask_b32_e64 v113, v113, v192, s[60:61]
	v_cmp_lt_f32_e64 s[60:61], |v120|, s66
	v_fmac_f32_e32 v201, 0x3f317217, v120
	v_sub_f32_e32 v111, v111, v187
	v_cndmask_b32_e64 v118, v118, v195, s[0:1]
	v_cmp_lt_f32_e64 s[0:1], |v121|, s66
	v_fmac_f32_e32 v204, 0x3f317217, v121
	v_sub_f32_e32 v112, v112, v190
	v_cndmask_b32_e64 v119, v119, v198, s[32:33]
	v_sub_f32_e32 v113, v113, v193
	v_cndmask_b32_e64 v120, v120, v201, s[60:61]
	v_sub_f32_e32 v118, v118, v196
	v_cndmask_b32_e64 v121, v121, v204, s[0:1]
	v_sub_f32_e32 v119, v119, v199
	v_sub_f32_e32 v120, v120, v202
	v_sub_f32_e32 v121, v121, v126

;     __device__ __forceinline__ void operator()(const f32x4 (&acc)[2][2][4][2], const Unit& u, int wr, int wc, int fr, int fq) const {
;     ...
;                 for (int m = 0; m < 4; ++m) {
;                     const int row = row0 + ai * HALF + m * 16; const float rs = rsc ? rsc[row - rbase] : rstd[row];
;                     float v[8];
; #pragma unroll
;                     for (int i = 0; i < 4; ++i) { v[i] = acc[ai][bj][m][0][i] * rs; v[4 + i] = acc[ai][bj][m][1][i] * rs; }
;                     if (seg == 0) {
; #pragma unroll
;                         for (int i = 0; i < 8; ++i) v[i] = v[i] * __builtin_amdgcn_rcpf(1.0f + __expf(-v[i])) * 0.08838834764831845f;
;                     } else if (seg == 1) {
; #pragma unroll
;                         for (int i = 0; i < 8; ++i) { const float s = __builtin_amdgcn_rcpf(1.0f + __expf(-v[i])); v[i] = __logf(lb[i] + (1.0f - lb[i]) * s); }
.LBB0_176:
	v_mul_f32_e32 v102, 0xbfb8aa3b, v94
	v_sub_f32_e32 v174, 1.0, v173
	v_sub_f32_e32 v175, 1.0, v172
	v_sub_f32_e32 v176, 1.0, v171
	v_sub_f32_e32 v177, 1.0, v170
	v_sub_f32_e32 v178, 1.0, v169
	v_sub_f32_e32 v179, 1.0, v168
	v_sub_f32_e32 v180, 1.0, v167
	v_sub_f32_e32 v181, 1.0, v166
	v_mul_f32_e32 v103, 0xbfb8aa3b, v95
	v_mul_f32_e32 v104, 0xbfb8aa3b, v96
	v_mul_f32_e32 v105, 0xbfb8aa3b, v97
	v_mul_f32_e32 v110, 0xbfb8aa3b, v90
	v_mul_f32_e32 v111, 0xbfb8aa3b, v91
	v_mul_f32_e32 v112, 0xbfb8aa3b, v92
	v_mul_f32_e32 v113, 0xbfb8aa3b, v93
	v_exp_f32_e32 v102, v102
	v_exp_f32_e32 v103, v103
	v_exp_f32_e32 v104, v104
	v_exp_f32_e32 v105, v105
	v_exp_f32_e32 v110, v110
	v_exp_f32_e32 v111, v111
	v_exp_f32_e32 v112, v112
	v_exp_f32_e32 v113, v113
	v_add_f32_e32 v102, 1.0, v102
	v_add_f32_e32 v103, 1.0, v103
	v_add_f32_e32 v104, 1.0, v104
	v_add_f32_e32 v105, 1.0, v105
	v_add_f32_e32 v110, 1.0, v110
	v_add_f32_e32 v111, 1.0, v111
	v_add_f32_e32 v112, 1.0, v112
	v_add_f32_e32 v113, 1.0, v113
	v_rcp_f32_e32 v102, v102
	v_rcp_f32_e32 v103, v103
	v_rcp_f32_e32 v104, v104
	v_rcp_f32_e32 v105, v105
	v_rcp_f32_e32 v110, v110
	v_rcp_f32_e32 v111, v111
	v_rcp_f32_e32 v112, v112
	v_rcp_f32_e32 v113, v113
	v_fma_f32 v102, v174, v102, v173
	v_fma_f32 v103, v175, v103, v172
	v_fma_f32 v104, v176, v104, v171
	v_fma_f32 v105, v177, v105, v170
	v_fma_f32 v110, v178, v110, v169
	v_fma_f32 v111, v179, v111, v168
	v_fma_f32 v112, v180, v112, v167
	v_fma_f32 v113, v181, v113, v166
	v_cmp_gt_f32_e64 s[0:1], s62, v102
	v_cmp_gt_f32_e64 s[32:33], s62, v103
	v_cmp_gt_f32_e64 s[60:61], s62, v104
	v_cndmask_b32_e64 v182, 0, 32, s[0:1]
	v_cndmask_b32_e64 v184, 0, v163, s[0:1]
	v_cmp_gt_f32_e64 s[0:1], s62, v105
	v_cndmask_b32_e64 v185, 0, 32, s[32:33]
	v_cndmask_b32_e64 v187, 0, v163, s[32:33]
	v_cmp_gt_f32_e64 s[32:33], s62, v110
	v_cndmask_b32_e64 v188, 0, 32, s[60:61]
	v_cndmask_b32_e64 v190, 0, v163, s[60:61]
	v_cmp_gt_f32_e64 s[60:61], s62, v111
	v_ldexp_f32 v102, v102, v182
	v_cndmask_b32_e64 v191, 0, 32, s[0:1]
	v_cndmask_b32_e64 v193, 0, v163, s[0:1]
	v_cmp_gt_f32_e64 s[0:1], s62, v112
	v_ldexp_f32 v103, v103, v185
	v_cndmask_b32_e64 v194, 0, 32, s[32:33]
	v_cndmask_b32_e64 v196, 0, v163, s[32:33]
	v_cmp_gt_f32_e64 s[32:33], s62, v113
	v_ldexp_f32 v104, v104, v188
	v_cndmask_b32_e64 v197, 0, 32, s[60:61]
	v_cndmask_b32_e64 v199, 0, v163, s[60:61]
	v_log_f32_e32 v102, v102
	v_ldexp_f32 v105, v105, v191
	v_cndmask_b32_e64 v200, 0, 32, s[0:1]
	v_cndmask_b32_e64 v202, 0, v163, s[0:1]
	v_log_f32_e32 v103, v103
	v_ldexp_f32 v110, v110, v194
	v_cndmask_b32_e64 v203, 0, 32, s[32:33]
	v_cndmask_b32_e64 v118, 0, v163, s[32:33]
	v_log_f32_e32 v104, v104
	v_ldexp_f32 v111, v111, v197
	v_mul_f32_e32 v183, 0x3f317217, v102
	v_cmp_lt_f32_e64 s[60:61], |v102|, s66
	v_log_f32_e32 v105, v105
	v_ldexp_f32 v112, v112, v200
	v_mul_f32_e32 v186, 0x3f317217, v103
	v_cmp_lt_f32_e64 s[0:1], |v103|, s66
	v_log_f32_e32 v110, v110
	v_ldexp_f32 v113, v113, v203
	v_mul_f32_e32 v189, 0x3f317217, v104
	v_cmp_lt_f32_e64 s[32:33], |v104|, s66
	v_log_f32_e32 v111, v111
	v_fma_f32 v183, v102, s63, -v183
	v_mul_f32_e32 v192, 0x3f317217, v105
	v_log_f32_e32 v112, v112
	v_fma_f32 v186, v103, s63, -v186
	v_mul_f32_e32 v195, 0x3f317217, v110
	v_log_f32_e32 v113, v113
	v_fma_f32 v189, v104, s63, -v189
	v_mul_f32_e32 v198, 0x3f317217, v111
	v_fmac_f32_e32 v183, 0x3377d1cf, v102
	v_fma_f32 v192, v105, s63, -v192
	v_mul_f32_e32 v201, 0x3f317217, v112
	v_fmac_f32_e32 v186, 0x3377d1cf, v103
	v_fma_f32 v195, v110, s63, -v195
	v_mul_f32_e32 v204, 0x3f317217, v113
	v_fmac_f32_e32 v189, 0x3377d1cf, v104
	v_fma_f32 v198, v111, s63, -v198
	v_fmac_f32_e32 v183, 0x3f317217, v102
	v_fmac_f32_e32 v192, 0x3377d1cf, v105
	v_fma_f32 v201, v112, s63, -v201
	v_fmac_f32_e32 v186, 0x3f317217, v103
	v_fmac_f32_e32 v195, 0x3377d1cf, v110
	v_fma_f32 v204, v113, s63, -v204
	v_fmac_f32_e32 v189, 0x3f317217, v104
	v_fmac_f32_e32 v198, 0x3377d1cf, v111
	v_cndmask_b32_e64 v102, v102, v183, s[60:61]
	v_cmp_lt_f32_e64 s[60:61], |v105|, s66
	v_fmac_f32_e32 v192, 0x3f317217, v105
	v_fmac_f32_e32 v201, 0x3377d1cf, v112
	v_cndmask_b32_e64 v103, v103, v186, s[0:1]
	v_cmp_lt_f32_e64 s[0:1], |v110|, s66
	v_fmac_f32_e32 v195, 0x3f317217, v110
	v_fmac_f32_e32 v204, 0x3377d1cf, v113
	v_cndmask_b32_e64 v104, v104, v189, s[32:33]
	v_cmp_lt_f32_e64 s[32:33], |v111|, s66
	v_fmac_f32_e32 v198, 0x3f317217, v111
	v_sub_f32_e32 v102, v102, v184
	v_cndmask_b32_e64 v105, v105, v192, s[60:61]
	v_cmp_lt_f32_e64 s[60:61], |v112|, s66
	v_fmac_f32_e32 v201, 0x3f317217, v112
	v_sub_f32_e32 v103, v103, v187
	v_cndmask_b32_e64 v110, v110, v195, s[0:1]
	v_cmp_lt_f32_e64 s[0:1], |v113|, s66
	v_fmac_f32_e32 v204, 0x3f317217, v113
	v_sub_f32_e32 v104, v104, v190
	v_cndmask_b32_e64 v111, v111, v198, s[32:33]
	v_sub_f32_e32 v105, v105, v193
	v_cndmask_b32_e64 v112, v112, v201, s[60:61]
	v_sub_f32_e32 v110, v110, v196
	v_cndmask_b32_e64 v113, v113, v204, s[0:1]
	v_sub_f32_e32 v111, v111, v199
	v_sub_f32_e32 v112, v112, v202
	v_sub_f32_e32 v113, v113, v118

;     __device__ __forceinline__ void operator()(const f32x4 (&acc)[2][2][4][2], const Unit& u, int wr, int wc, int fr, int fq) const {
;     ...
;                 for (int m = 0; m < 4; ++m) {
;                     const int row = row0 + ai * HALF + m * 16; const float rs = rsc ? rsc[row - rbase] : rstd[row];
;                     float v[8];
; #pragma unroll
;                     for (int i = 0; i < 4; ++i) { v[i] = acc[ai][bj][m][0][i] * rs; v[4 + i] = acc[ai][bj][m][1][i] * rs; }
;                     if (seg == 0) {
; #pragma unroll
;                         for (int i = 0; i < 8; ++i) v[i] = v[i] * __builtin_amdgcn_rcpf(1.0f + __expf(-v[i])) * 0.08838834764831845f;
;                     } else if (seg == 1) {
; #pragma unroll
;                         for (int i = 0; i < 8; ++i) { const float s = __builtin_amdgcn_rcpf(1.0f + __expf(-v[i])); v[i] = __logf(lb[i] + (1.0f - lb[i]) * s); }
.LBB0_189:
	v_mul_f32_e32 v94, 0xbfb8aa3b, v86
	v_sub_f32_e32 v174, 1.0, v173
	v_sub_f32_e32 v175, 1.0, v172
	v_sub_f32_e32 v176, 1.0, v171
	v_sub_f32_e32 v177, 1.0, v170
	v_sub_f32_e32 v178, 1.0, v169
	v_sub_f32_e32 v179, 1.0, v168
	v_sub_f32_e32 v180, 1.0, v167
	v_sub_f32_e32 v181, 1.0, v166
	v_mul_f32_e32 v95, 0xbfb8aa3b, v87
	v_mul_f32_e32 v96, 0xbfb8aa3b, v88
	v_mul_f32_e32 v97, 0xbfb8aa3b, v89
	v_mul_f32_e32 v102, 0xbfb8aa3b, v82
	v_mul_f32_e32 v103, 0xbfb8aa3b, v83
	v_mul_f32_e32 v104, 0xbfb8aa3b, v84
	v_mul_f32_e32 v105, 0xbfb8aa3b, v85
	v_exp_f32_e32 v94, v94
	v_exp_f32_e32 v95, v95
	v_exp_f32_e32 v96, v96
	v_exp_f32_e32 v97, v97
	v_exp_f32_e32 v102, v102
	v_exp_f32_e32 v103, v103
	v_exp_f32_e32 v104, v104
	v_exp_f32_e32 v105, v105
	v_add_f32_e32 v94, 1.0, v94
	v_add_f32_e32 v95, 1.0, v95
	v_add_f32_e32 v96, 1.0, v96
	v_add_f32_e32 v97, 1.0, v97
	v_add_f32_e32 v102, 1.0, v102
	v_add_f32_e32 v103, 1.0, v103
	v_add_f32_e32 v104, 1.0, v104
	v_add_f32_e32 v105, 1.0, v105
	v_rcp_f32_e32 v94, v94
	v_rcp_f32_e32 v95, v95
	v_rcp_f32_e32 v96, v96
	v_rcp_f32_e32 v97, v97
	v_rcp_f32_e32 v102, v102
	v_rcp_f32_e32 v103, v103
	v_rcp_f32_e32 v104, v104
	v_rcp_f32_e32 v105, v105
	v_fma_f32 v94, v174, v94, v173
	v_fma_f32 v95, v175, v95, v172
	v_fma_f32 v96, v176, v96, v171
	v_fma_f32 v97, v177, v97, v170
	v_fma_f32 v102, v178, v102, v169
	v_fma_f32 v103, v179, v103, v168
	v_fma_f32 v104, v180, v104, v167
	v_fma_f32 v105, v181, v105, v166
	v_cmp_gt_f32_e64 s[0:1], s62, v94
	v_cmp_gt_f32_e64 s[32:33], s62, v95
	v_cmp_gt_f32_e64 s[60:61], s62, v96
	v_cndmask_b32_e64 v182, 0, 32, s[0:1]
	v_cndmask_b32_e64 v184, 0, v163, s[0:1]
	v_cmp_gt_f32_e64 s[0:1], s62, v97
	v_cndmask_b32_e64 v185, 0, 32, s[32:33]
	v_cndmask_b32_e64 v187, 0, v163, s[32:33]
	v_cmp_gt_f32_e64 s[32:33], s62, v102
	v_cndmask_b32_e64 v188, 0, 32, s[60:61]
	v_cndmask_b32_e64 v190, 0, v163, s[60:61]
	v_cmp_gt_f32_e64 s[60:61], s62, v103
	v_ldexp_f32 v94, v94, v182
	v_cndmask_b32_e64 v191, 0, 32, s[0:1]
	v_cndmask_b32_e64 v193, 0, v163, s[0:1]
	v_cmp_gt_f32_e64 s[0:1], s62, v104
	v_ldexp_f32 v95, v95, v185
	v_cndmask_b32_e64 v194, 0, 32, s[32:33]
	v_cndmask_b32_e64 v196, 0, v163, s[32:33]
	v_cmp_gt_f32_e64 s[32:33], s62, v105
	v_ldexp_f32 v96, v96, v188
	v_cndmask_b32_e64 v197, 0, 32, s[60:61]
	v_cndmask_b32_e64 v199, 0, v163, s[60:61]
	v_log_f32_e32 v94, v94
	v_ldexp_f32 v97, v97, v191
	v_cndmask_b32_e64 v200, 0, 32, s[0:1]
	v_cndmask_b32_e64 v202, 0, v163, s[0:1]
	v_log_f32_e32 v95, v95
	v_ldexp_f32 v102, v102, v194
	v_cndmask_b32_e64 v203, 0, 32, s[32:33]
	v_cndmask_b32_e64 v110, 0, v163, s[32:33]
	v_log_f32_e32 v96, v96
	v_ldexp_f32 v103, v103, v197
	v_mul_f32_e32 v183, 0x3f317217, v94
	v_cmp_lt_f32_e64 s[60:61], |v94|, s66
	v_log_f32_e32 v97, v97
	v_ldexp_f32 v104, v104, v200
	v_mul_f32_e32 v186, 0x3f317217, v95
	v_cmp_lt_f32_e64 s[0:1], |v95|, s66
	v_log_f32_e32 v102, v102
	v_ldexp_f32 v105, v105, v203
	v_mul_f32_e32 v189, 0x3f317217, v96
	v_cmp_lt_f32_e64 s[32:33], |v96|, s66
	v_log_f32_e32 v103, v103
	v_fma_f32 v183, v94, s63, -v183
	v_mul_f32_e32 v192, 0x3f317217, v97
	v_log_f32_e32 v104, v104
	v_fma_f32 v186, v95, s63, -v186
	v_mul_f32_e32 v195, 0x3f317217, v102
	v_log_f32_e32 v105, v105
	v_fma_f32 v189, v96, s63, -v189
	v_mul_f32_e32 v198, 0x3f317217, v103
	v_fmac_f32_e32 v183, 0x3377d1cf, v94
	v_fma_f32 v192, v97, s63, -v192
	v_mul_f32_e32 v201, 0x3f317217, v104
	v_fmac_f32_e32 v186, 0x3377d1cf, v95
	v_fma_f32 v195, v102, s63, -v195
	v_mul_f32_e32 v204, 0x3f317217, v105
	v_fmac_f32_e32 v189, 0x3377d1cf, v96
	v_fma_f32 v198, v103, s63, -v198
	v_fmac_f32_e32 v183, 0x3f317217, v94
	v_fmac_f32_e32 v192, 0x3377d1cf, v97
	v_fma_f32 v201, v104, s63, -v201
	v_fmac_f32_e32 v186, 0x3f317217, v95
	v_fmac_f32_e32 v195, 0x3377d1cf, v102
	v_fma_f32 v204, v105, s63, -v204
	v_fmac_f32_e32 v189, 0x3f317217, v96
	v_fmac_f32_e32 v198, 0x3377d1cf, v103
	v_cndmask_b32_e64 v94, v94, v183, s[60:61]
	v_cmp_lt_f32_e64 s[60:61], |v97|, s66
	v_fmac_f32_e32 v192, 0x3f317217, v97
	v_fmac_f32_e32 v201, 0x3377d1cf, v104
	v_cndmask_b32_e64 v95, v95, v186, s[0:1]
	v_cmp_lt_f32_e64 s[0:1], |v102|, s66
	v_fmac_f32_e32 v195, 0x3f317217, v102
	v_fmac_f32_e32 v204, 0x3377d1cf, v105
	v_cndmask_b32_e64 v96, v96, v189, s[32:33]
	v_cmp_lt_f32_e64 s[32:33], |v103|, s66
	v_fmac_f32_e32 v198, 0x3f317217, v103
	v_sub_f32_e32 v94, v94, v184
	v_cndmask_b32_e64 v97, v97, v192, s[60:61]
	v_cmp_lt_f32_e64 s[60:61], |v104|, s66
	v_fmac_f32_e32 v201, 0x3f317217, v104
	v_sub_f32_e32 v95, v95, v187
	v_cndmask_b32_e64 v102, v102, v195, s[0:1]
	v_cmp_lt_f32_e64 s[0:1], |v105|, s66
	v_fmac_f32_e32 v204, 0x3f317217, v105
	v_sub_f32_e32 v96, v96, v190
	v_cndmask_b32_e64 v103, v103, v198, s[32:33]
	v_sub_f32_e32 v97, v97, v193
	v_cndmask_b32_e64 v104, v104, v201, s[60:61]
	v_sub_f32_e32 v102, v102, v196
	v_cndmask_b32_e64 v105, v105, v204, s[0:1]
	v_sub_f32_e32 v103, v103, v199
	v_sub_f32_e32 v104, v104, v202
	v_sub_f32_e32 v105, v105, v110

;     __device__ __forceinline__ void operator()(const f32x4 (&acc)[2][2][4][2], const Unit& u, int wr, int wc, int fr, int fq) const {
;     ...
;                 for (int m = 0; m < 4; ++m) {
;                     const int row = row0 + ai * HALF + m * 16; const float rs = rsc ? rsc[row - rbase] : rstd[row];
;                     float v[8];
; #pragma unroll
;                     for (int i = 0; i < 4; ++i) { v[i] = acc[ai][bj][m][0][i] * rs; v[4 + i] = acc[ai][bj][m][1][i] * rs; }
;                     if (seg == 0) {
; #pragma unroll
;                         for (int i = 0; i < 8; ++i) v[i] = v[i] * __builtin_amdgcn_rcpf(1.0f + __expf(-v[i])) * 0.08838834764831845f;
;                     } else if (seg == 1) {
; #pragma unroll
;                         for (int i = 0; i < 8; ++i) { const float s = __builtin_amdgcn_rcpf(1.0f + __expf(-v[i])); v[i] = __logf(lb[i] + (1.0f - lb[i]) * s); }
.LBB0_202:
	v_mul_f32_e32 v86, 0xbfb8aa3b, v78
	v_sub_f32_e32 v174, 1.0, v173
	v_sub_f32_e32 v175, 1.0, v172
	v_sub_f32_e32 v176, 1.0, v171
	v_sub_f32_e32 v177, 1.0, v170
	v_sub_f32_e32 v178, 1.0, v169
	v_sub_f32_e32 v179, 1.0, v168
	v_sub_f32_e32 v180, 1.0, v167
	v_sub_f32_e32 v181, 1.0, v166
	v_mul_f32_e32 v87, 0xbfb8aa3b, v79
	v_mul_f32_e32 v88, 0xbfb8aa3b, v80
	v_mul_f32_e32 v89, 0xbfb8aa3b, v81
	v_mul_f32_e32 v94, 0xbfb8aa3b, v74
	v_mul_f32_e32 v95, 0xbfb8aa3b, v75
	v_mul_f32_e32 v96, 0xbfb8aa3b, v76
	v_mul_f32_e32 v97, 0xbfb8aa3b, v77
	v_exp_f32_e32 v86, v86
	v_exp_f32_e32 v87, v87
	v_exp_f32_e32 v88, v88
	v_exp_f32_e32 v89, v89
	v_exp_f32_e32 v94, v94
	v_exp_f32_e32 v95, v95
	v_exp_f32_e32 v96, v96
	v_exp_f32_e32 v97, v97
	v_add_f32_e32 v86, 1.0, v86
	v_add_f32_e32 v87, 1.0, v87
	v_add_f32_e32 v88, 1.0, v88
	v_add_f32_e32 v89, 1.0, v89
	v_add_f32_e32 v94, 1.0, v94
	v_add_f32_e32 v95, 1.0, v95
	v_add_f32_e32 v96, 1.0, v96
	v_add_f32_e32 v97, 1.0, v97
	v_rcp_f32_e32 v86, v86
	v_rcp_f32_e32 v87, v87
	v_rcp_f32_e32 v88, v88
	v_rcp_f32_e32 v89, v89
	v_rcp_f32_e32 v94, v94
	v_rcp_f32_e32 v95, v95
	v_rcp_f32_e32 v96, v96
	v_rcp_f32_e32 v97, v97
	v_fma_f32 v86, v174, v86, v173
	v_fma_f32 v87, v175, v87, v172
	v_fma_f32 v88, v176, v88, v171
	v_fma_f32 v89, v177, v89, v170
	v_fma_f32 v94, v178, v94, v169
	v_fma_f32 v95, v179, v95, v168
	v_fma_f32 v96, v180, v96, v167
	v_fma_f32 v97, v181, v97, v166
	v_cmp_gt_f32_e64 s[0:1], s62, v86
	v_cmp_gt_f32_e64 s[32:33], s62, v87
	v_cmp_gt_f32_e64 s[60:61], s62, v88
	v_cndmask_b32_e64 v182, 0, 32, s[0:1]
	v_cndmask_b32_e64 v184, 0, v163, s[0:1]
	v_cmp_gt_f32_e64 s[0:1], s62, v89
	v_cndmask_b32_e64 v185, 0, 32, s[32:33]
	v_cndmask_b32_e64 v187, 0, v163, s[32:33]
	v_cmp_gt_f32_e64 s[32:33], s62, v94
	v_cndmask_b32_e64 v188, 0, 32, s[60:61]
	v_cndmask_b32_e64 v190, 0, v163, s[60:61]
	v_cmp_gt_f32_e64 s[60:61], s62, v95
	v_ldexp_f32 v86, v86, v182
	v_cndmask_b32_e64 v191, 0, 32, s[0:1]
	v_cndmask_b32_e64 v193, 0, v163, s[0:1]
	v_cmp_gt_f32_e64 s[0:1], s62, v96
	v_ldexp_f32 v87, v87, v185
	v_cndmask_b32_e64 v194, 0, 32, s[32:33]
	v_cndmask_b32_e64 v196, 0, v163, s[32:33]
	v_cmp_gt_f32_e64 s[32:33], s62, v97
	v_ldexp_f32 v88, v88, v188
	v_cndmask_b32_e64 v197, 0, 32, s[60:61]
	v_cndmask_b32_e64 v199, 0, v163, s[60:61]
	v_log_f32_e32 v86, v86
	v_ldexp_f32 v89, v89, v191
	v_cndmask_b32_e64 v200, 0, 32, s[0:1]
	v_cndmask_b32_e64 v202, 0, v163, s[0:1]
	v_log_f32_e32 v87, v87
	v_ldexp_f32 v94, v94, v194
	v_cndmask_b32_e64 v203, 0, 32, s[32:33]
	v_cndmask_b32_e64 v102, 0, v163, s[32:33]
	v_log_f32_e32 v88, v88
	v_ldexp_f32 v95, v95, v197
	v_mul_f32_e32 v183, 0x3f317217, v86
	v_cmp_lt_f32_e64 s[60:61], |v86|, s66
	v_log_f32_e32 v89, v89
	v_ldexp_f32 v96, v96, v200
	v_mul_f32_e32 v186, 0x3f317217, v87
	v_cmp_lt_f32_e64 s[0:1], |v87|, s66
	v_log_f32_e32 v94, v94
	v_ldexp_f32 v97, v97, v203
	v_mul_f32_e32 v189, 0x3f317217, v88
	v_cmp_lt_f32_e64 s[32:33], |v88|, s66
	v_log_f32_e32 v95, v95
	v_fma_f32 v183, v86, s63, -v183
	v_mul_f32_e32 v192, 0x3f317217, v89
	v_log_f32_e32 v96, v96
	v_fma_f32 v186, v87, s63, -v186
	v_mul_f32_e32 v195, 0x3f317217, v94
	v_log_f32_e32 v97, v97
	v_fma_f32 v189, v88, s63, -v189
	v_mul_f32_e32 v198, 0x3f317217, v95
	v_fmac_f32_e32 v183, 0x3377d1cf, v86
	v_fma_f32 v192, v89, s63, -v192
	v_mul_f32_e32 v201, 0x3f317217, v96
	v_fmac_f32_e32 v186, 0x3377d1cf, v87
	v_fma_f32 v195, v94, s63, -v195
	v_mul_f32_e32 v204, 0x3f317217, v97
	v_fmac_f32_e32 v189, 0x3377d1cf, v88
	v_fma_f32 v198, v95, s63, -v198
	v_fmac_f32_e32 v183, 0x3f317217, v86
	v_fmac_f32_e32 v192, 0x3377d1cf, v89
	v_fma_f32 v201, v96, s63, -v201
	v_fmac_f32_e32 v186, 0x3f317217, v87
	v_fmac_f32_e32 v195, 0x3377d1cf, v94
	v_fma_f32 v204, v97, s63, -v204
	v_fmac_f32_e32 v189, 0x3f317217, v88
	v_fmac_f32_e32 v198, 0x3377d1cf, v95
	v_cndmask_b32_e64 v86, v86, v183, s[60:61]
	v_cmp_lt_f32_e64 s[60:61], |v89|, s66
	v_fmac_f32_e32 v192, 0x3f317217, v89
	v_fmac_f32_e32 v201, 0x3377d1cf, v96
	v_cndmask_b32_e64 v87, v87, v186, s[0:1]
	v_cmp_lt_f32_e64 s[0:1], |v94|, s66
	v_fmac_f32_e32 v195, 0x3f317217, v94
	v_fmac_f32_e32 v204, 0x3377d1cf, v97
	v_cndmask_b32_e64 v88, v88, v189, s[32:33]
	v_cmp_lt_f32_e64 s[32:33], |v95|, s66
	v_fmac_f32_e32 v198, 0x3f317217, v95
	v_sub_f32_e32 v86, v86, v184
	v_cndmask_b32_e64 v89, v89, v192, s[60:61]
	v_cmp_lt_f32_e64 s[60:61], |v96|, s66
	v_fmac_f32_e32 v201, 0x3f317217, v96
	v_sub_f32_e32 v87, v87, v187
	v_cndmask_b32_e64 v94, v94, v195, s[0:1]
	v_cmp_lt_f32_e64 s[0:1], |v97|, s66
	v_fmac_f32_e32 v204, 0x3f317217, v97
	v_sub_f32_e32 v88, v88, v190
	v_cndmask_b32_e64 v95, v95, v198, s[32:33]
	v_sub_f32_e32 v89, v89, v193
	v_cndmask_b32_e64 v96, v96, v201, s[60:61]
	v_sub_f32_e32 v94, v94, v196
	v_cndmask_b32_e64 v97, v97, v204, s[0:1]
	v_sub_f32_e32 v95, v95, v199
	v_sub_f32_e32 v96, v96, v202
	v_sub_f32_e32 v97, v97, v102

;     __device__ __forceinline__ void operator()(const f32x4 (&acc)[2][2][4][2], const Unit& u, int wr, int wc, int fr, int fq) const {
;     ...
;                 for (int m = 0; m < 4; ++m) {
;                     const int row = row0 + ai * HALF + m * 16; const float rs = rsc ? rsc[row - rbase] : rstd[row];
;                     float v[8];
; #pragma unroll
;                     for (int i = 0; i < 4; ++i) { v[i] = acc[ai][bj][m][0][i] * rs; v[4 + i] = acc[ai][bj][m][1][i] * rs; }
;                     if (seg == 0) {
; #pragma unroll
;                         for (int i = 0; i < 8; ++i) v[i] = v[i] * __builtin_amdgcn_rcpf(1.0f + __expf(-v[i])) * 0.08838834764831845f;
;                     } else if (seg == 1) {
; #pragma unroll
;                         for (int i = 0; i < 8; ++i) { const float s = __builtin_amdgcn_rcpf(1.0f + __expf(-v[i])); v[i] = __logf(lb[i] + (1.0f - lb[i]) * s); }
.LBB0_215:
	v_mul_f32_e32 v174, 0xbfb8aa3b, v70
	v_mul_f32_e32 v175, 0xbfb8aa3b, v72
	v_mul_f32_e32 v176, 0xbfb8aa3b, v71
	v_sub_f32_e32 v177, 1.0, v173
	v_sub_f32_e32 v178, 1.0, v171
	v_mul_f32_e32 v179, 0xbfb8aa3b, v73
	v_sub_f32_e32 v180, 1.0, v172
	v_sub_f32_e32 v183, 1.0, v170
	v_mul_f32_e32 v185, 0xbfb8aa3b, v66
	v_sub_f32_e32 v188, 1.0, v169
	v_mul_f32_e32 v190, 0xbfb8aa3b, v67
	v_sub_f32_e32 v192, 1.0, v168
	v_mul_f32_e32 v193, 0xbfb8aa3b, v68
	v_sub_f32_e32 v197, 1.0, v167
	v_mul_f32_e32 v198, 0xbfb8aa3b, v69
	v_sub_f32_e32 v95, 1.0, v166
	v_exp_f32_e32 v174, v174
	v_exp_f32_e32 v175, v175
	v_exp_f32_e32 v176, v176
	v_exp_f32_e32 v179, v179
	v_exp_f32_e32 v185, v185
	v_exp_f32_e32 v190, v190
	v_exp_f32_e32 v193, v193
	v_exp_f32_e32 v198, v198
	v_add_f32_e32 v174, 1.0, v174
	v_add_f32_e32 v175, 1.0, v175
	v_add_f32_e32 v176, 1.0, v176
	v_add_f32_e32 v179, 1.0, v179
	v_add_f32_e32 v185, 1.0, v185
	v_add_f32_e32 v190, 1.0, v190
	v_add_f32_e32 v193, 1.0, v193
	v_add_f32_e32 v198, 1.0, v198
	v_rcp_f32_e32 v174, v174
	v_rcp_f32_e32 v175, v175
	v_rcp_f32_e32 v176, v176
	v_rcp_f32_e32 v179, v179
	v_rcp_f32_e32 v185, v185
	v_rcp_f32_e32 v190, v190
	v_rcp_f32_e32 v193, v193
	v_rcp_f32_e32 v198, v198
	v_fmac_f32_e32 v173, v177, v174
	v_fmac_f32_e32 v171, v178, v175
	v_fmac_f32_e32 v172, v180, v176
	v_fmac_f32_e32 v170, v183, v179
	v_fmac_f32_e32 v169, v188, v185
	v_fmac_f32_e32 v168, v192, v190
	v_fmac_f32_e32 v167, v197, v193
	v_fmac_f32_e32 v166, v95, v198
	v_cmp_gt_f32_e64 s[0:1], s62, v173
	v_cmp_gt_f32_e64 s[8:9], s62, v171
	v_cmp_gt_f32_e64 s[32:33], s62, v172
	v_cmp_gt_f32_e64 s[60:61], s62, v170
	v_cmp_gt_f32_e64 s[6:7], s62, v169
	v_cndmask_b32_e64 v78, 0, 32, s[0:1]
	v_cndmask_b32_e64 v184, 0, v163, s[0:1]
	v_cmp_gt_f32_e64 s[0:1], s62, v168
	v_cndmask_b32_e64 v187, 0, 32, s[8:9]
	v_cndmask_b32_e64 v191, 0, v163, s[8:9]
	v_cmp_gt_f32_e64 s[8:9], s62, v167
	v_cndmask_b32_e64 v182, 0, 32, s[32:33]
	v_cndmask_b32_e64 v186, 0, v163, s[32:33]
	v_cmp_gt_f32_e64 s[32:33], s62, v166
	v_cndmask_b32_e64 v189, 0, 32, s[60:61]
	v_cndmask_b32_e64 v195, 0, v163, s[60:61]
	v_cndmask_b32_e64 v194, 0, 32, s[6:7]
	v_cndmask_b32_e64 v199, 0, v163, s[6:7]
	v_ldexp_f32 v78, v173, v78
	v_cndmask_b32_e64 v196, 0, 32, s[0:1]
	v_cndmask_b32_e64 v201, 0, v163, s[0:1]
	v_ldexp_f32 v187, v171, v187
	v_cndmask_b32_e64 v200, 0, 32, s[8:9]
	v_cndmask_b32_e64 v203, 0, v163, s[8:9]
	v_ldexp_f32 v182, v172, v182
	v_cndmask_b32_e64 v202, 0, 32, s[32:33]
	v_cndmask_b32_e64 v94, 0, v163, s[32:33]
	v_ldexp_f32 v189, v170, v189
	v_ldexp_f32 v194, v169, v194
	v_log_f32_e32 v78, v78
	v_ldexp_f32 v196, v168, v196
	v_log_f32_e32 v187, v187
	v_ldexp_f32 v200, v167, v200
	v_log_f32_e32 v182, v182
	v_ldexp_f32 v202, v166, v202
	v_log_f32_e32 v189, v189
	v_log_f32_e32 v194, v194
	v_mul_f32_e32 v181, 0x3f317217, v78
	v_cmp_lt_f32_e64 s[60:61], |v78|, s66
	v_log_f32_e32 v196, v196
	v_mul_f32_e32 v80, 0x3f317217, v187
	v_cmp_lt_f32_e64 s[6:7], |v187|, s66
	v_log_f32_e32 v200, v200
	v_mul_f32_e32 v79, 0x3f317217, v182
	v_cmp_lt_f32_e64 s[0:1], |v182|, s66
	v_log_f32_e32 v202, v202
	v_mul_f32_e32 v81, 0x3f317217, v189
	v_cmp_lt_f32_e64 s[8:9], |v189|, s66
	v_mul_f32_e32 v86, 0x3f317217, v194
	v_cmp_lt_f32_e64 s[32:33], |v194|, s66
	v_fma_f32 v181, v78, s63, -v181
	v_mul_f32_e32 v87, 0x3f317217, v196
	v_fma_f32 v80, v187, s63, -v80
	v_mul_f32_e32 v88, 0x3f317217, v200
	v_fma_f32 v79, v182, s63, -v79
	v_mul_f32_e32 v89, 0x3f317217, v202
	v_fma_f32 v81, v189, s63, -v81
	v_fma_f32 v86, v194, s63, -v86
	v_fmac_f32_e32 v181, 0x3377d1cf, v78
	v_fma_f32 v87, v196, s63, -v87
	v_fmac_f32_e32 v80, 0x3377d1cf, v187
	v_fma_f32 v88, v200, s63, -v88
	v_fmac_f32_e32 v79, 0x3377d1cf, v182
	v_fma_f32 v89, v202, s63, -v89
	v_fmac_f32_e32 v81, 0x3377d1cf, v189
	v_fmac_f32_e32 v86, 0x3377d1cf, v194
	v_fmac_f32_e32 v181, 0x3f317217, v78
	v_fmac_f32_e32 v87, 0x3377d1cf, v196
	v_fmac_f32_e32 v80, 0x3f317217, v187
	v_fmac_f32_e32 v88, 0x3377d1cf, v200
	v_fmac_f32_e32 v79, 0x3f317217, v182
	v_fmac_f32_e32 v89, 0x3377d1cf, v202
	v_fmac_f32_e32 v81, 0x3f317217, v189
	v_fmac_f32_e32 v86, 0x3f317217, v194
	v_cndmask_b32_e64 v78, v78, v181, s[60:61]
	v_cmp_lt_f32_e64 s[60:61], |v196|, s66
	v_fmac_f32_e32 v87, 0x3f317217, v196
	v_cndmask_b32_e64 v80, v187, v80, s[6:7]
	v_cmp_lt_f32_e64 s[6:7], |v200|, s66
	v_fmac_f32_e32 v88, 0x3f317217, v200
	v_cndmask_b32_e64 v79, v182, v79, s[0:1]
	v_cmp_lt_f32_e64 s[0:1], |v202|, s66
	v_fmac_f32_e32 v89, 0x3f317217, v202
	v_cndmask_b32_e64 v81, v189, v81, s[8:9]
	v_cndmask_b32_e64 v86, v194, v86, s[32:33]
	v_sub_f32_e32 v78, v78, v184
	v_cndmask_b32_e64 v87, v196, v87, s[60:61]
	v_sub_f32_e32 v80, v80, v191
	v_cndmask_b32_e64 v88, v200, v88, s[6:7]
	v_sub_f32_e32 v79, v79, v186
	v_cndmask_b32_e64 v89, v202, v89, s[0:1]
	v_sub_f32_e32 v81, v81, v195
	v_sub_f32_e32 v86, v86, v199
	v_sub_f32_e32 v87, v87, v201
	v_sub_f32_e32 v88, v88, v203
	v_sub_f32_e32 v89, v89, v94

;     __device__ __forceinline__ void operator()(const f32x4 (&acc)[2][2][4][2], const Unit& u, int wr, int wc, int fr, int fq) const {
;     ...
; #pragma unroll
;         for (int bj = 0; bj < 2; ++bj) {
;             const int col0 = u.pn * BM + bj * HALF + wc * 32 + 8 * fq;
;             const int seg = __builtin_amdgcn_readfirstlane(col0 >> 9);
;             float lb[8];
; #pragma unroll
;             for (int i = 0; i < 8; ++i) lb[i] = 0.f;
;             if (seg == 1) {
;                 const int ci = col0 & 511;
; #pragma unroll
;                 for (int i = 0; i < 8; ++i) { const float l0 = lbl[ci + i], l1 = lbl[512 + ci + i]; lb[i] = __builtin_amdgcn_rcpf(1.0f + __expf(l1 - l0)); }
;             }
; #pragma unroll
;             for (int ai = 0; ai < 2; ++ai)
; #pragma unroll
;                 for (int m = 0; m < 4; ++m) {
;                     const int row = row0 + ai * HALF + m * 16; const float rs = rsc ? rsc[row - rbase] : rstd[row];
;                     float v[8];
; #pragma unroll
;                     for (int i = 0; i < 4; ++i) { v[i] = acc[ai][bj][m][0][i] * rs; v[4 + i] = acc[ai][bj][m][1][i] * rs; }
;                     if (seg == 0) {
; #pragma unroll
;                         for (int i = 0; i < 8; ++i) v[i] = v[i] * __builtin_amdgcn_rcpf(1.0f + __expf(-v[i])) * 0.08838834764831845f;
;                     } else if (seg == 1) {
; #pragma unroll
;                         for (int i = 0; i < 8; ++i) { const float s = __builtin_amdgcn_rcpf(1.0f + __expf(-v[i])); v[i] = __logf(lb[i] + (1.0f - lb[i]) * s); }
.LBB0_228:
	v_mul_f32_e32 v68, 0xbfb8aa3b, v62
	v_sub_f32_e32 v174, 1.0, v95
	v_sub_f32_e32 v175, 1.0, v94
	v_sub_f32_e32 v176, 1.0, v89
	v_sub_f32_e32 v177, 1.0, v88
	v_sub_f32_e32 v178, 1.0, v87
	v_sub_f32_e32 v179, 1.0, v86
	v_sub_f32_e32 v180, 1.0, v81
	v_sub_f32_e32 v181, 1.0, v80
	v_mul_f32_e32 v69, 0xbfb8aa3b, v63
	v_mul_f32_e32 v70, 0xbfb8aa3b, v64
	v_mul_f32_e32 v71, 0xbfb8aa3b, v65
	v_mul_f32_e32 v72, 0xbfb8aa3b, v58
	v_mul_f32_e32 v73, 0xbfb8aa3b, v59
	v_mul_f32_e32 v78, 0xbfb8aa3b, v60
	v_mul_f32_e32 v79, 0xbfb8aa3b, v61
	v_exp_f32_e32 v68, v68
	v_exp_f32_e32 v69, v69
	v_exp_f32_e32 v70, v70
	v_exp_f32_e32 v71, v71
	v_exp_f32_e32 v72, v72
	v_exp_f32_e32 v73, v73
	v_exp_f32_e32 v78, v78
	v_exp_f32_e32 v79, v79
	v_add_f32_e32 v68, 1.0, v68
	v_add_f32_e32 v69, 1.0, v69
	v_add_f32_e32 v70, 1.0, v70
	v_add_f32_e32 v71, 1.0, v71
	v_add_f32_e32 v72, 1.0, v72
	v_add_f32_e32 v73, 1.0, v73
	v_add_f32_e32 v78, 1.0, v78
	v_add_f32_e32 v79, 1.0, v79
	v_rcp_f32_e32 v68, v68
	v_rcp_f32_e32 v69, v69
	v_rcp_f32_e32 v70, v70
	v_rcp_f32_e32 v71, v71
	v_rcp_f32_e32 v72, v72
	v_rcp_f32_e32 v73, v73
	v_rcp_f32_e32 v78, v78
	v_rcp_f32_e32 v79, v79
	v_fma_f32 v68, v174, v68, v95
	v_fma_f32 v69, v175, v69, v94
	v_fma_f32 v70, v176, v70, v89
	v_fma_f32 v71, v177, v71, v88
	v_fma_f32 v72, v178, v72, v87
	v_fma_f32 v73, v179, v73, v86
	v_fma_f32 v78, v180, v78, v81
	v_fma_f32 v79, v181, v79, v80
	v_cmp_gt_f32_e64 s[0:1], s62, v68
	v_cmp_gt_f32_e64 s[8:9], s62, v69
	v_cmp_gt_f32_e64 s[32:33], s62, v70
	v_cmp_gt_f32_e64 s[60:61], s62, v71
	v_cndmask_b32_e64 v182, 0, 32, s[0:1]
	v_cndmask_b32_e64 v184, 0, v163, s[0:1]
	v_cmp_gt_f32_e64 s[0:1], s62, v72
	v_cndmask_b32_e64 v185, 0, 32, s[8:9]
	v_cndmask_b32_e64 v187, 0, v163, s[8:9]
	v_cmp_gt_f32_e64 s[8:9], s62, v73
	v_cndmask_b32_e64 v188, 0, 32, s[32:33]
	v_cndmask_b32_e64 v190, 0, v163, s[32:33]
	v_cmp_gt_f32_e64 s[32:33], s62, v78
	v_cndmask_b32_e64 v191, 0, 32, s[60:61]
	v_cndmask_b32_e64 v193, 0, v163, s[60:61]
	v_cmp_gt_f32_e64 s[60:61], s62, v79
	v_ldexp_f32 v68, v68, v182
	v_cndmask_b32_e64 v194, 0, 32, s[0:1]
	v_cndmask_b32_e64 v196, 0, v163, s[0:1]
	v_ldexp_f32 v69, v69, v185
	v_cndmask_b32_e64 v197, 0, 32, s[8:9]
	v_cndmask_b32_e64 v199, 0, v163, s[8:9]
	v_ldexp_f32 v70, v70, v188
	v_cndmask_b32_e64 v200, 0, 32, s[32:33]
	v_cndmask_b32_e64 v202, 0, v163, s[32:33]
	v_ldexp_f32 v71, v71, v191
	v_cndmask_b32_e64 v203, 0, 32, s[60:61]
	v_cndmask_b32_e64 v96, 0, v163, s[60:61]
	v_log_f32_e32 v68, v68
	v_ldexp_f32 v72, v72, v194
	v_log_f32_e32 v69, v69
	v_ldexp_f32 v73, v73, v197
	v_log_f32_e32 v70, v70
	v_ldexp_f32 v78, v78, v200
	v_log_f32_e32 v71, v71
	v_ldexp_f32 v79, v79, v203
	v_mul_f32_e32 v183, 0x3f317217, v68
	v_cmp_lt_f32_e64 s[0:1], |v68|, s66
	v_log_f32_e32 v72, v72
	v_mul_f32_e32 v186, 0x3f317217, v69
	v_cmp_lt_f32_e64 s[8:9], |v69|, s66
	v_log_f32_e32 v73, v73
	v_mul_f32_e32 v189, 0x3f317217, v70
	v_cmp_lt_f32_e64 s[32:33], |v70|, s66
	v_log_f32_e32 v78, v78
	v_mul_f32_e32 v192, 0x3f317217, v71
	v_cmp_lt_f32_e64 s[60:61], |v71|, s66
	v_log_f32_e32 v79, v79
	v_fma_f32 v183, v68, s63, -v183
	v_mul_f32_e32 v195, 0x3f317217, v72
	v_fma_f32 v186, v69, s63, -v186
	v_mul_f32_e32 v198, 0x3f317217, v73
	v_fma_f32 v189, v70, s63, -v189
	v_mul_f32_e32 v201, 0x3f317217, v78
	v_fma_f32 v192, v71, s63, -v192
	v_mul_f32_e32 v204, 0x3f317217, v79
	v_fmac_f32_e32 v183, 0x3377d1cf, v68
	v_fma_f32 v195, v72, s63, -v195
	v_fmac_f32_e32 v186, 0x3377d1cf, v69
	v_fma_f32 v198, v73, s63, -v198
	v_fmac_f32_e32 v189, 0x3377d1cf, v70
	v_fma_f32 v201, v78, s63, -v201
	v_fmac_f32_e32 v192, 0x3377d1cf, v71
	v_fma_f32 v204, v79, s63, -v204
	v_fmac_f32_e32 v183, 0x3f317217, v68
	v_fmac_f32_e32 v195, 0x3377d1cf, v72
	v_fmac_f32_e32 v186, 0x3f317217, v69
	v_fmac_f32_e32 v198, 0x3377d1cf, v73
	v_fmac_f32_e32 v189, 0x3f317217, v70
	v_fmac_f32_e32 v201, 0x3377d1cf, v78
	v_fmac_f32_e32 v192, 0x3f317217, v71
	v_fmac_f32_e32 v204, 0x3377d1cf, v79
	v_cndmask_b32_e64 v68, v68, v183, s[0:1]
	v_cmp_lt_f32_e64 s[0:1], |v72|, s66
	v_fmac_f32_e32 v195, 0x3f317217, v72
	v_cndmask_b32_e64 v69, v69, v186, s[8:9]
	v_cmp_lt_f32_e64 s[8:9], |v73|, s66
	v_fmac_f32_e32 v198, 0x3f317217, v73
	v_cndmask_b32_e64 v70, v70, v189, s[32:33]
	v_cmp_lt_f32_e64 s[32:33], |v78|, s66
	v_fmac_f32_e32 v201, 0x3f317217, v78
	v_cndmask_b32_e64 v71, v71, v192, s[60:61]
	v_cmp_lt_f32_e64 s[60:61], |v79|, s66
	v_fmac_f32_e32 v204, 0x3f317217, v79
	v_sub_f32_e32 v68, v68, v184
	v_cndmask_b32_e64 v72, v72, v195, s[0:1]
	v_sub_f32_e32 v69, v69, v187
	v_cndmask_b32_e64 v73, v73, v198, s[8:9]
	v_sub_f32_e32 v70, v70, v190
	v_cndmask_b32_e64 v78, v78, v201, s[32:33]
	v_sub_f32_e32 v71, v71, v193
	v_cndmask_b32_e64 v79, v79, v204, s[60:61]
	v_sub_f32_e32 v72, v72, v196
	v_sub_f32_e32 v73, v73, v199
	v_sub_f32_e32 v78, v78, v202
	v_sub_f32_e32 v79, v79, v96

;     __device__ __forceinline__ void operator()(const f32x4 (&acc)[2][2][4][2], const Unit& u, int wr, int wc, int fr, int fq) const {
;     ...
;                     } else if (seg == 1) {
; #pragma unroll
;                         for (int i = 0; i < 8; ++i) { const float s = __builtin_amdgcn_rcpf(1.0f + __expf(-v[i])); v[i] = __logf(lb[i] + (1.0f - lb[i]) * s); }
.LBB0_241:
	v_mul_f32_e32 v58, 0xbfb8aa3b, v54
	v_sub_f32_e32 v174, 1.0, v95
	v_sub_f32_e32 v175, 1.0, v94
	v_sub_f32_e32 v176, 1.0, v89
	v_sub_f32_e32 v177, 1.0, v88
	v_sub_f32_e32 v178, 1.0, v87
	v_sub_f32_e32 v179, 1.0, v86
	v_sub_f32_e32 v180, 1.0, v81
	v_sub_f32_e32 v181, 1.0, v80
	v_mul_f32_e32 v59, 0xbfb8aa3b, v55
	v_mul_f32_e32 v60, 0xbfb8aa3b, v56
	v_mul_f32_e32 v61, 0xbfb8aa3b, v57
	v_mul_f32_e32 v62, 0xbfb8aa3b, v50
	v_mul_f32_e32 v63, 0xbfb8aa3b, v51
	v_mul_f32_e32 v64, 0xbfb8aa3b, v52
	v_mul_f32_e32 v65, 0xbfb8aa3b, v53
	v_exp_f32_e32 v58, v58
	v_exp_f32_e32 v59, v59
	v_exp_f32_e32 v60, v60
	v_exp_f32_e32 v61, v61
	v_exp_f32_e32 v62, v62
	v_exp_f32_e32 v63, v63
	v_exp_f32_e32 v64, v64
	v_exp_f32_e32 v65, v65
	v_add_f32_e32 v58, 1.0, v58
	v_add_f32_e32 v59, 1.0, v59
	v_add_f32_e32 v60, 1.0, v60
	v_add_f32_e32 v61, 1.0, v61
	v_add_f32_e32 v62, 1.0, v62
	v_add_f32_e32 v63, 1.0, v63
	v_add_f32_e32 v64, 1.0, v64
	v_add_f32_e32 v65, 1.0, v65
	v_rcp_f32_e32 v58, v58
	v_rcp_f32_e32 v59, v59
	v_rcp_f32_e32 v60, v60
	v_rcp_f32_e32 v61, v61
	v_rcp_f32_e32 v62, v62
	v_rcp_f32_e32 v63, v63
	v_rcp_f32_e32 v64, v64
	v_rcp_f32_e32 v65, v65
	v_fma_f32 v58, v174, v58, v95
	v_fma_f32 v59, v175, v59, v94
	v_fma_f32 v60, v176, v60, v89
	v_fma_f32 v61, v177, v61, v88
	v_fma_f32 v62, v178, v62, v87
	v_fma_f32 v63, v179, v63, v86
	v_fma_f32 v64, v180, v64, v81
	v_fma_f32 v65, v181, v65, v80
	v_cmp_gt_f32_e64 s[0:1], s62, v58
	v_cmp_gt_f32_e64 s[32:33], s62, v59
	v_cmp_gt_f32_e64 s[60:61], s62, v60
	v_cndmask_b32_e64 v182, 0, 32, s[0:1]
	v_cndmask_b32_e64 v184, 0, v163, s[0:1]
	v_cmp_gt_f32_e64 s[0:1], s62, v61
	v_cndmask_b32_e64 v185, 0, 32, s[32:33]
	v_cndmask_b32_e64 v187, 0, v163, s[32:33]
	v_cmp_gt_f32_e64 s[32:33], s62, v62
	v_cndmask_b32_e64 v188, 0, 32, s[60:61]
	v_cndmask_b32_e64 v190, 0, v163, s[60:61]
	v_cmp_gt_f32_e64 s[60:61], s62, v63
	v_ldexp_f32 v58, v58, v182
	v_cndmask_b32_e64 v191, 0, 32, s[0:1]
	v_cndmask_b32_e64 v193, 0, v163, s[0:1]
	v_cmp_gt_f32_e64 s[0:1], s62, v64
	v_ldexp_f32 v59, v59, v185
	v_cndmask_b32_e64 v194, 0, 32, s[32:33]
	v_cndmask_b32_e64 v196, 0, v163, s[32:33]
	v_cmp_gt_f32_e64 s[32:33], s62, v65
	v_ldexp_f32 v60, v60, v188
	v_cndmask_b32_e64 v197, 0, 32, s[60:61]
	v_cndmask_b32_e64 v199, 0, v163, s[60:61]
	v_log_f32_e32 v58, v58
	v_ldexp_f32 v61, v61, v191
	v_cndmask_b32_e64 v200, 0, 32, s[0:1]
	v_cndmask_b32_e64 v202, 0, v163, s[0:1]
	v_log_f32_e32 v59, v59
	v_ldexp_f32 v62, v62, v194
	v_cndmask_b32_e64 v203, 0, 32, s[32:33]
	v_cndmask_b32_e64 v68, 0, v163, s[32:33]
	v_log_f32_e32 v60, v60
	v_ldexp_f32 v63, v63, v197
	v_mul_f32_e32 v183, 0x3f317217, v58
	v_cmp_lt_f32_e64 s[60:61], |v58|, s66
	v_log_f32_e32 v61, v61
	v_ldexp_f32 v64, v64, v200
	v_mul_f32_e32 v186, 0x3f317217, v59
	v_cmp_lt_f32_e64 s[0:1], |v59|, s66
	v_log_f32_e32 v62, v62
	v_ldexp_f32 v65, v65, v203
	v_mul_f32_e32 v189, 0x3f317217, v60
	v_cmp_lt_f32_e64 s[32:33], |v60|, s66
	v_log_f32_e32 v63, v63
	v_fma_f32 v183, v58, s63, -v183
	v_mul_f32_e32 v192, 0x3f317217, v61
	v_log_f32_e32 v64, v64
	v_fma_f32 v186, v59, s63, -v186
	v_mul_f32_e32 v195, 0x3f317217, v62
	v_log_f32_e32 v65, v65
	v_fma_f32 v189, v60, s63, -v189
	v_mul_f32_e32 v198, 0x3f317217, v63
	v_fmac_f32_e32 v183, 0x3377d1cf, v58
	v_fma_f32 v192, v61, s63, -v192
	v_mul_f32_e32 v201, 0x3f317217, v64
	v_fmac_f32_e32 v186, 0x3377d1cf, v59
	v_fma_f32 v195, v62, s63, -v195
	v_mul_f32_e32 v204, 0x3f317217, v65
	v_fmac_f32_e32 v189, 0x3377d1cf, v60
	v_fma_f32 v198, v63, s63, -v198
	v_fmac_f32_e32 v183, 0x3f317217, v58
	v_fmac_f32_e32 v192, 0x3377d1cf, v61
	v_fma_f32 v201, v64, s63, -v201
	v_fmac_f32_e32 v186, 0x3f317217, v59
	v_fmac_f32_e32 v195, 0x3377d1cf, v62
	v_fma_f32 v204, v65, s63, -v204
	v_fmac_f32_e32 v189, 0x3f317217, v60
	v_fmac_f32_e32 v198, 0x3377d1cf, v63
	v_cndmask_b32_e64 v58, v58, v183, s[60:61]
	v_cmp_lt_f32_e64 s[60:61], |v61|, s66
	v_fmac_f32_e32 v192, 0x3f317217, v61
	v_fmac_f32_e32 v201, 0x3377d1cf, v64
	v_cndmask_b32_e64 v59, v59, v186, s[0:1]
	v_cmp_lt_f32_e64 s[0:1], |v62|, s66
	v_fmac_f32_e32 v195, 0x3f317217, v62
	v_fmac_f32_e32 v204, 0x3377d1cf, v65
	v_cndmask_b32_e64 v60, v60, v189, s[32:33]
	v_cmp_lt_f32_e64 s[32:33], |v63|, s66
	v_fmac_f32_e32 v198, 0x3f317217, v63
	v_sub_f32_e32 v58, v58, v184
	v_cndmask_b32_e64 v61, v61, v192, s[60:61]
	v_cmp_lt_f32_e64 s[60:61], |v64|, s66
	v_fmac_f32_e32 v201, 0x3f317217, v64
	v_sub_f32_e32 v59, v59, v187
	v_cndmask_b32_e64 v62, v62, v195, s[0:1]
	v_cmp_lt_f32_e64 s[0:1], |v65|, s66
	v_fmac_f32_e32 v204, 0x3f317217, v65
	v_sub_f32_e32 v60, v60, v190
	v_cndmask_b32_e64 v63, v63, v198, s[32:33]
	v_sub_f32_e32 v61, v61, v193
	v_cndmask_b32_e64 v64, v64, v201, s[60:61]
	v_sub_f32_e32 v62, v62, v196
	v_cndmask_b32_e64 v65, v65, v204, s[0:1]
	v_sub_f32_e32 v63, v63, v199
	v_sub_f32_e32 v64, v64, v202
	v_sub_f32_e32 v65, v65, v68

;     __device__ __forceinline__ void operator()(const f32x4 (&acc)[2][2][4][2], const Unit& u, int wr, int wc, int fr, int fq) const {
;     ...
;                     } else if (seg == 1) {
; #pragma unroll
;                         for (int i = 0; i < 8; ++i) { const float s = __builtin_amdgcn_rcpf(1.0f + __expf(-v[i])); v[i] = __logf(lb[i] + (1.0f - lb[i]) * s); }
.LBB0_254:
	v_mul_f32_e32 v50, 0xbfb8aa3b, v46
	v_sub_f32_e32 v174, 1.0, v95
	v_sub_f32_e32 v175, 1.0, v94
	v_sub_f32_e32 v176, 1.0, v89
	v_sub_f32_e32 v177, 1.0, v88
	v_sub_f32_e32 v178, 1.0, v87
	v_sub_f32_e32 v179, 1.0, v86
	v_sub_f32_e32 v180, 1.0, v81
	v_sub_f32_e32 v181, 1.0, v80
	v_mul_f32_e32 v51, 0xbfb8aa3b, v47
	v_mul_f32_e32 v52, 0xbfb8aa3b, v48
	v_mul_f32_e32 v53, 0xbfb8aa3b, v49
	v_mul_f32_e32 v54, 0xbfb8aa3b, v42
	v_mul_f32_e32 v55, 0xbfb8aa3b, v43
	v_mul_f32_e32 v56, 0xbfb8aa3b, v44
	v_mul_f32_e32 v57, 0xbfb8aa3b, v45
	v_exp_f32_e32 v50, v50
	v_exp_f32_e32 v51, v51
	v_exp_f32_e32 v52, v52
	v_exp_f32_e32 v53, v53
	v_exp_f32_e32 v54, v54
	v_exp_f32_e32 v55, v55
	v_exp_f32_e32 v56, v56
	v_exp_f32_e32 v57, v57
	v_add_f32_e32 v50, 1.0, v50
	v_add_f32_e32 v51, 1.0, v51
	v_add_f32_e32 v52, 1.0, v52
	v_add_f32_e32 v53, 1.0, v53
	v_add_f32_e32 v54, 1.0, v54
	v_add_f32_e32 v55, 1.0, v55
	v_add_f32_e32 v56, 1.0, v56
	v_add_f32_e32 v57, 1.0, v57
	v_rcp_f32_e32 v50, v50
	v_rcp_f32_e32 v51, v51
	v_rcp_f32_e32 v52, v52
	v_rcp_f32_e32 v53, v53
	v_rcp_f32_e32 v54, v54
	v_rcp_f32_e32 v55, v55
	v_rcp_f32_e32 v56, v56
	v_rcp_f32_e32 v57, v57
	v_fma_f32 v50, v174, v50, v95
	v_fma_f32 v51, v175, v51, v94
	v_fma_f32 v52, v176, v52, v89
	v_fma_f32 v53, v177, v53, v88
	v_fma_f32 v54, v178, v54, v87
	v_fma_f32 v55, v179, v55, v86
	v_fma_f32 v56, v180, v56, v81
	v_fma_f32 v57, v181, v57, v80
	v_cmp_gt_f32_e64 s[0:1], s62, v50
	v_cmp_gt_f32_e64 s[32:33], s62, v51
	v_cmp_gt_f32_e64 s[60:61], s62, v52
	v_cndmask_b32_e64 v182, 0, 32, s[0:1]
	v_cndmask_b32_e64 v184, 0, v163, s[0:1]
	v_cmp_gt_f32_e64 s[0:1], s62, v53
	v_cndmask_b32_e64 v185, 0, 32, s[32:33]
	v_cndmask_b32_e64 v187, 0, v163, s[32:33]
	v_cmp_gt_f32_e64 s[32:33], s62, v54
	v_cndmask_b32_e64 v188, 0, 32, s[60:61]
	v_cndmask_b32_e64 v190, 0, v163, s[60:61]
	v_cmp_gt_f32_e64 s[60:61], s62, v55
	v_ldexp_f32 v50, v50, v182
	v_cndmask_b32_e64 v191, 0, 32, s[0:1]
	v_cndmask_b32_e64 v193, 0, v163, s[0:1]
	v_cmp_gt_f32_e64 s[0:1], s62, v56
	v_ldexp_f32 v51, v51, v185
	v_cndmask_b32_e64 v194, 0, 32, s[32:33]
	v_cndmask_b32_e64 v196, 0, v163, s[32:33]
	v_cmp_gt_f32_e64 s[32:33], s62, v57
	v_ldexp_f32 v52, v52, v188
	v_cndmask_b32_e64 v197, 0, 32, s[60:61]
	v_cndmask_b32_e64 v199, 0, v163, s[60:61]
	v_log_f32_e32 v50, v50
	v_ldexp_f32 v53, v53, v191
	v_cndmask_b32_e64 v200, 0, 32, s[0:1]
	v_cndmask_b32_e64 v202, 0, v163, s[0:1]
	v_log_f32_e32 v51, v51
	v_ldexp_f32 v54, v54, v194
	v_cndmask_b32_e64 v203, 0, 32, s[32:33]
	v_cndmask_b32_e64 v58, 0, v163, s[32:33]
	v_log_f32_e32 v52, v52
	v_ldexp_f32 v55, v55, v197
	v_mul_f32_e32 v183, 0x3f317217, v50
	v_cmp_lt_f32_e64 s[60:61], |v50|, s66
	v_log_f32_e32 v53, v53
	v_ldexp_f32 v56, v56, v200
	v_mul_f32_e32 v186, 0x3f317217, v51
	v_cmp_lt_f32_e64 s[0:1], |v51|, s66
	v_log_f32_e32 v54, v54
	v_ldexp_f32 v57, v57, v203
	v_mul_f32_e32 v189, 0x3f317217, v52
	v_cmp_lt_f32_e64 s[32:33], |v52|, s66
	v_log_f32_e32 v55, v55
	v_fma_f32 v183, v50, s63, -v183
	v_mul_f32_e32 v192, 0x3f317217, v53
	v_log_f32_e32 v56, v56
	v_fma_f32 v186, v51, s63, -v186
	v_mul_f32_e32 v195, 0x3f317217, v54
	v_log_f32_e32 v57, v57
	v_fma_f32 v189, v52, s63, -v189
	v_mul_f32_e32 v198, 0x3f317217, v55
	v_fmac_f32_e32 v183, 0x3377d1cf, v50
	v_fma_f32 v192, v53, s63, -v192
	v_mul_f32_e32 v201, 0x3f317217, v56
	v_fmac_f32_e32 v186, 0x3377d1cf, v51
	v_fma_f32 v195, v54, s63, -v195
	v_mul_f32_e32 v204, 0x3f317217, v57
	v_fmac_f32_e32 v189, 0x3377d1cf, v52
	v_fma_f32 v198, v55, s63, -v198
	v_fmac_f32_e32 v183, 0x3f317217, v50
	v_fmac_f32_e32 v192, 0x3377d1cf, v53
	v_fma_f32 v201, v56, s63, -v201
	v_fmac_f32_e32 v186, 0x3f317217, v51
	v_fmac_f32_e32 v195, 0x3377d1cf, v54
	v_fma_f32 v204, v57, s63, -v204
	v_fmac_f32_e32 v189, 0x3f317217, v52
	v_fmac_f32_e32 v198, 0x3377d1cf, v55
	v_cndmask_b32_e64 v50, v50, v183, s[60:61]
	v_cmp_lt_f32_e64 s[60:61], |v53|, s66
	v_fmac_f32_e32 v192, 0x3f317217, v53
	v_fmac_f32_e32 v201, 0x3377d1cf, v56
	v_cndmask_b32_e64 v51, v51, v186, s[0:1]
	v_cmp_lt_f32_e64 s[0:1], |v54|, s66
	v_fmac_f32_e32 v195, 0x3f317217, v54
	v_fmac_f32_e32 v204, 0x3377d1cf, v57
	v_cndmask_b32_e64 v52, v52, v189, s[32:33]
	v_cmp_lt_f32_e64 s[32:33], |v55|, s66
	v_fmac_f32_e32 v198, 0x3f317217, v55
	v_sub_f32_e32 v50, v50, v184
	v_cndmask_b32_e64 v53, v53, v192, s[60:61]
	v_cmp_lt_f32_e64 s[60:61], |v56|, s66
	v_fmac_f32_e32 v201, 0x3f317217, v56
	v_sub_f32_e32 v51, v51, v187
	v_cndmask_b32_e64 v54, v54, v195, s[0:1]
	v_cmp_lt_f32_e64 s[0:1], |v57|, s66
	v_fmac_f32_e32 v204, 0x3f317217, v57
	v_sub_f32_e32 v52, v52, v190
	v_cndmask_b32_e64 v55, v55, v198, s[32:33]
	v_sub_f32_e32 v53, v53, v193
	v_cndmask_b32_e64 v56, v56, v201, s[60:61]
	v_sub_f32_e32 v54, v54, v196
	v_cndmask_b32_e64 v57, v57, v204, s[0:1]
	v_sub_f32_e32 v55, v55, v199
	v_sub_f32_e32 v56, v56, v202
	v_sub_f32_e32 v57, v57, v58

;     __device__ __forceinline__ void operator()(const f32x4 (&acc)[2][2][4][2], const Unit& u, int wr, int wc, int fr, int fq) const {
;     ...
;                     } else if (seg == 1) {
; #pragma unroll
;                         for (int i = 0; i < 8; ++i) { const float s = __builtin_amdgcn_rcpf(1.0f + __expf(-v[i])); v[i] = __logf(lb[i] + (1.0f - lb[i]) * s); }
.LBB0_267:
	v_mul_f32_e32 v42, 0xbfb8aa3b, v38
	v_sub_f32_e32 v174, 1.0, v95
	v_sub_f32_e32 v175, 1.0, v94
	v_sub_f32_e32 v176, 1.0, v89
	v_sub_f32_e32 v177, 1.0, v88
	v_sub_f32_e32 v178, 1.0, v87
	v_sub_f32_e32 v179, 1.0, v86
	v_sub_f32_e32 v180, 1.0, v81
	v_sub_f32_e32 v181, 1.0, v80
	v_mul_f32_e32 v43, 0xbfb8aa3b, v39
	v_mul_f32_e32 v44, 0xbfb8aa3b, v40
	v_mul_f32_e32 v45, 0xbfb8aa3b, v41
	v_mul_f32_e32 v46, 0xbfb8aa3b, v34
	v_mul_f32_e32 v47, 0xbfb8aa3b, v35
	v_mul_f32_e32 v48, 0xbfb8aa3b, v36
	v_mul_f32_e32 v49, 0xbfb8aa3b, v37
	v_exp_f32_e32 v42, v42
	v_exp_f32_e32 v43, v43
	v_exp_f32_e32 v44, v44
	v_exp_f32_e32 v45, v45
	v_exp_f32_e32 v46, v46
	v_exp_f32_e32 v47, v47
	v_exp_f32_e32 v48, v48
	v_exp_f32_e32 v49, v49
	v_add_f32_e32 v42, 1.0, v42
	v_add_f32_e32 v43, 1.0, v43
	v_add_f32_e32 v44, 1.0, v44
	v_add_f32_e32 v45, 1.0, v45
	v_add_f32_e32 v46, 1.0, v46
	v_add_f32_e32 v47, 1.0, v47
	v_add_f32_e32 v48, 1.0, v48
	v_add_f32_e32 v49, 1.0, v49
	v_rcp_f32_e32 v42, v42
	v_rcp_f32_e32 v43, v43
	v_rcp_f32_e32 v44, v44
	v_rcp_f32_e32 v45, v45
	v_rcp_f32_e32 v46, v46
	v_rcp_f32_e32 v47, v47
	v_rcp_f32_e32 v48, v48
	v_rcp_f32_e32 v49, v49
	v_fma_f32 v42, v174, v42, v95
	v_fma_f32 v43, v175, v43, v94
	v_fma_f32 v44, v176, v44, v89
	v_fma_f32 v45, v177, v45, v88
	v_fma_f32 v46, v178, v46, v87
	v_fma_f32 v47, v179, v47, v86
	v_fma_f32 v48, v180, v48, v81
	v_fma_f32 v49, v181, v49, v80
	v_cmp_gt_f32_e64 s[0:1], s62, v42
	v_cmp_gt_f32_e64 s[32:33], s62, v43
	v_cmp_gt_f32_e64 s[60:61], s62, v44
	v_cndmask_b32_e64 v182, 0, 32, s[0:1]
	v_cndmask_b32_e64 v184, 0, v163, s[0:1]
	v_cmp_gt_f32_e64 s[0:1], s62, v45
	v_cndmask_b32_e64 v185, 0, 32, s[32:33]
	v_cndmask_b32_e64 v187, 0, v163, s[32:33]
	v_cmp_gt_f32_e64 s[32:33], s62, v46
	v_cndmask_b32_e64 v188, 0, 32, s[60:61]
	v_cndmask_b32_e64 v190, 0, v163, s[60:61]
	v_cmp_gt_f32_e64 s[60:61], s62, v47
	v_ldexp_f32 v42, v42, v182
	v_cndmask_b32_e64 v191, 0, 32, s[0:1]
	v_cndmask_b32_e64 v193, 0, v163, s[0:1]
	v_cmp_gt_f32_e64 s[0:1], s62, v48
	v_ldexp_f32 v43, v43, v185
	v_cndmask_b32_e64 v194, 0, 32, s[32:33]
	v_cndmask_b32_e64 v196, 0, v163, s[32:33]
	v_cmp_gt_f32_e64 s[32:33], s62, v49
	v_ldexp_f32 v44, v44, v188
	v_cndmask_b32_e64 v197, 0, 32, s[60:61]
	v_cndmask_b32_e64 v199, 0, v163, s[60:61]
	v_log_f32_e32 v42, v42
	v_ldexp_f32 v45, v45, v191
	v_cndmask_b32_e64 v200, 0, 32, s[0:1]
	v_cndmask_b32_e64 v202, 0, v163, s[0:1]
	v_log_f32_e32 v43, v43
	v_ldexp_f32 v46, v46, v194
	v_cndmask_b32_e64 v203, 0, 32, s[32:33]
	v_cndmask_b32_e64 v50, 0, v163, s[32:33]
	v_log_f32_e32 v44, v44
	v_ldexp_f32 v47, v47, v197
	v_mul_f32_e32 v183, 0x3f317217, v42
	v_cmp_lt_f32_e64 s[60:61], |v42|, s66
	v_log_f32_e32 v45, v45
	v_ldexp_f32 v48, v48, v200
	v_mul_f32_e32 v186, 0x3f317217, v43
	v_cmp_lt_f32_e64 s[0:1], |v43|, s66
	v_log_f32_e32 v46, v46
	v_ldexp_f32 v49, v49, v203
	v_mul_f32_e32 v189, 0x3f317217, v44
	v_cmp_lt_f32_e64 s[32:33], |v44|, s66
	v_log_f32_e32 v47, v47
	v_fma_f32 v183, v42, s63, -v183
	v_mul_f32_e32 v192, 0x3f317217, v45
	v_log_f32_e32 v48, v48
	v_fma_f32 v186, v43, s63, -v186
	v_mul_f32_e32 v195, 0x3f317217, v46
	v_log_f32_e32 v49, v49
	v_fma_f32 v189, v44, s63, -v189
	v_mul_f32_e32 v198, 0x3f317217, v47
	v_fmac_f32_e32 v183, 0x3377d1cf, v42
	v_fma_f32 v192, v45, s63, -v192
	v_mul_f32_e32 v201, 0x3f317217, v48
	v_fmac_f32_e32 v186, 0x3377d1cf, v43
	v_fma_f32 v195, v46, s63, -v195
	v_mul_f32_e32 v204, 0x3f317217, v49
	v_fmac_f32_e32 v189, 0x3377d1cf, v44
	v_fma_f32 v198, v47, s63, -v198
	v_fmac_f32_e32 v183, 0x3f317217, v42
	v_fmac_f32_e32 v192, 0x3377d1cf, v45
	v_fma_f32 v201, v48, s63, -v201
	v_fmac_f32_e32 v186, 0x3f317217, v43
	v_fmac_f32_e32 v195, 0x3377d1cf, v46
	v_fma_f32 v204, v49, s63, -v204
	v_fmac_f32_e32 v189, 0x3f317217, v44
	v_fmac_f32_e32 v198, 0x3377d1cf, v47
	v_cndmask_b32_e64 v42, v42, v183, s[60:61]
	v_cmp_lt_f32_e64 s[60:61], |v45|, s66
	v_fmac_f32_e32 v192, 0x3f317217, v45
	v_fmac_f32_e32 v201, 0x3377d1cf, v48
	v_cndmask_b32_e64 v43, v43, v186, s[0:1]
	v_cmp_lt_f32_e64 s[0:1], |v46|, s66
	v_fmac_f32_e32 v195, 0x3f317217, v46
	v_fmac_f32_e32 v204, 0x3377d1cf, v49
	v_cndmask_b32_e64 v44, v44, v189, s[32:33]
	v_cmp_lt_f32_e64 s[32:33], |v47|, s66
	v_fmac_f32_e32 v198, 0x3f317217, v47
	v_sub_f32_e32 v42, v42, v184
	v_cndmask_b32_e64 v45, v45, v192, s[60:61]
	v_cmp_lt_f32_e64 s[60:61], |v48|, s66
	v_fmac_f32_e32 v201, 0x3f317217, v48
	v_sub_f32_e32 v43, v43, v187
	v_cndmask_b32_e64 v46, v46, v195, s[0:1]
	v_cmp_lt_f32_e64 s[0:1], |v49|, s66
	v_fmac_f32_e32 v204, 0x3f317217, v49
	v_sub_f32_e32 v44, v44, v190
	v_cndmask_b32_e64 v47, v47, v198, s[32:33]
	v_sub_f32_e32 v45, v45, v193
	v_cndmask_b32_e64 v48, v48, v201, s[60:61]
	v_sub_f32_e32 v46, v46, v196
	v_cndmask_b32_e64 v49, v49, v204, s[0:1]
	v_sub_f32_e32 v47, v47, v199
	v_sub_f32_e32 v48, v48, v202
	v_sub_f32_e32 v49, v49, v50

;     __device__ __forceinline__ void operator()(const f32x4 (&acc)[2][2][4][2], const Unit& u, int wr, int wc, int fr, int fq) const {
;     ...
;                     } else if (seg == 1) {
; #pragma unroll
;                         for (int i = 0; i < 8; ++i) { const float s = __builtin_amdgcn_rcpf(1.0f + __expf(-v[i])); v[i] = __logf(lb[i] + (1.0f - lb[i]) * s); }
.LBB0_280:
	v_mul_f32_e32 v34, 0xbfb8aa3b, v30
	v_sub_f32_e32 v174, 1.0, v95
	v_sub_f32_e32 v175, 1.0, v94
	v_sub_f32_e32 v176, 1.0, v89
	v_sub_f32_e32 v177, 1.0, v88
	v_sub_f32_e32 v178, 1.0, v87
	v_sub_f32_e32 v179, 1.0, v86
	v_sub_f32_e32 v180, 1.0, v81
	v_sub_f32_e32 v181, 1.0, v80
	v_mul_f32_e32 v35, 0xbfb8aa3b, v31
	v_mul_f32_e32 v36, 0xbfb8aa3b, v32
	v_mul_f32_e32 v37, 0xbfb8aa3b, v33
	v_mul_f32_e32 v38, 0xbfb8aa3b, v26
	v_mul_f32_e32 v39, 0xbfb8aa3b, v27
	v_mul_f32_e32 v40, 0xbfb8aa3b, v28
	v_mul_f32_e32 v41, 0xbfb8aa3b, v29
	v_exp_f32_e32 v34, v34
	v_exp_f32_e32 v35, v35
	v_exp_f32_e32 v36, v36
	v_exp_f32_e32 v37, v37
	v_exp_f32_e32 v38, v38
	v_exp_f32_e32 v39, v39
	v_exp_f32_e32 v40, v40
	v_exp_f32_e32 v41, v41
	v_add_f32_e32 v34, 1.0, v34
	v_add_f32_e32 v35, 1.0, v35
	v_add_f32_e32 v36, 1.0, v36
	v_add_f32_e32 v37, 1.0, v37
	v_add_f32_e32 v38, 1.0, v38
	v_add_f32_e32 v39, 1.0, v39
	v_add_f32_e32 v40, 1.0, v40
	v_add_f32_e32 v41, 1.0, v41
	v_rcp_f32_e32 v34, v34
	v_rcp_f32_e32 v35, v35
	v_rcp_f32_e32 v36, v36
	v_rcp_f32_e32 v37, v37
	v_rcp_f32_e32 v38, v38
	v_rcp_f32_e32 v39, v39
	v_rcp_f32_e32 v40, v40
	v_rcp_f32_e32 v41, v41
	v_fma_f32 v34, v174, v34, v95
	v_fma_f32 v35, v175, v35, v94
	v_fma_f32 v36, v176, v36, v89
	v_fma_f32 v37, v177, v37, v88
	v_fma_f32 v38, v178, v38, v87
	v_fma_f32 v39, v179, v39, v86
	v_fma_f32 v40, v180, v40, v81
	v_fma_f32 v41, v181, v41, v80
	v_cmp_gt_f32_e64 s[0:1], s62, v34
	v_cmp_gt_f32_e64 s[32:33], s62, v35
	v_cmp_gt_f32_e64 s[60:61], s62, v36
	v_cndmask_b32_e64 v182, 0, 32, s[0:1]
	v_cndmask_b32_e64 v184, 0, v163, s[0:1]
	v_cmp_gt_f32_e64 s[0:1], s62, v37
	v_cndmask_b32_e64 v185, 0, 32, s[32:33]
	v_cndmask_b32_e64 v187, 0, v163, s[32:33]
	v_cmp_gt_f32_e64 s[32:33], s62, v38
	v_cndmask_b32_e64 v188, 0, 32, s[60:61]
	v_cndmask_b32_e64 v190, 0, v163, s[60:61]
	v_cmp_gt_f32_e64 s[60:61], s62, v39
	v_ldexp_f32 v34, v34, v182
	v_cndmask_b32_e64 v191, 0, 32, s[0:1]
	v_cndmask_b32_e64 v193, 0, v163, s[0:1]
	v_cmp_gt_f32_e64 s[0:1], s62, v40
	v_ldexp_f32 v35, v35, v185
	v_cndmask_b32_e64 v194, 0, 32, s[32:33]
	v_cndmask_b32_e64 v196, 0, v163, s[32:33]
	v_cmp_gt_f32_e64 s[32:33], s62, v41
	v_ldexp_f32 v36, v36, v188
	v_cndmask_b32_e64 v197, 0, 32, s[60:61]
	v_cndmask_b32_e64 v199, 0, v163, s[60:61]
	v_log_f32_e32 v34, v34
	v_ldexp_f32 v37, v37, v191
	v_cndmask_b32_e64 v200, 0, 32, s[0:1]
	v_cndmask_b32_e64 v202, 0, v163, s[0:1]
	v_log_f32_e32 v35, v35
	v_ldexp_f32 v38, v38, v194
	v_cndmask_b32_e64 v203, 0, 32, s[32:33]
	v_cndmask_b32_e64 v42, 0, v163, s[32:33]
	v_log_f32_e32 v36, v36
	v_ldexp_f32 v39, v39, v197
	v_mul_f32_e32 v183, 0x3f317217, v34
	v_cmp_lt_f32_e64 s[60:61], |v34|, s66
	v_log_f32_e32 v37, v37
	v_ldexp_f32 v40, v40, v200
	v_mul_f32_e32 v186, 0x3f317217, v35
	v_cmp_lt_f32_e64 s[0:1], |v35|, s66
	v_log_f32_e32 v38, v38
	v_ldexp_f32 v41, v41, v203
	v_mul_f32_e32 v189, 0x3f317217, v36
	v_cmp_lt_f32_e64 s[32:33], |v36|, s66
	v_log_f32_e32 v39, v39
	v_fma_f32 v183, v34, s63, -v183
	v_mul_f32_e32 v192, 0x3f317217, v37
	v_log_f32_e32 v40, v40
	v_fma_f32 v186, v35, s63, -v186
	v_mul_f32_e32 v195, 0x3f317217, v38
	v_log_f32_e32 v41, v41
	v_fma_f32 v189, v36, s63, -v189
	v_mul_f32_e32 v198, 0x3f317217, v39
	v_fmac_f32_e32 v183, 0x3377d1cf, v34
	v_fma_f32 v192, v37, s63, -v192
	v_mul_f32_e32 v201, 0x3f317217, v40
	v_fmac_f32_e32 v186, 0x3377d1cf, v35
	v_fma_f32 v195, v38, s63, -v195
	v_mul_f32_e32 v204, 0x3f317217, v41
	v_fmac_f32_e32 v189, 0x3377d1cf, v36
	v_fma_f32 v198, v39, s63, -v198
	v_fmac_f32_e32 v183, 0x3f317217, v34
	v_fmac_f32_e32 v192, 0x3377d1cf, v37
	v_fma_f32 v201, v40, s63, -v201
	v_fmac_f32_e32 v186, 0x3f317217, v35
	v_fmac_f32_e32 v195, 0x3377d1cf, v38
	v_fma_f32 v204, v41, s63, -v204
	v_fmac_f32_e32 v189, 0x3f317217, v36
	v_fmac_f32_e32 v198, 0x3377d1cf, v39
	v_cndmask_b32_e64 v34, v34, v183, s[60:61]
	v_cmp_lt_f32_e64 s[60:61], |v37|, s66
	v_fmac_f32_e32 v192, 0x3f317217, v37
	v_fmac_f32_e32 v201, 0x3377d1cf, v40
	v_cndmask_b32_e64 v35, v35, v186, s[0:1]
	v_cmp_lt_f32_e64 s[0:1], |v38|, s66
	v_fmac_f32_e32 v195, 0x3f317217, v38
	v_fmac_f32_e32 v204, 0x3377d1cf, v41
	v_cndmask_b32_e64 v36, v36, v189, s[32:33]
	v_cmp_lt_f32_e64 s[32:33], |v39|, s66
	v_fmac_f32_e32 v198, 0x3f317217, v39
	v_sub_f32_e32 v34, v34, v184
	v_cndmask_b32_e64 v37, v37, v192, s[60:61]
	v_cmp_lt_f32_e64 s[60:61], |v40|, s66
	v_fmac_f32_e32 v201, 0x3f317217, v40
	v_sub_f32_e32 v35, v35, v187
	v_cndmask_b32_e64 v38, v38, v195, s[0:1]
	v_cmp_lt_f32_e64 s[0:1], |v41|, s66
	v_fmac_f32_e32 v204, 0x3f317217, v41
	v_sub_f32_e32 v36, v36, v190
	v_cndmask_b32_e64 v39, v39, v198, s[32:33]
	v_sub_f32_e32 v37, v37, v193
	v_cndmask_b32_e64 v40, v40, v201, s[60:61]
	v_sub_f32_e32 v38, v38, v196
	v_cndmask_b32_e64 v41, v41, v204, s[0:1]
	v_sub_f32_e32 v39, v39, v199
	v_sub_f32_e32 v40, v40, v202
	v_sub_f32_e32 v41, v41, v42

;     __device__ __forceinline__ void operator()(const f32x4 (&acc)[2][2][4][2], const Unit& u, int wr, int wc, int fr, int fq) const {
;     ...
;                     } else if (seg == 1) {
; #pragma unroll
;                         for (int i = 0; i < 8; ++i) { const float s = __builtin_amdgcn_rcpf(1.0f + __expf(-v[i])); v[i] = __logf(lb[i] + (1.0f - lb[i]) * s); }
.LBB0_293:
	v_mul_f32_e32 v26, 0xbfb8aa3b, v22
	v_sub_f32_e32 v174, 1.0, v95
	v_sub_f32_e32 v175, 1.0, v94
	v_sub_f32_e32 v176, 1.0, v89
	v_sub_f32_e32 v177, 1.0, v88
	v_sub_f32_e32 v178, 1.0, v87
	v_sub_f32_e32 v179, 1.0, v86
	v_sub_f32_e32 v180, 1.0, v81
	v_sub_f32_e32 v181, 1.0, v80
	v_mul_f32_e32 v27, 0xbfb8aa3b, v23
	v_mul_f32_e32 v28, 0xbfb8aa3b, v24
	v_mul_f32_e32 v29, 0xbfb8aa3b, v25
	v_mul_f32_e32 v30, 0xbfb8aa3b, v18
	v_mul_f32_e32 v31, 0xbfb8aa3b, v19
	v_mul_f32_e32 v32, 0xbfb8aa3b, v20
	v_mul_f32_e32 v33, 0xbfb8aa3b, v21
	v_exp_f32_e32 v26, v26
	v_exp_f32_e32 v27, v27
	v_exp_f32_e32 v28, v28
	v_exp_f32_e32 v29, v29
	v_exp_f32_e32 v30, v30
	v_exp_f32_e32 v31, v31
	v_exp_f32_e32 v32, v32
	v_exp_f32_e32 v33, v33
	v_add_f32_e32 v26, 1.0, v26
	v_add_f32_e32 v27, 1.0, v27
	v_add_f32_e32 v28, 1.0, v28
	v_add_f32_e32 v29, 1.0, v29
	v_add_f32_e32 v30, 1.0, v30
	v_add_f32_e32 v31, 1.0, v31
	v_add_f32_e32 v32, 1.0, v32
	v_add_f32_e32 v33, 1.0, v33
	v_rcp_f32_e32 v26, v26
	v_rcp_f32_e32 v27, v27
	v_rcp_f32_e32 v28, v28
	v_rcp_f32_e32 v29, v29
	v_rcp_f32_e32 v30, v30
	v_rcp_f32_e32 v31, v31
	v_rcp_f32_e32 v32, v32
	v_rcp_f32_e32 v33, v33
	v_fma_f32 v26, v174, v26, v95
	v_fma_f32 v27, v175, v27, v94
	v_fma_f32 v28, v176, v28, v89
	v_fma_f32 v29, v177, v29, v88
	v_fma_f32 v30, v178, v30, v87
	v_fma_f32 v31, v179, v31, v86
	v_fma_f32 v32, v180, v32, v81
	v_fma_f32 v33, v181, v33, v80
	v_cmp_gt_f32_e64 s[0:1], s62, v26
	v_cmp_gt_f32_e64 s[32:33], s62, v27
	v_cmp_gt_f32_e64 s[60:61], s62, v28
	v_cndmask_b32_e64 v182, 0, 32, s[0:1]
	v_cndmask_b32_e64 v184, 0, v163, s[0:1]
	v_cmp_gt_f32_e64 s[0:1], s62, v29
	v_cndmask_b32_e64 v185, 0, 32, s[32:33]
	v_cndmask_b32_e64 v187, 0, v163, s[32:33]
	v_cmp_gt_f32_e64 s[32:33], s62, v30
	v_cndmask_b32_e64 v188, 0, 32, s[60:61]
	v_cndmask_b32_e64 v190, 0, v163, s[60:61]
	v_cmp_gt_f32_e64 s[60:61], s62, v31
	v_ldexp_f32 v26, v26, v182
	v_cndmask_b32_e64 v191, 0, 32, s[0:1]
	v_cndmask_b32_e64 v193, 0, v163, s[0:1]
	v_cmp_gt_f32_e64 s[0:1], s62, v32
	v_ldexp_f32 v27, v27, v185
	v_cndmask_b32_e64 v194, 0, 32, s[32:33]
	v_cndmask_b32_e64 v196, 0, v163, s[32:33]
	v_cmp_gt_f32_e64 s[32:33], s62, v33
	v_ldexp_f32 v28, v28, v188
	v_cndmask_b32_e64 v197, 0, 32, s[60:61]
	v_cndmask_b32_e64 v199, 0, v163, s[60:61]
	v_log_f32_e32 v26, v26
	v_ldexp_f32 v29, v29, v191
	v_cndmask_b32_e64 v200, 0, 32, s[0:1]
	v_cndmask_b32_e64 v202, 0, v163, s[0:1]
	v_log_f32_e32 v27, v27
	v_ldexp_f32 v30, v30, v194
	v_cndmask_b32_e64 v203, 0, 32, s[32:33]
	v_cndmask_b32_e64 v34, 0, v163, s[32:33]
	v_log_f32_e32 v28, v28
	v_ldexp_f32 v31, v31, v197
	v_mul_f32_e32 v183, 0x3f317217, v26
	v_cmp_lt_f32_e64 s[60:61], |v26|, s66
	v_log_f32_e32 v29, v29
	v_ldexp_f32 v32, v32, v200
	v_mul_f32_e32 v186, 0x3f317217, v27
	v_cmp_lt_f32_e64 s[0:1], |v27|, s66
	v_log_f32_e32 v30, v30
	v_ldexp_f32 v33, v33, v203
	v_mul_f32_e32 v189, 0x3f317217, v28
	v_cmp_lt_f32_e64 s[32:33], |v28|, s66
	v_log_f32_e32 v31, v31
	v_fma_f32 v183, v26, s63, -v183
	v_mul_f32_e32 v192, 0x3f317217, v29
	v_log_f32_e32 v32, v32
	v_fma_f32 v186, v27, s63, -v186
	v_mul_f32_e32 v195, 0x3f317217, v30
	v_log_f32_e32 v33, v33
	v_fma_f32 v189, v28, s63, -v189
	v_mul_f32_e32 v198, 0x3f317217, v31
	v_fmac_f32_e32 v183, 0x3377d1cf, v26
	v_fma_f32 v192, v29, s63, -v192
	v_mul_f32_e32 v201, 0x3f317217, v32
	v_fmac_f32_e32 v186, 0x3377d1cf, v27
	v_fma_f32 v195, v30, s63, -v195
	v_mul_f32_e32 v204, 0x3f317217, v33
	v_fmac_f32_e32 v189, 0x3377d1cf, v28
	v_fma_f32 v198, v31, s63, -v198
	v_fmac_f32_e32 v183, 0x3f317217, v26
	v_fmac_f32_e32 v192, 0x3377d1cf, v29
	v_fma_f32 v201, v32, s63, -v201
	v_fmac_f32_e32 v186, 0x3f317217, v27
	v_fmac_f32_e32 v195, 0x3377d1cf, v30
	v_fma_f32 v204, v33, s63, -v204
	v_fmac_f32_e32 v189, 0x3f317217, v28
	v_fmac_f32_e32 v198, 0x3377d1cf, v31
	v_cndmask_b32_e64 v26, v26, v183, s[60:61]
	v_cmp_lt_f32_e64 s[60:61], |v29|, s66
	v_fmac_f32_e32 v192, 0x3f317217, v29
	v_fmac_f32_e32 v201, 0x3377d1cf, v32
	v_cndmask_b32_e64 v27, v27, v186, s[0:1]
	v_cmp_lt_f32_e64 s[0:1], |v30|, s66
	v_fmac_f32_e32 v195, 0x3f317217, v30
	v_fmac_f32_e32 v204, 0x3377d1cf, v33
	v_cndmask_b32_e64 v28, v28, v189, s[32:33]
	v_cmp_lt_f32_e64 s[32:33], |v31|, s66
	v_fmac_f32_e32 v198, 0x3f317217, v31
	v_sub_f32_e32 v26, v26, v184
	v_cndmask_b32_e64 v29, v29, v192, s[60:61]
	v_cmp_lt_f32_e64 s[60:61], |v32|, s66
	v_fmac_f32_e32 v201, 0x3f317217, v32
	v_sub_f32_e32 v27, v27, v187
	v_cndmask_b32_e64 v30, v30, v195, s[0:1]
	v_cmp_lt_f32_e64 s[0:1], |v33|, s66
	v_fmac_f32_e32 v204, 0x3f317217, v33
	v_sub_f32_e32 v28, v28, v190
	v_cndmask_b32_e64 v31, v31, v198, s[32:33]
	v_sub_f32_e32 v29, v29, v193
	v_cndmask_b32_e64 v32, v32, v201, s[60:61]
	v_sub_f32_e32 v30, v30, v196
	v_cndmask_b32_e64 v33, v33, v204, s[0:1]
	v_sub_f32_e32 v31, v31, v199
	v_sub_f32_e32 v32, v32, v202
	v_sub_f32_e32 v33, v33, v34

;     __device__ __forceinline__ void operator()(const f32x4 (&acc)[2][2][4][2], const Unit& u, int wr, int wc, int fr, int fq) const {
;     ...
;                     } else if (seg == 1) {
; #pragma unroll
;                         for (int i = 0; i < 8; ++i) { const float s = __builtin_amdgcn_rcpf(1.0f + __expf(-v[i])); v[i] = __logf(lb[i] + (1.0f - lb[i]) * s); }
.LBB0_306:
	v_mul_f32_e32 v18, 0xbfb8aa3b, v14
	v_sub_f32_e32 v174, 1.0, v95
	v_sub_f32_e32 v175, 1.0, v94
	v_sub_f32_e32 v176, 1.0, v89
	v_sub_f32_e32 v177, 1.0, v88
	v_sub_f32_e32 v178, 1.0, v87
	v_sub_f32_e32 v179, 1.0, v86
	v_sub_f32_e32 v180, 1.0, v81
	v_sub_f32_e32 v181, 1.0, v80
	v_mul_f32_e32 v19, 0xbfb8aa3b, v15
	v_mul_f32_e32 v20, 0xbfb8aa3b, v16
	v_mul_f32_e32 v21, 0xbfb8aa3b, v17
	v_mul_f32_e32 v22, 0xbfb8aa3b, v10
	v_mul_f32_e32 v23, 0xbfb8aa3b, v11
	v_mul_f32_e32 v24, 0xbfb8aa3b, v12
	v_mul_f32_e32 v25, 0xbfb8aa3b, v13
	v_exp_f32_e32 v18, v18
	v_exp_f32_e32 v19, v19
	v_exp_f32_e32 v20, v20
	v_exp_f32_e32 v21, v21
	v_exp_f32_e32 v22, v22
	v_exp_f32_e32 v23, v23
	v_exp_f32_e32 v24, v24
	v_exp_f32_e32 v25, v25
	v_add_f32_e32 v18, 1.0, v18
	v_add_f32_e32 v19, 1.0, v19
	v_add_f32_e32 v20, 1.0, v20
	v_add_f32_e32 v21, 1.0, v21
	v_add_f32_e32 v22, 1.0, v22
	v_add_f32_e32 v23, 1.0, v23
	v_add_f32_e32 v24, 1.0, v24
	v_add_f32_e32 v25, 1.0, v25
	v_rcp_f32_e32 v18, v18
	v_rcp_f32_e32 v19, v19
	v_rcp_f32_e32 v20, v20
	v_rcp_f32_e32 v21, v21
	v_rcp_f32_e32 v22, v22
	v_rcp_f32_e32 v23, v23
	v_rcp_f32_e32 v24, v24
	v_rcp_f32_e32 v25, v25
	v_fma_f32 v18, v174, v18, v95
	v_fma_f32 v19, v175, v19, v94
	v_fma_f32 v20, v176, v20, v89
	v_fma_f32 v21, v177, v21, v88
	v_fma_f32 v22, v178, v22, v87
	v_fma_f32 v23, v179, v23, v86
	v_fma_f32 v24, v180, v24, v81
	v_fma_f32 v25, v181, v25, v80
	v_cmp_gt_f32_e64 s[0:1], s62, v18
	v_cmp_gt_f32_e64 s[32:33], s62, v19
	v_cmp_gt_f32_e64 s[60:61], s62, v20
	v_cndmask_b32_e64 v182, 0, 32, s[0:1]
	v_cndmask_b32_e64 v184, 0, v163, s[0:1]
	v_cmp_gt_f32_e64 s[0:1], s62, v21
	v_cndmask_b32_e64 v185, 0, 32, s[32:33]
	v_cndmask_b32_e64 v187, 0, v163, s[32:33]
	v_cmp_gt_f32_e64 s[32:33], s62, v22
	v_cndmask_b32_e64 v188, 0, 32, s[60:61]
	v_cndmask_b32_e64 v190, 0, v163, s[60:61]
	v_cmp_gt_f32_e64 s[60:61], s62, v23
	v_ldexp_f32 v18, v18, v182
	v_cndmask_b32_e64 v191, 0, 32, s[0:1]
	v_cndmask_b32_e64 v193, 0, v163, s[0:1]
	v_cmp_gt_f32_e64 s[0:1], s62, v24
	v_ldexp_f32 v19, v19, v185
	v_cndmask_b32_e64 v194, 0, 32, s[32:33]
	v_cndmask_b32_e64 v196, 0, v163, s[32:33]
	v_cmp_gt_f32_e64 s[32:33], s62, v25
	v_ldexp_f32 v20, v20, v188
	v_cndmask_b32_e64 v197, 0, 32, s[60:61]
	v_cndmask_b32_e64 v199, 0, v163, s[60:61]
	v_log_f32_e32 v18, v18
	v_ldexp_f32 v21, v21, v191
	v_cndmask_b32_e64 v200, 0, 32, s[0:1]
	v_cndmask_b32_e64 v202, 0, v163, s[0:1]
	v_log_f32_e32 v19, v19
	v_ldexp_f32 v22, v22, v194
	v_cndmask_b32_e64 v203, 0, 32, s[32:33]
	v_cndmask_b32_e64 v26, 0, v163, s[32:33]
	v_log_f32_e32 v20, v20
	v_ldexp_f32 v23, v23, v197
	v_mul_f32_e32 v183, 0x3f317217, v18
	v_cmp_lt_f32_e64 s[60:61], |v18|, s66
	v_log_f32_e32 v21, v21
	v_ldexp_f32 v24, v24, v200
	v_mul_f32_e32 v186, 0x3f317217, v19
	v_cmp_lt_f32_e64 s[0:1], |v19|, s66
	v_log_f32_e32 v22, v22
	v_ldexp_f32 v25, v25, v203
	v_mul_f32_e32 v189, 0x3f317217, v20
	v_cmp_lt_f32_e64 s[32:33], |v20|, s66
	v_log_f32_e32 v23, v23
	v_fma_f32 v183, v18, s63, -v183
	v_mul_f32_e32 v192, 0x3f317217, v21
	v_log_f32_e32 v24, v24
	v_fma_f32 v186, v19, s63, -v186
	v_mul_f32_e32 v195, 0x3f317217, v22
	v_log_f32_e32 v25, v25
	v_fma_f32 v189, v20, s63, -v189
	v_mul_f32_e32 v198, 0x3f317217, v23
	v_fmac_f32_e32 v183, 0x3377d1cf, v18
	v_fma_f32 v192, v21, s63, -v192
	v_mul_f32_e32 v201, 0x3f317217, v24
	v_fmac_f32_e32 v186, 0x3377d1cf, v19
	v_fma_f32 v195, v22, s63, -v195
	v_mul_f32_e32 v204, 0x3f317217, v25
	v_fmac_f32_e32 v189, 0x3377d1cf, v20
	v_fma_f32 v198, v23, s63, -v198
	v_fmac_f32_e32 v183, 0x3f317217, v18
	v_fmac_f32_e32 v192, 0x3377d1cf, v21
	v_fma_f32 v201, v24, s63, -v201
	v_fmac_f32_e32 v186, 0x3f317217, v19
	v_fmac_f32_e32 v195, 0x3377d1cf, v22
	v_fma_f32 v204, v25, s63, -v204
	v_fmac_f32_e32 v189, 0x3f317217, v20
	v_fmac_f32_e32 v198, 0x3377d1cf, v23
	v_cndmask_b32_e64 v18, v18, v183, s[60:61]
	v_cmp_lt_f32_e64 s[60:61], |v21|, s66
	v_fmac_f32_e32 v192, 0x3f317217, v21
	v_fmac_f32_e32 v201, 0x3377d1cf, v24
	v_cndmask_b32_e64 v19, v19, v186, s[0:1]
	v_cmp_lt_f32_e64 s[0:1], |v22|, s66
	v_fmac_f32_e32 v195, 0x3f317217, v22
	v_fmac_f32_e32 v204, 0x3377d1cf, v25
	v_cndmask_b32_e64 v20, v20, v189, s[32:33]
	v_cmp_lt_f32_e64 s[32:33], |v23|, s66
	v_fmac_f32_e32 v198, 0x3f317217, v23
	v_sub_f32_e32 v18, v18, v184
	v_cndmask_b32_e64 v21, v21, v192, s[60:61]
	v_cmp_lt_f32_e64 s[60:61], |v24|, s66
	v_fmac_f32_e32 v201, 0x3f317217, v24
	v_sub_f32_e32 v19, v19, v187
	v_cndmask_b32_e64 v22, v22, v195, s[0:1]
	v_cmp_lt_f32_e64 s[0:1], |v25|, s66
	v_fmac_f32_e32 v204, 0x3f317217, v25
	v_sub_f32_e32 v20, v20, v190
	v_cndmask_b32_e64 v23, v23, v198, s[32:33]
	v_sub_f32_e32 v21, v21, v193
	v_cndmask_b32_e64 v24, v24, v201, s[60:61]
	v_sub_f32_e32 v22, v22, v196
	v_cndmask_b32_e64 v25, v25, v204, s[0:1]
	v_sub_f32_e32 v23, v23, v199
	v_sub_f32_e32 v24, v24, v202
	v_sub_f32_e32 v25, v25, v26

;     __device__ __forceinline__ void operator()(const f32x4 (&acc)[2][2][4][2], const Unit& u, int wr, int wc, int fr, int fq) const {
;     ...
;                     } else if (seg == 1) {
; #pragma unroll
;                         for (int i = 0; i < 8; ++i) { const float s = __builtin_amdgcn_rcpf(1.0f + __expf(-v[i])); v[i] = __logf(lb[i] + (1.0f - lb[i]) * s); }
.LBB0_319:
	v_mul_f32_e32 v174, 0xbfb8aa3b, v6
	v_mul_f32_e32 v175, 0xbfb8aa3b, v8
	v_mul_f32_e32 v176, 0xbfb8aa3b, v7
	v_sub_f32_e32 v177, 1.0, v95
	v_sub_f32_e32 v178, 1.0, v89
	v_mul_f32_e32 v179, 0xbfb8aa3b, v9
	v_sub_f32_e32 v180, 1.0, v94
	v_sub_f32_e32 v183, 1.0, v88
	v_mul_f32_e32 v185, 0xbfb8aa3b, v2
	v_sub_f32_e32 v188, 1.0, v87
	v_mul_f32_e32 v190, 0xbfb8aa3b, v3
	v_sub_f32_e32 v192, 1.0, v86
	v_mul_f32_e32 v193, 0xbfb8aa3b, v4
	v_sub_f32_e32 v197, 1.0, v81
	v_mul_f32_e32 v198, 0xbfb8aa3b, v5
	v_sub_f32_e32 v19, 1.0, v80
	v_exp_f32_e32 v174, v174
	v_exp_f32_e32 v175, v175
	v_exp_f32_e32 v176, v176
	v_exp_f32_e32 v179, v179
	v_exp_f32_e32 v185, v185
	v_exp_f32_e32 v190, v190
	v_exp_f32_e32 v193, v193
	v_exp_f32_e32 v198, v198
	v_add_f32_e32 v174, 1.0, v174
	v_add_f32_e32 v175, 1.0, v175
	v_add_f32_e32 v176, 1.0, v176
	v_add_f32_e32 v179, 1.0, v179
	v_add_f32_e32 v185, 1.0, v185
	v_add_f32_e32 v190, 1.0, v190
	v_add_f32_e32 v193, 1.0, v193
	v_add_f32_e32 v198, 1.0, v198
	v_rcp_f32_e32 v174, v174
	v_rcp_f32_e32 v175, v175
	v_rcp_f32_e32 v176, v176
	v_rcp_f32_e32 v179, v179
	v_rcp_f32_e32 v185, v185
	v_rcp_f32_e32 v190, v190
	v_rcp_f32_e32 v193, v193
	v_rcp_f32_e32 v198, v198
	v_fmac_f32_e32 v95, v177, v174
	v_fmac_f32_e32 v89, v178, v175
	v_fmac_f32_e32 v94, v180, v176
	v_fmac_f32_e32 v88, v183, v179
	v_fmac_f32_e32 v87, v188, v185
	v_fmac_f32_e32 v86, v192, v190
	v_fmac_f32_e32 v81, v197, v193
	v_fmac_f32_e32 v80, v19, v198
	v_cmp_gt_f32_e64 s[0:1], s62, v95
	v_cmp_gt_f32_e64 s[8:9], s62, v89
	v_cmp_gt_f32_e64 s[32:33], s62, v94
	v_cmp_gt_f32_e64 s[60:61], s62, v88
	v_cmp_gt_f32_e64 s[6:7], s62, v87
	v_cndmask_b32_e64 v10, 0, 32, s[0:1]
	v_cndmask_b32_e64 v184, 0, v163, s[0:1]
	v_cmp_gt_f32_e64 s[0:1], s62, v86
	v_cndmask_b32_e64 v187, 0, 32, s[8:9]
	v_cndmask_b32_e64 v191, 0, v163, s[8:9]
	v_cmp_gt_f32_e64 s[8:9], s62, v81
	v_cndmask_b32_e64 v182, 0, 32, s[32:33]
	v_cndmask_b32_e64 v186, 0, v163, s[32:33]
	v_cmp_gt_f32_e64 s[32:33], s62, v80
	v_cndmask_b32_e64 v189, 0, 32, s[60:61]
	v_cndmask_b32_e64 v195, 0, v163, s[60:61]
	v_cndmask_b32_e64 v194, 0, 32, s[6:7]
	v_cndmask_b32_e64 v199, 0, v163, s[6:7]
	v_ldexp_f32 v10, v95, v10
	v_cndmask_b32_e64 v196, 0, 32, s[0:1]
	v_cndmask_b32_e64 v201, 0, v163, s[0:1]
	v_ldexp_f32 v187, v89, v187
	v_cndmask_b32_e64 v200, 0, 32, s[8:9]
	v_cndmask_b32_e64 v203, 0, v163, s[8:9]
	v_ldexp_f32 v182, v94, v182
	v_cndmask_b32_e64 v202, 0, 32, s[32:33]
	v_cndmask_b32_e64 v18, 0, v163, s[32:33]
	v_ldexp_f32 v189, v88, v189
	v_ldexp_f32 v194, v87, v194
	v_log_f32_e32 v10, v10
	v_ldexp_f32 v196, v86, v196
	v_log_f32_e32 v187, v187
	v_ldexp_f32 v200, v81, v200
	v_log_f32_e32 v182, v182
	v_ldexp_f32 v202, v80, v202
	v_log_f32_e32 v189, v189
	v_log_f32_e32 v194, v194
	v_mul_f32_e32 v181, 0x3f317217, v10
	v_cmp_lt_f32_e64 s[60:61], |v10|, s66
	v_log_f32_e32 v196, v196
	v_mul_f32_e32 v12, 0x3f317217, v187
	v_cmp_lt_f32_e64 s[6:7], |v187|, s66
	v_log_f32_e32 v200, v200
	v_mul_f32_e32 v11, 0x3f317217, v182
	v_cmp_lt_f32_e64 s[0:1], |v182|, s66
	v_log_f32_e32 v202, v202
	v_mul_f32_e32 v13, 0x3f317217, v189
	v_cmp_lt_f32_e64 s[8:9], |v189|, s66
	v_mul_f32_e32 v14, 0x3f317217, v194
	v_cmp_lt_f32_e64 s[32:33], |v194|, s66
	v_fma_f32 v181, v10, s63, -v181
	v_mul_f32_e32 v15, 0x3f317217, v196
	v_fma_f32 v12, v187, s63, -v12
	v_mul_f32_e32 v16, 0x3f317217, v200
	v_fma_f32 v11, v182, s63, -v11
	v_mul_f32_e32 v17, 0x3f317217, v202
	v_fma_f32 v13, v189, s63, -v13
	v_fma_f32 v14, v194, s63, -v14
	v_fmac_f32_e32 v181, 0x3377d1cf, v10
	v_fma_f32 v15, v196, s63, -v15
	v_fmac_f32_e32 v12, 0x3377d1cf, v187
	v_fma_f32 v16, v200, s63, -v16
	v_fmac_f32_e32 v11, 0x3377d1cf, v182
	v_fma_f32 v17, v202, s63, -v17
	v_fmac_f32_e32 v13, 0x3377d1cf, v189
	v_fmac_f32_e32 v14, 0x3377d1cf, v194
	v_fmac_f32_e32 v181, 0x3f317217, v10
	v_fmac_f32_e32 v15, 0x3377d1cf, v196
	v_fmac_f32_e32 v12, 0x3f317217, v187
	v_fmac_f32_e32 v16, 0x3377d1cf, v200
	v_fmac_f32_e32 v11, 0x3f317217, v182
	v_fmac_f32_e32 v17, 0x3377d1cf, v202
	v_fmac_f32_e32 v13, 0x3f317217, v189
	v_fmac_f32_e32 v14, 0x3f317217, v194
	v_cndmask_b32_e64 v10, v10, v181, s[60:61]
	v_cmp_lt_f32_e64 s[60:61], |v196|, s66
	v_fmac_f32_e32 v15, 0x3f317217, v196
	v_cndmask_b32_e64 v12, v187, v12, s[6:7]
	v_cmp_lt_f32_e64 s[6:7], |v200|, s66
	v_fmac_f32_e32 v16, 0x3f317217, v200
	v_cndmask_b32_e64 v11, v182, v11, s[0:1]
	v_cmp_lt_f32_e64 s[0:1], |v202|, s66
	v_fmac_f32_e32 v17, 0x3f317217, v202
	v_cndmask_b32_e64 v13, v189, v13, s[8:9]
	v_cndmask_b32_e64 v14, v194, v14, s[32:33]
	v_sub_f32_e32 v10, v10, v184
	v_cndmask_b32_e64 v15, v196, v15, s[60:61]
	v_sub_f32_e32 v12, v12, v191
	v_cndmask_b32_e64 v16, v200, v16, s[6:7]
	v_sub_f32_e32 v11, v11, v186
	v_cndmask_b32_e64 v17, v202, v17, s[0:1]
	v_sub_f32_e32 v13, v13, v195
	v_sub_f32_e32 v14, v14, v199
	v_sub_f32_e32 v15, v15, v201
	v_sub_f32_e32 v16, v16, v203
	v_sub_f32_e32 v17, v17, v18

; __device__ __forceinline__ int mix_first_item(const Frame& F) { const int bx = blockIdx.x; return (F.G == 256) ? (bx & 7) * 32 + (bx >> 3) : bx; }
; __device__ __forceinline__ void hgrn_local_ws2(Frame& F, int item) {
;     ...
;     if (part == 0) { const float val = __expf(Bprev); asm volatile("global_store_dword %0, %1, off sc0 sc1" :: "v"(F.DTOT + item * 128 + c), "v"(val) : "memory"); }
; }
; __device__ __forceinline__ void hgrn_publish(Frame& F, unsigned* cnt, int item) {
;     asm volatile("s_waitcnt vmcnt(0)" ::: "memory");
;     __syncthreads();
;     if (F.tid == 0) __hip_atomic_fetch_add(cnt + 64 * (item >> 3), 1u, __ATOMIC_RELAXED, __HIP_MEMORY_SCOPE_AGENT);
; }
; __device__ __forceinline__ void mix_phase_a(Frame& F, bool handoff, unsigned* cnt) {
;     ...
;     for (int it = mix_first_item(F); it < NB * HH * 8; it += F.G) {
;     ...
;         hgrn_local_ws2(F, it);
;     ...
;         hgrn_local(F, it);
;     ...
;         if (handoff) hgrn_publish(F, cnt, it); }
.LBB0_479:
	s_lshl_b32 s90, s61, 7
	v_mul_f32_e32 v2, 0x3fb8aa3b, v115
	s_ashr_i32 s91, s90, 31
	v_exp_f32_e32 v4, v2
	v_lshl_add_u64 v[2:3], s[90:91], 2, v[108:109]
	global_store_dword v[2:3], v4, off sc0 sc1
	s_or_b64 exec, exec, s[88:89]
	s_andn2_b64 vcc, exec, s[68:69]
	s_branch .LBB0_453

; __device__ __forceinline__ void xcd_barrier(const XcdBarrier& b) {
;     asm volatile("s_waitcnt vmcnt(0)" ::: "memory");
;     __syncthreads();
;     if (threadIdx.x == 0) {
;         unsigned* bar = b.bar;
;         __builtin_amdgcn_s_waitcnt(0);
;         unsigned nloc = b.st[0], nx = b.st[1];
;         if (nloc == 0u) { xcd_barrier_complete(bar, b.x, nloc, nx); b.st[0] = nloc; b.st[1] = nx; }
; __device__ __forceinline__ void hgrn_publish(Frame& F, unsigned* cnt, int item) {
;     asm volatile("s_waitcnt vmcnt(0)" ::: "memory");
;     __syncthreads();
;     if (F.tid == 0) __hip_atomic_fetch_add(cnt + 64 * (item >> 3), 1u, __ATOMIC_RELAXED, __HIP_MEMORY_SCOPE_AGENT);
.LBB0_492:
	s_andn2_b64 vcc, exec, s[68:69]
	s_cbranch_vccnz .Lp2_nopub
	s_waitcnt vmcnt(0)
	s_barrier
	s_and_saveexec_b64 s[4:5], s[28:29]
	s_cbranch_execz .Lp2_pubdone
	s_and_b32 s0, s2, 7
	s_lshl_b32 s0, s0, 5
	s_lshr_b32 s1, s2, 3
	s_add_i32 s0, s0, s1
	s_lshr_b32 s0, s0, 3
	s_lshl_b32 s0, s0, 8
	s_add_u32 s0, s30, s0
	s_addc_u32 s1, s31, 0
	v_mov_b32_e32 v1, 0
	v_mov_b32_e32 v2, 1
	global_atomic_add v1, v2, s[0:1]
.Lp2_pubdone:
	s_or_b64 exec, exec, s[4:5]
.Lp2_nopub:
	s_xor_b64 s[0:1], s[68:69], -1
	s_and_b64 s[0:1], s[0:1], s[76:77]
	v_readlane_b32 s62, v238, 3
	s_andn2_b64 vcc, exec, s[0:1]
	v_readlane_b32 s63, v238, 4
	s_cbranch_vccnz .LBB0_546
	s_waitcnt vmcnt(0)
	s_barrier
	s_and_saveexec_b64 s[0:1], s[28:29]
	s_cbranch_execz .LBB0_545
	s_add_i32 s4, 0, 0x20160
	v_mov_b32_e32 v1, s4
	s_waitcnt vmcnt(0) expcnt(0) lgkmcnt(0)
	ds_read_b32 v3, v1
	s_add_i32 s4, 0, 0x20164
	v_mov_b32_e32 v1, s4
	ds_read_b32 v1, v1
	s_waitcnt lgkmcnt(1)
	v_cmp_ne_u32_e32 vcc, 0, v3
	s_cbranch_vccnz .LBB0_509
	v_readlane_b32 s4, v238, 0
	v_readlane_b32 s5, v238, 1
	s_load_dwordx2 s[8:9], s[4:5], 0x4
	s_add_u32 s4, s58, 0x4200
	s_addc_u32 s5, s59, 0
	s_add_u32 s6, s58, 0x4400
	s_addc_u32 s7, s59, 0
	s_waitcnt lgkmcnt(0)
	s_mul_i32 s33, s8, s3
	s_add_u32 s8, s58, 0x4500
	s_mul_i32 s33, s33, s9
	s_addc_u32 s9, s59, 0
	s_add_u32 s10, s58, 0x4600
	s_addc_u32 s11, s59, 0
	s_add_u32 s12, s58, 0x4700
	s_addc_u32 s13, s59, 0
	s_add_u32 s14, s58, 0x4800
	s_addc_u32 s15, s59, 0
	s_add_u32 s16, s58, 0x4900
	s_addc_u32 s17, s59, 0
	s_add_u32 s18, s58, 0x4a00
	s_addc_u32 s19, s59, 0
	s_add_u32 s20, s58, 0x4b00
	s_addc_u32 s21, s59, 0
	s_add_u32 s22, s58, 0x4c00
	s_addc_u32 s23, s59, 0
	s_add_u32 s24, s58, 0x4d00
	s_addc_u32 s25, s59, 0
	s_add_u32 s26, s58, 0x4e00
	s_addc_u32 s27, s59, 0
	s_add_u32 s46, s58, 0x4f00
	s_addc_u32 s47, s59, 0
	s_add_u32 s48, s58, 0x5000
	s_addc_u32 s49, s59, 0
	s_add_u32 s50, s58, 0x5100
	s_addc_u32 s51, s59, 0
	s_add_u32 s78, s58, 0x5200
	s_addc_u32 s79, s59, 0
	s_add_u32 s80, s58, 0x5300
	s_addc_u32 s81, s59, 0
	s_mov_b32 s60, 1
	v_mov_b32_e32 v17, 0
	s_branch .LBB0_497

; #define LAS __attribute__((address_space(3)))
; __device__ __forceinline__ void hgrn_correct(Frame& F, int item) {
;     const int b = item >> 5, h = (item >> 3) & 3, seg = item & 7;
;     const int lane = F.lane, w = F.wave, quad = lane >> 4, l15 = lane & 15;
;     const size_t row0 = (size_t)b * SEQ + seg * 256;
;     LAS bf16* ST = (LAS bf16*)F.lds;
;     v4u qf[2][4];
;     ...
;             const f32x4 og = *(const f32x4*)(F.ogain + 16 * vt + 4 * quad);
.LBB0_546:
	s_add_u32 s0, s58, 0x9800000
	s_addc_u32 s1, s59, 0
	s_cmp_lt_i32 s56, 4
	s_cselect_b64 s[4:5], -1, 0
	s_and_b64 s[4:5], s[4:5], s[76:77]
	s_andn2_b64 vcc, exec, s[4:5]
	s_cbranch_vccnz .LBB0_625
	s_lshl_b32 s4, s2, 5
	s_and_b32 s4, s4, 0xe0
	s_ashr_i32 s5, s2, 3
	s_add_i32 s6, s4, s5
	s_and_b64 s[4:5], s[62:63], exec
	s_cselect_b32 s16, s6, s2
	s_cmpk_gt_i32 s16, 0xff
	s_cbranch_scc1 .LBB0_571
	v_mov_b32_e32 v155, 0
	v_and_b32_e32 v1, 15, v0
	v_lshlrev_b32_e32 v2, 4, v206
	v_mov_b32_e32 v3, v155
	v_lshrrev_b32_e32 v4, 4, v206
	v_lshl_add_u64 v[158:159], s[72:73], 0, v[2:3]
	v_lshl_or_b32 v3, s94, 4, v1
	s_movk_i32 s4, 0x110
	v_lshlrev_b32_e32 v5, 3, v4
	v_and_b32_e32 v154, 48, v206
	v_lshlrev_b32_e32 v2, 2, v4
	v_mul_lo_u32 v3, v3, s4
	v_and_b32_e32 v4, 48, v0
	s_lshl_b32 s6, s94, 5
	s_mov_b32 s9, 0
	v_lshl_add_u64 v[156:157], s[70:71], 0, v[154:155]
	v_lshl_add_u64 v[160:161], s[74:75], 0, v[154:155]
	v_add_u32_e32 v3, 0, v3
	v_add_u32_e32 v4, 0, v4
	v_mul_u32_u24_e32 v6, 0x110, v1
	v_lshl_add_u64 v[164:165], s[42:43], 0, v[154:155]
	v_lshl_add_u64 v[166:167], s[44:45], 0, v[154:155]
	v_lshlrev_b32_e32 v225, 2, v0
	v_cmp_gt_u32_e32 vcc, 0x80, v0
	s_and_saveexec_b64 s[12:13], vcc
	global_load_dword v224, v225, s[44:45]
	s_waitcnt vmcnt(0)
	ds_write_b32 v225, v224 offset:36864
	s_or_b64 exec, exec, s[12:13]
	v_and_b32_e32 v224, 48, v206
	s_waitcnt lgkmcnt(0)
	v_cndmask_b32_e64 v7, 0, 1, s[68:69]
	v_lshlrev_b32_e32 v154, 1, v2
	v_mbcnt_lo_u32_b32 v2, -1, 0
	s_mov_b32 s7, s9
	v_or_b32_e32 v162, s6, v1
	v_mov_b32_e32 v163, v155
	v_cmp_ne_u32_e64 s[4:5], 1, v7
	s_movk_i32 s17, 0x1000
	v_add_u32_e32 v207, v3, v5
	s_movk_i32 s18, 0x1600
	v_add_u32_e32 v208, v4, v6
	v_mbcnt_hi_u32_b32 v209, -1, v2
	v_mov_b32_e32 v210, 0x358637bd
	s_movk_i32 s19, 0x7fff
	v_mov_b32_e32 v211, 1
	s_mov_b32 s20, s16
	s_branch .LBB0_552

; __device__ __forceinline__ unsigned pk2(float lo, float hi) { return f2bf(lo) | (f2bf(hi) << 16); }
; __device__ __forceinline__ void hgrn_correct(Frame& F, int item) {
;     ...
; #pragma unroll
;     for (int tt = 0; tt < 2; ++tt) {
;         const size_t row = row0 + 32 * w + 16 * tt + l15;
;         float ss = 0.f;
; #pragma unroll
;         for (int vt = 0; vt < 8; ++vt) { const f32x4 o = O[vt][tt] + OL[tt][vt]; O[vt][tt] = o; ss += (o[0] * o[0] + o[1] * o[1]) + (o[2] * o[2] + o[3] * o[3]); }
;         ss += __shfl_xor(ss, 16); ss += __shfl_xor(ss, 32);
;         const float rs = __builtin_amdgcn_rsqf(ss * (1.0f / 128.0f) + EPS);
;         bf16* mp = F.MIXED + row * D + h * 128 + 4 * quad;
; #pragma unroll
;         for (int vt = 0; vt < 8; ++vt) {
;             const v2u gw = GW[tt][vt];
;             const f32x4 og = *(const f32x4*)(F.ogain + 16 * vt + 4 * quad);
;             const f32x4 o = O[vt][tt];
;             v2u ow; ow.x = pk2(o[0] * rs * og[0] * bflo(gw.x), o[1] * rs * og[1] * bfhi(gw.x)); ow.y = pk2(o[2] * rs * og[2] * bflo(gw.y), o[3] * rs * og[3] * bfhi(gw.y));
;             *(v2u*)(mp + 16 * vt) = ow;
.LBB0_551:
	s_waitcnt vmcnt(30)
	v_pk_add_f32 v[82:83], v[120:121], v[152:153]
	v_pk_add_f32 v[84:85], v[118:119], v[150:151]
	ds_read_b128 v[118:121], v224 offset:36864
	s_nop 0
	v_and_b32_e32 v71, 64, v209
	v_xor_b32_e32 v70, 16, v209
	v_add_u32_e32 v72, 64, v71
	v_cmp_lt_i32_e32 vcc, v70, v72
	v_pk_add_f32 v[122:123], v[122:123], v[146:147]
	v_pk_add_f32 v[92:93], v[124:125], v[148:149]
	v_cndmask_b32_e32 v70, v209, v70, vcc
	v_mov_b32_e32 v74, v85
	v_mov_b32_e32 v75, v123
	v_lshlrev_b32_e32 v73, 2, v70
	v_mov_b32_e32 v70, v84
	v_mov_b32_e32 v71, v122
	v_pk_mul_f32 v[74:75], v[74:75], v[74:75]
	v_mov_b32_e32 v76, v83
	v_mov_b32_e32 v77, v93
	v_pk_fma_f32 v[70:71], v[70:71], v[70:71], v[74:75]
	v_mov_b32_e32 v74, v82
	v_mov_b32_e32 v75, v92
	v_pk_mul_f32 v[76:77], v[76:77], v[76:77]
	s_waitcnt vmcnt(30)
	v_pk_add_f32 v[116:117], v[116:117], v[128:129]
	v_pk_fma_f32 v[74:75], v[74:75], v[74:75], v[76:77]
	v_pk_add_f32 v[114:115], v[114:115], v[126:127]
	v_pk_add_f32 v[70:71], v[70:71], v[74:75]
	v_pk_mul_f32 v[74:75], v[116:117], v[116:117]
	v_pk_add_f32 v[70:71], v[70:71], v[70:71] op_sel_hi:[0,1]
	v_pk_mul_f32 v[76:77], v[114:115], v[114:115]
	s_waitcnt vmcnt(29)
	v_pk_add_f32 v[110:111], v[110:111], v[130:131]
	v_pk_mov_b32 v[78:79], v[76:77], v[74:75] op_sel:[1,0]
	v_mov_b32_e32 v77, v75
	v_pk_add_f32 v[112:113], v[112:113], v[132:133]
	v_mul_f32_e32 v70, v110, v110
	v_pk_add_f32 v[74:75], v[78:79], v[76:77]
	v_pk_fma_f32 v[76:77], v[110:111], v[110:111], v[70:71] op_sel_hi:[1,1,0]
	v_mul_f32_e32 v70, v112, v112
	v_pk_add_f32 v[74:75], v[74:75], v[74:75] op_sel_hi:[0,1]
	v_pk_fma_f32 v[78:79], v[112:113], v[112:113], v[70:71] op_sel_hi:[1,1,0]
	s_waitcnt vmcnt(24)
	v_pk_add_f32 v[86:87], v[108:109], v[144:145]
	v_pk_add_f32 v[88:89], v[106:107], v[142:143]
	v_mul_f32_e32 v74, v86, v86
	v_mul_f32_e32 v76, v88, v88
	v_mul_f32_e32 v78, v89, v89
	v_mul_f32_e32 v70, v87, v87
	v_pk_add_f32 v[76:77], v[76:77], v[78:79]
	v_pk_add_f32 v[70:71], v[74:75], v[70:71]
	s_waitcnt vmcnt(23)
	v_pk_add_f32 v[78:79], v[104:105], v[136:137]
	v_pk_add_f32 v[70:71], v[76:77], v[70:71]
	v_pk_add_f32 v[80:81], v[102:103], v[134:135]
	v_pk_add_f32 v[90:91], v[70:71], v[70:71] op_sel_hi:[0,1]
	v_pk_mul_f32 v[70:71], v[78:79], v[78:79]
	v_pk_mul_f32 v[74:75], v[80:81], v[80:81]
	s_waitcnt vmcnt(21)
	v_pk_add_f32 v[68:69], v[96:97], v[68:69]
	v_pk_mov_b32 v[76:77], v[74:75], v[70:71] op_sel:[1,0]
	v_mov_b32_e32 v75, v71
	v_pk_add_f32 v[70:71], v[76:77], v[74:75]
	v_pk_add_f32 v[76:77], v[98:99], v[138:139]
	v_pk_add_f32 v[102:103], v[70:71], v[70:71] op_sel_hi:[0,1]
	v_pk_add_f32 v[74:75], v[100:101], v[140:141]
	v_mul_f32_e32 v70, v76, v76
	v_pk_fma_f32 v[98:99], v[76:77], v[76:77], v[70:71] op_sel_hi:[1,1,0]
	v_mul_f32_e32 v70, v74, v74
	v_pk_fma_f32 v[100:101], v[74:75], v[74:75], v[70:71] op_sel_hi:[1,1,0]
	v_pk_add_f32 v[70:71], v[94:95], v[66:67]
	v_mul_f32_e32 v102, v68, v68
	v_mul_f32_e32 v98, v70, v70
	v_mul_f32_e32 v100, v71, v71
	v_mul_f32_e32 v90, v69, v69
	v_pk_add_f32 v[66:67], v[98:99], v[100:101]
	v_pk_add_f32 v[90:91], v[102:103], v[90:91]
	v_mov_b32_e32 v94, v122
	v_pk_add_f32 v[66:67], v[66:67], v[90:91]
	v_xor_b32_e32 v90, 32, v209
	v_add_f32_e32 v66, v66, v67
	ds_bpermute_b32 v67, v73, v66
	v_cmp_lt_i32_e32 vcc, v90, v72
	v_mov_b32_e32 v95, v92
	v_mov_b32_e32 v92, v123
	v_cndmask_b32_e32 v72, v209, v90, vcc
	v_lshlrev_b32_e32 v90, 2, v72
	s_waitcnt lgkmcnt(0)
	v_add_f32_e32 v66, v66, v67
	ds_bpermute_b32 v67, v90, v66
	s_waitcnt vmcnt(0) lgkmcnt(0)
	v_mov_b32_e32 v96, v118
	v_mov_b32_e32 v97, v120
	v_mov_b32_e32 v120, v119
	v_mov_b32_e32 v100, v84
	s_waitcnt lgkmcnt(0)
	v_add_f32_e32 v66, v66, v67
	v_fmamk_f32 v66, v66, 0x3c000000, v210
	v_rsq_f32_e32 v72, v66
	v_lshl_add_u64 v[66:67], s[0:1], 0, v[204:205]
	v_lshl_add_u64 v[66:67], v[66:67], 0, v[182:183]
	v_lshl_add_u64 v[66:67], v[66:67], 0, v[154:155]
	v_pk_mul_f32 v[94:95], v[94:95], v[72:73] op_sel_hi:[1,0]
	v_pk_mul_f32 v[92:93], v[92:93], v[72:73] op_sel_hi:[1,0]
	v_pk_mul_f32 v[94:95], v[96:97], v[94:95]
	v_lshlrev_b32_e32 v97, 16, v203
	v_lshlrev_b32_e32 v96, 16, v202
	v_pk_mul_f32 v[94:95], v[94:95], v[96:97]
	v_pk_mul_f32 v[92:93], v[120:121], v[92:93]
	v_and_b32_e32 v97, 0xffff0000, v203
	v_and_b32_e32 v96, 0xffff0000, v202
	v_pk_mul_f32 v[92:93], v[92:93], v[96:97]
	v_and_b32_sdwa v91, v95, v211 dst_sel:DWORD dst_unused:UNUSED_PAD src0_sel:WORD_1 src1_sel:DWORD
	v_and_b32_sdwa v96, v94, v211 dst_sel:DWORD dst_unused:UNUSED_PAD src0_sel:WORD_1 src1_sel:DWORD
	v_add3_u32 v94, v94, v96, s19
	v_add3_u32 v91, v95, v91, s19
	v_and_b32_sdwa v95, v93, v211 dst_sel:DWORD dst_unused:UNUSED_PAD src0_sel:WORD_1 src1_sel:DWORD
	v_and_b32_sdwa v96, v92, v211 dst_sel:DWORD dst_unused:UNUSED_PAD src0_sel:WORD_1 src1_sel:DWORD
	v_add3_u32 v93, v93, v95, s19
	v_add3_u32 v92, v92, v96, s19
	v_and_b32_e32 v93, 0xffff0000, v93
	v_and_b32_e32 v92, 0xffff0000, v92
	v_or_b32_sdwa v93, v93, v91 dst_sel:DWORD dst_unused:UNUSED_PAD src0_sel:DWORD src1_sel:WORD_1
	v_or_b32_sdwa v92, v92, v94 dst_sel:DWORD dst_unused:UNUSED_PAD src0_sel:DWORD src1_sel:WORD_1
	global_store_dwordx2 v[66:67], v[92:93], off
	ds_read_b128 v[92:95], v224 offset:36928
	v_mov_b32_e32 v101, v82
	v_mov_b32_e32 v82, v85
	v_pk_mul_f32 v[84:85], v[100:101], v[72:73] op_sel_hi:[1,0]
	v_pk_mul_f32 v[82:83], v[82:83], v[72:73] op_sel_hi:[1,0]
	v_and_b32_e32 v99, 0xffff0000, v201
	v_and_b32_e32 v98, 0xffff0000, v200
	v_lshlrev_b32_e32 v97, 16, v201
	v_lshlrev_b32_e32 v96, 16, v200
	v_pk_add_f32 v[58:59], v[42:43], v[58:59]
	v_pk_add_f32 v[42:43], v[36:37], v[64:65]
	v_pk_add_f32 v[36:37], v[22:23], v[54:55]
	v_mov_b32_e32 v23, v68
	v_mov_b32_e32 v68, v71
	v_pk_add_f32 v[60:61], v[44:45], v[60:61]
	v_pk_add_f32 v[44:45], v[34:35], v[62:63]
	v_pk_add_f32 v[34:35], v[24:25], v[56:57]
	v_mov_b32_e32 v22, v70
	v_pk_mul_f32 v[24:25], v[68:69], v[72:73] op_sel_hi:[1,0]
	v_pk_mul_f32 v[22:23], v[22:23], v[72:73] op_sel_hi:[1,0]
	s_add_i32 s16, s16, s3
	s_add_i32 s20, s20, s3
	s_cmpk_lt_i32 s16, 0x100
	s_waitcnt lgkmcnt(0)
; __device__ __forceinline__ unsigned pk2(float lo, float hi) { return f2bf(lo) | (f2bf(hi) << 16); }
; __device__ __forceinline__ void hgrn_correct(Frame& F, int item) {
;     ...
; #pragma unroll
;         for (int vt = 0; vt < 8; ++vt) {
;             const v2u gw = GW[tt][vt];
;             const f32x4 og = *(const f32x4*)(F.ogain + 16 * vt + 4 * quad);
;             const f32x4 o = O[vt][tt];
;             v2u ow; ow.x = pk2(o[0] * rs * og[0] * bflo(gw.x), o[1] * rs * og[1] * bfhi(gw.x)); ow.y = pk2(o[2] * rs * og[2] * bflo(gw.y), o[3] * rs * og[3] * bfhi(gw.y));
;             *(v2u*)(mp + 16 * vt) = ow;
	v_mov_b32_e32 v101, v94
	v_mov_b32_e32 v94, v93
	v_mov_b32_e32 v100, v92
	v_pk_mul_f32 v[82:83], v[94:95], v[82:83]
	v_pk_mul_f32 v[84:85], v[100:101], v[84:85]
	v_pk_mul_f32 v[82:83], v[82:83], v[98:99]
	v_pk_mul_f32 v[84:85], v[84:85], v[96:97]
	v_and_b32_sdwa v93, v83, v211 dst_sel:DWORD dst_unused:UNUSED_PAD src0_sel:WORD_1 src1_sel:DWORD
	v_and_b32_sdwa v94, v82, v211 dst_sel:DWORD dst_unused:UNUSED_PAD src0_sel:WORD_1 src1_sel:DWORD
	v_and_b32_sdwa v91, v85, v211 dst_sel:DWORD dst_unused:UNUSED_PAD src0_sel:WORD_1 src1_sel:DWORD
	v_and_b32_sdwa v92, v84, v211 dst_sel:DWORD dst_unused:UNUSED_PAD src0_sel:WORD_1 src1_sel:DWORD
	v_add3_u32 v83, v83, v93, s19
	v_add3_u32 v82, v82, v94, s19
	v_add3_u32 v84, v84, v92, s19
	v_add3_u32 v85, v85, v91, s19
	v_and_b32_e32 v83, 0xffff0000, v83
	v_and_b32_e32 v82, 0xffff0000, v82
	v_or_b32_sdwa v83, v83, v85 dst_sel:DWORD dst_unused:UNUSED_PAD src0_sel:DWORD src1_sel:WORD_1
	v_or_b32_sdwa v82, v82, v84 dst_sel:DWORD dst_unused:UNUSED_PAD src0_sel:DWORD src1_sel:WORD_1
	global_store_dwordx2 v[66:67], v[82:83], off offset:32
	ds_read_b128 v[82:85], v224 offset:36992
	v_mov_b32_e32 v97, v116
	v_mov_b32_e32 v116, v115
	v_mov_b32_e32 v96, v114
	v_pk_mul_f32 v[98:99], v[116:117], v[72:73] op_sel_hi:[1,0]
	v_and_b32_e32 v95, 0xffff0000, v199
	v_and_b32_e32 v94, 0xffff0000, v198
	v_pk_mul_f32 v[96:97], v[96:97], v[72:73] op_sel_hi:[1,0]
	v_lshlrev_b32_e32 v93, 16, v199
	v_lshlrev_b32_e32 v92, 16, v198
	s_waitcnt lgkmcnt(0)
	v_mov_b32_e32 v101, v84
	v_mov_b32_e32 v84, v83
	v_mov_b32_e32 v100, v82
	v_pk_mul_f32 v[84:85], v[84:85], v[98:99]
	v_pk_mul_f32 v[82:83], v[100:101], v[96:97]
	v_pk_mul_f32 v[84:85], v[84:85], v[94:95]
	v_pk_mul_f32 v[82:83], v[82:83], v[92:93]
	v_and_b32_sdwa v93, v85, v211 dst_sel:DWORD dst_unused:UNUSED_PAD src0_sel:WORD_1 src1_sel:DWORD
	v_and_b32_sdwa v94, v84, v211 dst_sel:DWORD dst_unused:UNUSED_PAD src0_sel:WORD_1 src1_sel:DWORD
	v_and_b32_sdwa v91, v83, v211 dst_sel:DWORD dst_unused:UNUSED_PAD src0_sel:WORD_1 src1_sel:DWORD
	v_and_b32_sdwa v92, v82, v211 dst_sel:DWORD dst_unused:UNUSED_PAD src0_sel:WORD_1 src1_sel:DWORD
	v_add3_u32 v85, v85, v93, s19
	v_add3_u32 v84, v84, v94, s19
	v_add3_u32 v82, v82, v92, s19
	v_add3_u32 v83, v83, v91, s19
	v_and_b32_e32 v85, 0xffff0000, v85
	v_and_b32_e32 v84, 0xffff0000, v84
	v_or_b32_sdwa v83, v85, v83 dst_sel:DWORD dst_unused:UNUSED_PAD src0_sel:DWORD src1_sel:WORD_1
	v_or_b32_sdwa v82, v84, v82 dst_sel:DWORD dst_unused:UNUSED_PAD src0_sel:DWORD src1_sel:WORD_1
	global_store_dwordx2 v[66:67], v[82:83], off offset:64
	ds_read_b128 v[82:85], v224 offset:37056
	v_mov_b32_e32 v97, v112
	v_mov_b32_e32 v112, v111
	v_mov_b32_e32 v96, v110
	v_pk_mul_f32 v[98:99], v[112:113], v[72:73] op_sel_hi:[1,0]
	v_and_b32_e32 v95, 0xffff0000, v197
	v_and_b32_e32 v94, 0xffff0000, v196
	v_pk_mul_f32 v[96:97], v[96:97], v[72:73] op_sel_hi:[1,0]
	v_lshlrev_b32_e32 v93, 16, v197
	v_lshlrev_b32_e32 v92, 16, v196
	s_waitcnt lgkmcnt(0)
	v_mov_b32_e32 v101, v84
	v_mov_b32_e32 v84, v83
	v_mov_b32_e32 v100, v82
	v_pk_mul_f32 v[84:85], v[84:85], v[98:99]
	v_pk_mul_f32 v[82:83], v[100:101], v[96:97]
	v_pk_mul_f32 v[84:85], v[84:85], v[94:95]
	v_pk_mul_f32 v[82:83], v[82:83], v[92:93]
	v_and_b32_sdwa v93, v85, v211 dst_sel:DWORD dst_unused:UNUSED_PAD src0_sel:WORD_1 src1_sel:DWORD
	v_and_b32_sdwa v94, v84, v211 dst_sel:DWORD dst_unused:UNUSED_PAD src0_sel:WORD_1 src1_sel:DWORD
	v_and_b32_sdwa v91, v83, v211 dst_sel:DWORD dst_unused:UNUSED_PAD src0_sel:WORD_1 src1_sel:DWORD
	v_and_b32_sdwa v92, v82, v211 dst_sel:DWORD dst_unused:UNUSED_PAD src0_sel:WORD_1 src1_sel:DWORD
	v_add3_u32 v85, v85, v93, s19
	v_add3_u32 v84, v84, v94, s19
	v_add3_u32 v82, v82, v92, s19
	v_add3_u32 v83, v83, v91, s19
	v_and_b32_e32 v85, 0xffff0000, v85
	v_and_b32_e32 v84, 0xffff0000, v84
	v_or_b32_sdwa v83, v85, v83 dst_sel:DWORD dst_unused:UNUSED_PAD src0_sel:DWORD src1_sel:WORD_1
	v_or_b32_sdwa v82, v84, v82 dst_sel:DWORD dst_unused:UNUSED_PAD src0_sel:DWORD src1_sel:WORD_1
	global_store_dwordx2 v[66:67], v[82:83], off offset:96
	ds_read_b128 v[82:85], v224 offset:37120
	v_mov_b32_e32 v96, v88
	v_mov_b32_e32 v97, v86
	v_mov_b32_e32 v86, v89
	v_pk_mul_f32 v[88:89], v[96:97], v[72:73] op_sel_hi:[1,0]
	v_pk_mul_f32 v[86:87], v[86:87], v[72:73] op_sel_hi:[1,0]
	v_and_b32_e32 v95, 0xffff0000, v195
	v_and_b32_e32 v94, 0xffff0000, v194
	v_lshlrev_b32_e32 v93, 16, v195
	v_lshlrev_b32_e32 v92, 16, v194
	s_waitcnt lgkmcnt(0)
	v_mov_b32_e32 v97, v84
	v_mov_b32_e32 v84, v83
	v_mov_b32_e32 v96, v82
	v_pk_mul_f32 v[84:85], v[84:85], v[86:87]
	v_pk_mul_f32 v[82:83], v[96:97], v[88:89]
	v_pk_mul_f32 v[84:85], v[84:85], v[94:95]
	v_pk_mul_f32 v[82:83], v[82:83], v[92:93]
	v_and_b32_sdwa v88, v85, v211 dst_sel:DWORD dst_unused:UNUSED_PAD src0_sel:WORD_1 src1_sel:DWORD
	v_and_b32_sdwa v89, v84, v211 dst_sel:DWORD dst_unused:UNUSED_PAD src0_sel:WORD_1 src1_sel:DWORD
	v_and_b32_sdwa v86, v83, v211 dst_sel:DWORD dst_unused:UNUSED_PAD src0_sel:WORD_1 src1_sel:DWORD
	v_and_b32_sdwa v87, v82, v211 dst_sel:DWORD dst_unused:UNUSED_PAD src0_sel:WORD_1 src1_sel:DWORD
	v_add3_u32 v85, v85, v88, s19
	v_add3_u32 v84, v84, v89, s19
	v_add3_u32 v82, v82, v87, s19
	v_add3_u32 v83, v83, v86, s19
	v_and_b32_e32 v85, 0xffff0000, v85
	v_and_b32_e32 v84, 0xffff0000, v84
	v_or_b32_sdwa v83, v85, v83 dst_sel:DWORD dst_unused:UNUSED_PAD src0_sel:DWORD src1_sel:WORD_1
	v_or_b32_sdwa v82, v84, v82 dst_sel:DWORD dst_unused:UNUSED_PAD src0_sel:DWORD src1_sel:WORD_1
	global_store_dwordx2 v[66:67], v[82:83], off offset:128
	ds_read_b128 v[82:85], v224 offset:37184
	v_mov_b32_e32 v92, v80
	v_mov_b32_e32 v93, v78
	v_mov_b32_e32 v78, v81
	v_pk_mul_f32 v[80:81], v[92:93], v[72:73] op_sel_hi:[1,0]
	v_pk_mul_f32 v[78:79], v[78:79], v[72:73] op_sel_hi:[1,0]
	v_and_b32_e32 v89, 0xffff0000, v193
	v_and_b32_e32 v88, 0xffff0000, v192
	v_lshlrev_b32_e32 v87, 16, v193
	v_lshlrev_b32_e32 v86, 16, v192
	s_waitcnt lgkmcnt(0)
; __device__ __forceinline__ unsigned pk2(float lo, float hi) { return f2bf(lo) | (f2bf(hi) << 16); }
; __device__ __forceinline__ void hgrn_correct(Frame& F, int item) {
;     ...
;     for (int tt = 0; tt < 2; ++tt) {
;         const size_t row = row0 + 32 * w + 16 * tt + l15;
;         float ss = 0.f;
; #pragma unroll
;         for (int vt = 0; vt < 8; ++vt) { const f32x4 o = O[vt][tt] + OL[tt][vt]; O[vt][tt] = o; ss += (o[0] * o[0] + o[1] * o[1]) + (o[2] * o[2] + o[3] * o[3]); }
;         ss += __shfl_xor(ss, 16); ss += __shfl_xor(ss, 32);
;     ...
; #pragma unroll
;         for (int vt = 0; vt < 8; ++vt) {
;             const v2u gw = GW[tt][vt];
;             const f32x4 og = *(const f32x4*)(F.ogain + 16 * vt + 4 * quad);
;             const f32x4 o = O[vt][tt];
;             v2u ow; ow.x = pk2(o[0] * rs * og[0] * bflo(gw.x), o[1] * rs * og[1] * bfhi(gw.x)); ow.y = pk2(o[2] * rs * og[2] * bflo(gw.y), o[3] * rs * og[3] * bfhi(gw.y));
;             *(v2u*)(mp + 16 * vt) = ow;
	v_mov_b32_e32 v93, v84
	v_mov_b32_e32 v84, v83
	v_mov_b32_e32 v92, v82
	v_pk_mul_f32 v[78:79], v[84:85], v[78:79]
	v_pk_mul_f32 v[80:81], v[92:93], v[80:81]
	v_pk_mul_f32 v[78:79], v[78:79], v[88:89]
	v_pk_mul_f32 v[80:81], v[80:81], v[86:87]
	v_and_b32_sdwa v84, v79, v211 dst_sel:DWORD dst_unused:UNUSED_PAD src0_sel:WORD_1 src1_sel:DWORD
	v_and_b32_sdwa v85, v78, v211 dst_sel:DWORD dst_unused:UNUSED_PAD src0_sel:WORD_1 src1_sel:DWORD
	v_and_b32_sdwa v82, v81, v211 dst_sel:DWORD dst_unused:UNUSED_PAD src0_sel:WORD_1 src1_sel:DWORD
	v_and_b32_sdwa v83, v80, v211 dst_sel:DWORD dst_unused:UNUSED_PAD src0_sel:WORD_1 src1_sel:DWORD
	v_add3_u32 v79, v79, v84, s19
	v_add3_u32 v78, v78, v85, s19
	v_add3_u32 v80, v80, v83, s19
	v_add3_u32 v81, v81, v82, s19
	v_and_b32_e32 v79, 0xffff0000, v79
	v_and_b32_e32 v78, 0xffff0000, v78
	v_or_b32_sdwa v79, v79, v81 dst_sel:DWORD dst_unused:UNUSED_PAD src0_sel:DWORD src1_sel:WORD_1
	v_or_b32_sdwa v78, v78, v80 dst_sel:DWORD dst_unused:UNUSED_PAD src0_sel:DWORD src1_sel:WORD_1
	global_store_dwordx2 v[66:67], v[78:79], off offset:160
	ds_read_b128 v[78:81], v224 offset:37248
	v_mov_b32_e32 v86, v76
	v_mov_b32_e32 v87, v74
	v_mov_b32_e32 v74, v77
	v_pk_mul_f32 v[76:77], v[86:87], v[72:73] op_sel_hi:[1,0]
	v_pk_mul_f32 v[74:75], v[74:75], v[72:73] op_sel_hi:[1,0]
	v_and_b32_e32 v85, 0xffff0000, v191
	v_and_b32_e32 v84, 0xffff0000, v190
	v_lshlrev_b32_e32 v83, 16, v191
	v_lshlrev_b32_e32 v82, 16, v190
	s_waitcnt lgkmcnt(0)
	v_mov_b32_e32 v87, v80
	v_mov_b32_e32 v80, v79
	v_mov_b32_e32 v86, v78
	v_pk_mul_f32 v[74:75], v[74:75], v[80:81]
	v_pk_mul_f32 v[76:77], v[76:77], v[86:87]
	v_pk_mul_f32 v[74:75], v[74:75], v[84:85]
	v_pk_mul_f32 v[76:77], v[76:77], v[82:83]
	v_and_b32_sdwa v80, v75, v211 dst_sel:DWORD dst_unused:UNUSED_PAD src0_sel:WORD_1 src1_sel:DWORD
	v_and_b32_sdwa v81, v74, v211 dst_sel:DWORD dst_unused:UNUSED_PAD src0_sel:WORD_1 src1_sel:DWORD
	v_and_b32_sdwa v78, v77, v211 dst_sel:DWORD dst_unused:UNUSED_PAD src0_sel:WORD_1 src1_sel:DWORD
	v_and_b32_sdwa v79, v76, v211 dst_sel:DWORD dst_unused:UNUSED_PAD src0_sel:WORD_1 src1_sel:DWORD
	v_add3_u32 v75, v75, v80, s19
	v_add3_u32 v74, v74, v81, s19
	v_add3_u32 v76, v76, v79, s19
	v_add3_u32 v77, v77, v78, s19
	v_and_b32_e32 v75, 0xffff0000, v75
	v_and_b32_e32 v74, 0xffff0000, v74
	v_or_b32_sdwa v75, v75, v77 dst_sel:DWORD dst_unused:UNUSED_PAD src0_sel:DWORD src1_sel:WORD_1
	v_or_b32_sdwa v74, v74, v76 dst_sel:DWORD dst_unused:UNUSED_PAD src0_sel:DWORD src1_sel:WORD_1
	global_store_dwordx2 v[66:67], v[74:75], off offset:192
	ds_read_b128 v[74:77], v224 offset:37312
	v_and_b32_e32 v81, 0xffff0000, v189
	v_and_b32_e32 v80, 0xffff0000, v188
	v_lshlrev_b32_e32 v79, 16, v189
	v_lshlrev_b32_e32 v78, 16, v188
	s_waitcnt lgkmcnt(0)
	v_mov_b32_e32 v55, v76
	v_mov_b32_e32 v76, v75
	v_mov_b32_e32 v54, v74
	v_pk_mul_f32 v[24:25], v[24:25], v[76:77]
	v_pk_mul_f32 v[22:23], v[22:23], v[54:55]
	v_pk_mul_f32 v[24:25], v[24:25], v[80:81]
	v_pk_mul_f32 v[22:23], v[22:23], v[78:79]
	v_and_b32_sdwa v56, v25, v211 dst_sel:DWORD dst_unused:UNUSED_PAD src0_sel:WORD_1 src1_sel:DWORD
	v_and_b32_sdwa v57, v24, v211 dst_sel:DWORD dst_unused:UNUSED_PAD src0_sel:WORD_1 src1_sel:DWORD
	v_and_b32_sdwa v54, v23, v211 dst_sel:DWORD dst_unused:UNUSED_PAD src0_sel:WORD_1 src1_sel:DWORD
	v_and_b32_sdwa v55, v22, v211 dst_sel:DWORD dst_unused:UNUSED_PAD src0_sel:WORD_1 src1_sel:DWORD
	v_add3_u32 v25, v25, v56, s19
	v_add3_u32 v24, v24, v57, s19
	v_add3_u32 v22, v22, v55, s19
	v_add3_u32 v23, v23, v54, s19
	v_and_b32_e32 v25, 0xffff0000, v25
	v_and_b32_e32 v24, 0xffff0000, v24
	v_or_b32_sdwa v23, v25, v23 dst_sel:DWORD dst_unused:UNUSED_PAD src0_sel:DWORD src1_sel:WORD_1
	v_or_b32_sdwa v22, v24, v22 dst_sel:DWORD dst_unused:UNUSED_PAD src0_sel:DWORD src1_sel:WORD_1
	global_store_dwordx2 v[66:67], v[22:23], off offset:224
	ds_read_b128 v[62:65], v224 offset:36864
	v_pk_add_f32 v[56:57], v[2:3], v[26:27]
	v_pk_add_f32 v[26:27], v[8:9], v[32:33]
	v_pk_add_f32 v[22:23], v[12:13], v[40:41]
	v_pk_add_f32 v[8:9], v[16:17], v[48:49]
	v_mov_b32_e32 v12, v45
	v_mov_b32_e32 v13, v59
	v_mov_b32_e32 v16, v43
	v_mov_b32_e32 v17, v61
	v_pk_add_f32 v[54:55], v[4:5], v[28:29]
	v_pk_add_f32 v[28:29], v[6:7], v[30:31]
	v_pk_add_f32 v[24:25], v[10:11], v[38:39]
	v_pk_add_f32 v[10:11], v[14:15], v[46:47]
	v_pk_add_f32 v[2:3], v[20:21], v[52:53]
	v_pk_add_f32 v[4:5], v[18:19], v[50:51]
	v_mov_b32_e32 v6, v44
	v_mov_b32_e32 v7, v58
	v_mov_b32_e32 v14, v42
	v_mov_b32_e32 v15, v60
	v_pk_mul_f32 v[18:19], v[34:35], v[34:35]
	v_pk_mul_f32 v[20:21], v[36:37], v[36:37]
	v_pk_mul_f32 v[12:13], v[12:13], v[12:13]
	v_pk_mul_f32 v[16:17], v[16:17], v[16:17]
	v_pk_mov_b32 v[50:51], v[20:21], v[18:19] op_sel:[1,0]
	v_mov_b32_e32 v21, v19
	v_pk_fma_f32 v[6:7], v[6:7], v[6:7], v[12:13]
	v_pk_fma_f32 v[12:13], v[14:15], v[14:15], v[16:17]
	v_mul_f32_e32 v30, v56, v56
	v_mul_f32_e32 v32, v54, v54
	v_pk_add_f32 v[14:15], v[50:51], v[20:21]
	v_pk_add_f32 v[6:7], v[6:7], v[12:13]
	v_pk_fma_f32 v[18:19], v[56:57], v[56:57], v[30:31] op_sel_hi:[1,1,0]
	v_pk_fma_f32 v[30:31], v[54:55], v[54:55], v[32:33] op_sel_hi:[1,1,0]
	v_pk_add_f32 v[12:13], v[14:15], v[14:15] op_sel_hi:[0,1]
	v_pk_add_f32 v[6:7], v[6:7], v[6:7] op_sel_hi:[0,1]
	v_pk_mul_f32 v[38:39], v[22:23], v[22:23]
	v_pk_mul_f32 v[40:41], v[24:25], v[24:25]
	v_mul_f32_e32 v18, v28, v28
	v_mul_f32_e32 v30, v29, v29
	v_mul_f32_e32 v12, v26, v26
	v_mul_f32_e32 v6, v27, v27
	v_pk_mov_b32 v[32:33], v[40:41], v[38:39] op_sel:[1,0]
	v_mov_b32_e32 v41, v39
	v_pk_add_f32 v[14:15], v[18:19], v[30:31]
	v_pk_add_f32 v[6:7], v[12:13], v[6:7]
	v_mul_f32_e32 v46, v10, v10
	v_mul_f32_e32 v48, v8, v8
	v_pk_add_f32 v[16:17], v[32:33], v[40:41]
	v_pk_add_f32 v[6:7], v[14:15], v[6:7]
	v_pk_fma_f32 v[38:39], v[10:11], v[10:11], v[46:47] op_sel_hi:[1,1,0]
	v_pk_fma_f32 v[46:47], v[8:9], v[8:9], v[48:49] op_sel_hi:[1,1,0]
	v_pk_add_f32 v[16:17], v[16:17], v[16:17] op_sel_hi:[0,1]
	v_pk_add_f32 v[6:7], v[6:7], v[6:7] op_sel_hi:[0,1]
	v_mul_f32_e32 v38, v4, v4
	v_mul_f32_e32 v46, v5, v5
	v_mul_f32_e32 v16, v2, v2
	v_mul_f32_e32 v6, v3, v3
	v_pk_add_f32 v[18:19], v[38:39], v[46:47]
	v_pk_add_f32 v[6:7], v[16:17], v[6:7]
	v_lshlrev_b32_e32 v15, 16, v185
	v_pk_add_f32 v[6:7], v[18:19], v[6:7]
	v_mov_b32_e32 v18, v58
	v_add_f32_e32 v12, v6, v7
	ds_bpermute_b32 v13, v73, v12
	v_mov_b32_e32 v19, v60
	v_mov_b32_e32 v60, v59
	v_lshlrev_b32_e32 v14, 16, v184
	v_and_b32_e32 v17, 0xffff0000, v185
	s_waitcnt lgkmcnt(0)
; __device__ __forceinline__ unsigned pk2(float lo, float hi) { return f2bf(lo) | (f2bf(hi) << 16); }
; __device__ __forceinline__ void hgrn_correct(Frame& F, int item) {
;     ...
;         ss += __shfl_xor(ss, 16); ss += __shfl_xor(ss, 32);
;         const float rs = __builtin_amdgcn_rsqf(ss * (1.0f / 128.0f) + EPS);
;         bf16* mp = F.MIXED + row * D + h * 128 + 4 * quad;
; #pragma unroll
;         for (int vt = 0; vt < 8; ++vt) {
;             const v2u gw = GW[tt][vt];
;             const f32x4 og = *(const f32x4*)(F.ogain + 16 * vt + 4 * quad);
;             const f32x4 o = O[vt][tt];
;             v2u ow; ow.x = pk2(o[0] * rs * og[0] * bflo(gw.x), o[1] * rs * og[1] * bfhi(gw.x)); ow.y = pk2(o[2] * rs * og[2] * bflo(gw.y), o[3] * rs * og[3] * bfhi(gw.y));
;             *(v2u*)(mp + 16 * vt) = ow;
	v_add_f32_e32 v12, v12, v13
	ds_bpermute_b32 v13, v90, v12
	v_and_b32_e32 v16, 0xffff0000, v184
	v_lshl_add_u64 v[6:7], s[0:1], 0, v[186:187]
	v_lshl_add_u64 v[6:7], v[6:7], 0, v[182:183]
	v_lshl_add_u64 v[6:7], v[6:7], 0, v[154:155]
	s_waitcnt lgkmcnt(0)
	v_add_f32_e32 v12, v12, v13
	v_fmamk_f32 v12, v12, 0x3c000000, v210
	v_rsq_f32_e32 v12, v12
	s_waitcnt lgkmcnt(0)
	v_mov_b32_e32 v30, v62
	v_pk_mul_f32 v[18:19], v[18:19], v[12:13] op_sel_hi:[1,0]
	v_pk_mul_f32 v[20:21], v[60:61], v[12:13] op_sel_hi:[1,0]
	v_mov_b32_e32 v31, v64
	v_mov_b32_e32 v64, v63
	v_pk_mul_f32 v[18:19], v[30:31], v[18:19]
	v_pk_mul_f32 v[20:21], v[64:65], v[20:21]
	v_pk_mul_f32 v[14:15], v[18:19], v[14:15]
	v_pk_mul_f32 v[16:17], v[20:21], v[16:17]
	v_and_b32_sdwa v13, v15, v211 dst_sel:DWORD dst_unused:UNUSED_PAD src0_sel:WORD_1 src1_sel:DWORD
	v_and_b32_sdwa v19, v17, v211 dst_sel:DWORD dst_unused:UNUSED_PAD src0_sel:WORD_1 src1_sel:DWORD
	v_and_b32_sdwa v20, v16, v211 dst_sel:DWORD dst_unused:UNUSED_PAD src0_sel:WORD_1 src1_sel:DWORD
	v_and_b32_sdwa v18, v14, v211 dst_sel:DWORD dst_unused:UNUSED_PAD src0_sel:WORD_1 src1_sel:DWORD
	v_add3_u32 v13, v15, v13, s19
	v_add3_u32 v15, v17, v19, s19
	v_add3_u32 v16, v16, v20, s19
	v_add3_u32 v14, v14, v18, s19
	v_and_b32_e32 v15, 0xffff0000, v15
	v_and_b32_e32 v16, 0xffff0000, v16
	v_or_b32_sdwa v15, v15, v13 dst_sel:DWORD dst_unused:UNUSED_PAD src0_sel:DWORD src1_sel:WORD_1
	v_or_b32_sdwa v14, v16, v14 dst_sel:DWORD dst_unused:UNUSED_PAD src0_sel:DWORD src1_sel:WORD_1
	global_store_dwordx2 v[6:7], v[14:15], off
	ds_read_b128 v[14:17], v224 offset:36928
	v_mov_b32_e32 v30, v44
	v_mov_b32_e32 v31, v42
	v_mov_b32_e32 v42, v45
	v_pk_mul_f32 v[30:31], v[30:31], v[12:13] op_sel_hi:[1,0]
	v_pk_mul_f32 v[32:33], v[42:43], v[12:13] op_sel_hi:[1,0]
	v_lshlrev_b32_e32 v19, 16, v181
	v_lshlrev_b32_e32 v18, 16, v180
	v_and_b32_e32 v21, 0xffff0000, v181
	v_and_b32_e32 v20, 0xffff0000, v180
	s_waitcnt lgkmcnt(0)
	v_mov_b32_e32 v38, v14
	v_mov_b32_e32 v39, v16
	v_mov_b32_e32 v16, v15
	v_pk_mul_f32 v[14:15], v[38:39], v[30:31]
	v_pk_mul_f32 v[16:17], v[16:17], v[32:33]
	v_pk_mul_f32 v[14:15], v[14:15], v[18:19]
	v_pk_mul_f32 v[16:17], v[16:17], v[20:21]
	v_and_b32_sdwa v13, v15, v211 dst_sel:DWORD dst_unused:UNUSED_PAD src0_sel:WORD_1 src1_sel:DWORD
	v_and_b32_sdwa v19, v17, v211 dst_sel:DWORD dst_unused:UNUSED_PAD src0_sel:WORD_1 src1_sel:DWORD
	v_and_b32_sdwa v20, v16, v211 dst_sel:DWORD dst_unused:UNUSED_PAD src0_sel:WORD_1 src1_sel:DWORD
	v_and_b32_sdwa v18, v14, v211 dst_sel:DWORD dst_unused:UNUSED_PAD src0_sel:WORD_1 src1_sel:DWORD
	v_add3_u32 v13, v15, v13, s19
	v_add3_u32 v15, v17, v19, s19
	v_add3_u32 v16, v16, v20, s19
	v_add3_u32 v14, v14, v18, s19
	v_and_b32_e32 v15, 0xffff0000, v15
	v_and_b32_e32 v16, 0xffff0000, v16
	v_or_b32_sdwa v15, v15, v13 dst_sel:DWORD dst_unused:UNUSED_PAD src0_sel:DWORD src1_sel:WORD_1
	v_or_b32_sdwa v14, v16, v14 dst_sel:DWORD dst_unused:UNUSED_PAD src0_sel:DWORD src1_sel:WORD_1
	global_store_dwordx2 v[6:7], v[14:15], off offset:32
	ds_read_b128 v[14:17], v224 offset:36992
	v_mov_b32_e32 v30, v36
	v_mov_b32_e32 v31, v34
	v_mov_b32_e32 v34, v37
	v_pk_mul_f32 v[30:31], v[30:31], v[12:13] op_sel_hi:[1,0]
	v_pk_mul_f32 v[32:33], v[34:35], v[12:13] op_sel_hi:[1,0]
	v_lshlrev_b32_e32 v19, 16, v179
	v_lshlrev_b32_e32 v18, 16, v178
	v_and_b32_e32 v21, 0xffff0000, v179
	v_and_b32_e32 v20, 0xffff0000, v178
	s_waitcnt lgkmcnt(0)
	v_mov_b32_e32 v34, v14
	v_mov_b32_e32 v35, v16
	v_mov_b32_e32 v16, v15
	v_pk_mul_f32 v[14:15], v[30:31], v[34:35]
	v_pk_mul_f32 v[16:17], v[32:33], v[16:17]
	v_pk_mul_f32 v[14:15], v[14:15], v[18:19]
	v_pk_mul_f32 v[16:17], v[16:17], v[20:21]
	v_and_b32_sdwa v13, v15, v211 dst_sel:DWORD dst_unused:UNUSED_PAD src0_sel:WORD_1 src1_sel:DWORD
	v_and_b32_sdwa v19, v17, v211 dst_sel:DWORD dst_unused:UNUSED_PAD src0_sel:WORD_1 src1_sel:DWORD
	v_and_b32_sdwa v20, v16, v211 dst_sel:DWORD dst_unused:UNUSED_PAD src0_sel:WORD_1 src1_sel:DWORD
	v_and_b32_sdwa v18, v14, v211 dst_sel:DWORD dst_unused:UNUSED_PAD src0_sel:WORD_1 src1_sel:DWORD
	v_add3_u32 v13, v15, v13, s19
	v_add3_u32 v15, v17, v19, s19
	v_add3_u32 v16, v16, v20, s19
	v_add3_u32 v14, v14, v18, s19
	v_and_b32_e32 v15, 0xffff0000, v15
	v_and_b32_e32 v16, 0xffff0000, v16
	v_or_b32_sdwa v15, v15, v13 dst_sel:DWORD dst_unused:UNUSED_PAD src0_sel:DWORD src1_sel:WORD_1
	v_or_b32_sdwa v14, v16, v14 dst_sel:DWORD dst_unused:UNUSED_PAD src0_sel:DWORD src1_sel:WORD_1
	global_store_dwordx2 v[6:7], v[14:15], off offset:64
	ds_read_b128 v[14:17], v224 offset:37056
	v_mov_b32_e32 v30, v56
	v_mov_b32_e32 v31, v54
	v_mov_b32_e32 v54, v57
	v_pk_mul_f32 v[30:31], v[30:31], v[12:13] op_sel_hi:[1,0]
	v_pk_mul_f32 v[32:33], v[54:55], v[12:13] op_sel_hi:[1,0]
	v_lshlrev_b32_e32 v19, 16, v177
	v_lshlrev_b32_e32 v18, 16, v176
	v_and_b32_e32 v21, 0xffff0000, v177
	v_and_b32_e32 v20, 0xffff0000, v176
	s_waitcnt lgkmcnt(0)
	v_mov_b32_e32 v34, v14
	v_mov_b32_e32 v35, v16
	v_mov_b32_e32 v16, v15
	v_pk_mul_f32 v[14:15], v[30:31], v[34:35]
	v_pk_mul_f32 v[16:17], v[32:33], v[16:17]
	v_pk_mul_f32 v[14:15], v[14:15], v[18:19]
	v_pk_mul_f32 v[16:17], v[16:17], v[20:21]
	v_and_b32_sdwa v13, v15, v211 dst_sel:DWORD dst_unused:UNUSED_PAD src0_sel:WORD_1 src1_sel:DWORD
	v_and_b32_sdwa v19, v17, v211 dst_sel:DWORD dst_unused:UNUSED_PAD src0_sel:WORD_1 src1_sel:DWORD
	v_and_b32_sdwa v20, v16, v211 dst_sel:DWORD dst_unused:UNUSED_PAD src0_sel:WORD_1 src1_sel:DWORD
	v_and_b32_sdwa v18, v14, v211 dst_sel:DWORD dst_unused:UNUSED_PAD src0_sel:WORD_1 src1_sel:DWORD
	v_add3_u32 v13, v15, v13, s19
	v_add3_u32 v15, v17, v19, s19
	v_add3_u32 v16, v16, v20, s19
	v_add3_u32 v14, v14, v18, s19
	v_and_b32_e32 v15, 0xffff0000, v15
	v_and_b32_e32 v16, 0xffff0000, v16
	v_or_b32_sdwa v15, v15, v13 dst_sel:DWORD dst_unused:UNUSED_PAD src0_sel:DWORD src1_sel:WORD_1
	v_or_b32_sdwa v14, v16, v14 dst_sel:DWORD dst_unused:UNUSED_PAD src0_sel:DWORD src1_sel:WORD_1
	global_store_dwordx2 v[6:7], v[14:15], off offset:96
	ds_read_b128 v[14:17], v224 offset:37120
	v_mov_b32_e32 v30, v28
	v_mov_b32_e32 v31, v26
	v_mov_b32_e32 v26, v29
	v_pk_mul_f32 v[28:29], v[30:31], v[12:13] op_sel_hi:[1,0]
	v_pk_mul_f32 v[26:27], v[26:27], v[12:13] op_sel_hi:[1,0]
	v_lshlrev_b32_e32 v19, 16, v175
	v_lshlrev_b32_e32 v18, 16, v174
	v_and_b32_e32 v21, 0xffff0000, v175
	v_and_b32_e32 v20, 0xffff0000, v174
	s_waitcnt lgkmcnt(0)
; __device__ __forceinline__ unsigned pk2(float lo, float hi) { return f2bf(lo) | (f2bf(hi) << 16); }
; __device__ __forceinline__ void hgrn_correct(Frame& F, int item) {
;     ...
; #pragma unroll
;         for (int vt = 0; vt < 8; ++vt) {
;             const v2u gw = GW[tt][vt];
;             const f32x4 og = *(const f32x4*)(F.ogain + 16 * vt + 4 * quad);
;             const f32x4 o = O[vt][tt];
;             v2u ow; ow.x = pk2(o[0] * rs * og[0] * bflo(gw.x), o[1] * rs * og[1] * bfhi(gw.x)); ow.y = pk2(o[2] * rs * og[2] * bflo(gw.y), o[3] * rs * og[3] * bfhi(gw.y));
;             *(v2u*)(mp + 16 * vt) = ow;
;         }
;     }
;     __syncthreads();
	v_mov_b32_e32 v30, v14
	v_mov_b32_e32 v31, v16
	v_mov_b32_e32 v16, v15
	v_pk_mul_f32 v[14:15], v[28:29], v[30:31]
	v_pk_mul_f32 v[16:17], v[26:27], v[16:17]
	v_pk_mul_f32 v[14:15], v[14:15], v[18:19]
	v_pk_mul_f32 v[16:17], v[16:17], v[20:21]
	v_and_b32_sdwa v13, v15, v211 dst_sel:DWORD dst_unused:UNUSED_PAD src0_sel:WORD_1 src1_sel:DWORD
	v_and_b32_sdwa v19, v17, v211 dst_sel:DWORD dst_unused:UNUSED_PAD src0_sel:WORD_1 src1_sel:DWORD
	v_and_b32_sdwa v20, v16, v211 dst_sel:DWORD dst_unused:UNUSED_PAD src0_sel:WORD_1 src1_sel:DWORD
	v_and_b32_sdwa v18, v14, v211 dst_sel:DWORD dst_unused:UNUSED_PAD src0_sel:WORD_1 src1_sel:DWORD
	v_add3_u32 v13, v15, v13, s19
	v_add3_u32 v15, v17, v19, s19
	v_add3_u32 v16, v16, v20, s19
	v_add3_u32 v14, v14, v18, s19
	v_and_b32_e32 v15, 0xffff0000, v15
	v_and_b32_e32 v16, 0xffff0000, v16
	v_or_b32_sdwa v15, v15, v13 dst_sel:DWORD dst_unused:UNUSED_PAD src0_sel:DWORD src1_sel:WORD_1
	v_or_b32_sdwa v14, v16, v14 dst_sel:DWORD dst_unused:UNUSED_PAD src0_sel:DWORD src1_sel:WORD_1
	global_store_dwordx2 v[6:7], v[14:15], off offset:128
	ds_read_b128 v[14:17], v224 offset:37184
	v_mov_b32_e32 v26, v24
	v_mov_b32_e32 v27, v22
	v_mov_b32_e32 v22, v25
	v_pk_mul_f32 v[24:25], v[26:27], v[12:13] op_sel_hi:[1,0]
	v_pk_mul_f32 v[22:23], v[22:23], v[12:13] op_sel_hi:[1,0]
	v_lshlrev_b32_e32 v19, 16, v173
	v_lshlrev_b32_e32 v18, 16, v172
	v_and_b32_e32 v21, 0xffff0000, v173
	v_and_b32_e32 v20, 0xffff0000, v172
	s_waitcnt lgkmcnt(0)
	v_mov_b32_e32 v26, v14
	v_mov_b32_e32 v27, v16
	v_mov_b32_e32 v16, v15
	v_pk_mul_f32 v[14:15], v[24:25], v[26:27]
	v_pk_mul_f32 v[16:17], v[22:23], v[16:17]
	v_pk_mul_f32 v[14:15], v[14:15], v[18:19]
	v_pk_mul_f32 v[16:17], v[16:17], v[20:21]
	v_and_b32_sdwa v13, v15, v211 dst_sel:DWORD dst_unused:UNUSED_PAD src0_sel:WORD_1 src1_sel:DWORD
	v_and_b32_sdwa v19, v17, v211 dst_sel:DWORD dst_unused:UNUSED_PAD src0_sel:WORD_1 src1_sel:DWORD
	v_and_b32_sdwa v20, v16, v211 dst_sel:DWORD dst_unused:UNUSED_PAD src0_sel:WORD_1 src1_sel:DWORD
	v_and_b32_sdwa v18, v14, v211 dst_sel:DWORD dst_unused:UNUSED_PAD src0_sel:WORD_1 src1_sel:DWORD
	v_add3_u32 v13, v15, v13, s19
	v_add3_u32 v15, v17, v19, s19
	v_add3_u32 v16, v16, v20, s19
	v_add3_u32 v14, v14, v18, s19
	v_and_b32_e32 v15, 0xffff0000, v15
	v_and_b32_e32 v16, 0xffff0000, v16
	v_or_b32_sdwa v15, v15, v13 dst_sel:DWORD dst_unused:UNUSED_PAD src0_sel:DWORD src1_sel:WORD_1
	v_or_b32_sdwa v14, v16, v14 dst_sel:DWORD dst_unused:UNUSED_PAD src0_sel:DWORD src1_sel:WORD_1
	global_store_dwordx2 v[6:7], v[14:15], off offset:160
	ds_read_b128 v[14:17], v224 offset:37248
	v_mov_b32_e32 v22, v10
	v_mov_b32_e32 v23, v8
	v_mov_b32_e32 v8, v11
	v_pk_mul_f32 v[10:11], v[22:23], v[12:13] op_sel_hi:[1,0]
	v_pk_mul_f32 v[8:9], v[8:9], v[12:13] op_sel_hi:[1,0]
	v_and_b32_e32 v21, 0xffff0000, v171
	v_and_b32_e32 v20, 0xffff0000, v170
	v_lshlrev_b32_e32 v19, 16, v171
	v_lshlrev_b32_e32 v18, 16, v170
	s_waitcnt lgkmcnt(0)
	v_mov_b32_e32 v23, v16
	v_mov_b32_e32 v16, v15
	v_mov_b32_e32 v22, v14
	v_pk_mul_f32 v[8:9], v[8:9], v[16:17]
	v_pk_mul_f32 v[10:11], v[10:11], v[22:23]
	v_pk_mul_f32 v[8:9], v[8:9], v[20:21]
	v_pk_mul_f32 v[10:11], v[10:11], v[18:19]
	v_and_b32_sdwa v15, v9, v211 dst_sel:DWORD dst_unused:UNUSED_PAD src0_sel:WORD_1 src1_sel:DWORD
	v_and_b32_sdwa v16, v8, v211 dst_sel:DWORD dst_unused:UNUSED_PAD src0_sel:WORD_1 src1_sel:DWORD
	v_and_b32_sdwa v13, v11, v211 dst_sel:DWORD dst_unused:UNUSED_PAD src0_sel:WORD_1 src1_sel:DWORD
	v_and_b32_sdwa v14, v10, v211 dst_sel:DWORD dst_unused:UNUSED_PAD src0_sel:WORD_1 src1_sel:DWORD
	v_add3_u32 v9, v9, v15, s19
	v_add3_u32 v8, v8, v16, s19
	v_add3_u32 v10, v10, v14, s19
	v_add3_u32 v11, v11, v13, s19
	v_and_b32_e32 v9, 0xffff0000, v9
	v_and_b32_e32 v8, 0xffff0000, v8
	v_or_b32_sdwa v9, v9, v11 dst_sel:DWORD dst_unused:UNUSED_PAD src0_sel:DWORD src1_sel:WORD_1
	v_or_b32_sdwa v8, v8, v10 dst_sel:DWORD dst_unused:UNUSED_PAD src0_sel:DWORD src1_sel:WORD_1
	global_store_dwordx2 v[6:7], v[8:9], off offset:192
	ds_read_b128 v[8:11], v224 offset:37312
	v_mov_b32_e32 v18, v4
	v_mov_b32_e32 v19, v2
	v_mov_b32_e32 v2, v5
	v_pk_mul_f32 v[4:5], v[18:19], v[12:13] op_sel_hi:[1,0]
	v_pk_mul_f32 v[2:3], v[2:3], v[12:13] op_sel_hi:[1,0]
	v_and_b32_e32 v17, 0xffff0000, v169
	v_and_b32_e32 v16, 0xffff0000, v168
	v_lshlrev_b32_e32 v15, 16, v169
	v_lshlrev_b32_e32 v14, 16, v168
	s_waitcnt lgkmcnt(0)
	v_mov_b32_e32 v13, v10
	v_mov_b32_e32 v10, v9
	v_mov_b32_e32 v12, v8
	v_pk_mul_f32 v[2:3], v[2:3], v[10:11]
	v_pk_mul_f32 v[4:5], v[4:5], v[12:13]
	v_pk_mul_f32 v[2:3], v[2:3], v[16:17]
	v_pk_mul_f32 v[4:5], v[4:5], v[14:15]
	v_and_b32_sdwa v10, v3, v211 dst_sel:DWORD dst_unused:UNUSED_PAD src0_sel:WORD_1 src1_sel:DWORD
	v_and_b32_sdwa v11, v2, v211 dst_sel:DWORD dst_unused:UNUSED_PAD src0_sel:WORD_1 src1_sel:DWORD
	v_and_b32_sdwa v8, v5, v211 dst_sel:DWORD dst_unused:UNUSED_PAD src0_sel:WORD_1 src1_sel:DWORD
	v_and_b32_sdwa v9, v4, v211 dst_sel:DWORD dst_unused:UNUSED_PAD src0_sel:WORD_1 src1_sel:DWORD
	v_add3_u32 v3, v3, v10, s19
	v_add3_u32 v2, v2, v11, s19
	v_add3_u32 v4, v4, v9, s19
	v_add3_u32 v5, v5, v8, s19
	v_and_b32_e32 v3, 0xffff0000, v3
	v_and_b32_e32 v2, 0xffff0000, v2
	v_or_b32_sdwa v3, v3, v5 dst_sel:DWORD dst_unused:UNUSED_PAD src0_sel:DWORD src1_sel:WORD_1
	v_or_b32_sdwa v2, v2, v4 dst_sel:DWORD dst_unused:UNUSED_PAD src0_sel:DWORD src1_sel:WORD_1
	global_store_dwordx2 v[6:7], v[2:3], off offset:224
	s_barrier
	s_cbranch_scc0 .LBB0_571

; #define PG8_STAGE(bufoff, gbase, voff) do { _Pragma("unroll") for (int _i = 0; _i < 2; ++_i) \
;         __builtin_amdgcn_global_load_lds((const unsigned*)((const char*)(gbase) + (voff)[_i]), (PG8_LAS unsigned*)(lds + (bufoff) + ldsw + _i * 8192), 16, 0, 0); } while (0)
; #define PG8_LDA(dst, b, h) do { _Pragma("unroll") for (int m = 0; m < 4; ++m) _Pragma("unroll") for (int k = 0; k < 2; ++k) dst[m][k] = *(const PG8_LAS bf16x8*)(lds + PG8_SA(b, h) + aoff + m * 2048 + k * 1024); } while (0)
; #define PG8_LDB(dst, b, h) do { _Pragma("unroll") for (int n = 0; n < 2; ++n) _Pragma("unroll") for (int k = 0; k < 2; ++k) dst[n][k] = *(const PG8_LAS bf16x8*)(lds + PG8_SB(b, h) + boff + n * 2048 + k * 1024); } while (0)
; #define PG8_MMA(ai, bj, At, Bt) do { __builtin_amdgcn_s_setprio(1); _Pragma("unroll") for (int m = 0; m < 4; ++m) _Pragma("unroll") for (int n = 0; n < 2; ++n) _Pragma("unroll") for (int k = 0; k < 2; ++k) \
;         acc[ai][bj][m][n] = __builtin_amdgcn_mfma_f32_16x16x32_bf16(Bt[n][k], At[m][k], acc[ai][bj][m][n], 0, 0, 0); __builtin_amdgcn_s_setprio(0); } while (0)
; #define PG8_WAIT_V(n) asm volatile("s_waitcnt vmcnt(" #n ")" ::: "memory")
; #define PG8_WAIT_L(n) asm volatile("s_waitcnt lgkmcnt(" #n ")" ::: "memory")
; #define PG8_BAR __builtin_amdgcn_s_barrier()
; #define PG8_SCHED __builtin_amdgcn_sched_barrier(0)
; template <class Epi, class Sched, bool ALIGN_EPI = false, bool SP2 = false>
; __device__ __forceinline__ void gemm_phase(PG8_LAS unsigned char* lds, const Gemm g, const Sched& S, const Epi& E) {
;     ...
;             PG8_LDB(B0, 0, 0); PG8_LDB(B1, 0, 1); PG8_SCHED; PG8_LDA(At, 0, 0); PG8_STAGE(PG8_SA(1, 1), a1 + hstep, voffA);
;             PG8_WAIT_V(8); PG8_WAIT_L(0); PG8_BAR; PG8_MMA(0, 0, At, B0); PG8_MMA(0, 1, At, B1); PG8_BAR; PG8_SCHED;
;             PG8_LDA(At, 0, 1); PG8_STAGE(PG8_SB(0, 0), b2, voffB); PG8_STAGE(PG8_SB(0, 1), b2 + hstep, voffB); PG8_STAGE(PG8_SA(0, 0), a2, voffA);
;             PG8_WAIT_V(8); PG8_WAIT_L(0); PG8_BAR; PG8_MMA(1, 0, At, B0); PG8_MMA(1, 1, At, B1); PG8_BAR; PG8_SCHED;
.LBB0_646:
	ds_read_b128 v[148:151], v152
	ds_read_b128 v[156:159], v152 offset:1024
	ds_read_b128 v[160:163], v152 offset:2048
	ds_read_b128 v[164:167], v152 offset:3072
	ds_read_b128 v[168:171], v153
	ds_read_b128 v[172:175], v153 offset:1024
	ds_read_b128 v[176:179], v153 offset:2048
	ds_read_b128 v[180:183], v153 offset:3072
	s_add_u32 s46, s44, 0xfffc0080
	s_addc_u32 s47, s45, -1
	s_cmp_eq_u32 s73, 12
	s_cselect_b32 s49, s21, s47
	s_cselect_b32 s48, s27, s46
	s_cselect_b32 s47, s19, s72
	s_cselect_b32 s46, s33, s71
	v_lshl_add_u64 v[204:205], s[44:45], 0, v[140:141]
	s_add_i32 m0, s31, 0xc000
	ds_read_b128 v[184:187], v154
	ds_read_b128 v[188:191], v154 offset:1024
	ds_read_b128 v[192:195], v154 offset:2048
	ds_read_b128 v[196:199], v154 offset:3072
	ds_read_b128 v[200:203], v154 offset:4096
	ds_read_b128 v[208:211], v154 offset:5120
	ds_read_b128 v[212:215], v154 offset:6144
	ds_read_b128 v[216:219], v154 offset:7168
	global_load_lds_dwordx4 v[204:205], off
	v_lshl_add_u64 v[204:205], s[44:45], 0, v[142:143]
	s_add_i32 m0, s31, 0xe000
	s_nop 0
	global_load_lds_dwordx4 v[204:205], off
	s_waitcnt vmcnt(8)
	s_waitcnt lgkmcnt(0)
	s_barrier
	s_setprio 1
	s_waitcnt lgkmcnt(0)
	v_mfma_f32_16x16x32_bf16 v[126:129], v[148:151], v[184:187], v[126:129]
	v_mfma_f32_16x16x32_bf16 v[122:125], v[160:163], v[184:187], v[122:125]
	v_mfma_f32_16x16x32_bf16 v[110:113], v[148:151], v[192:195], v[110:113]
	v_mfma_f32_16x16x32_bf16 v[106:109], v[160:163], v[192:195], v[106:109]
	v_mfma_f32_16x16x32_bf16 v[94:97], v[148:151], v[200:203], v[94:97]
	v_mfma_f32_16x16x32_bf16 v[90:93], v[160:163], v[200:203], v[90:93]
	v_mfma_f32_16x16x32_bf16 v[78:81], v[148:151], v[212:215], v[78:81]
	v_mfma_f32_16x16x32_bf16 v[74:77], v[160:163], v[212:215], v[74:77]
	v_mfma_f32_16x16x32_bf16 v[126:129], v[156:159], v[188:191], v[126:129]
	v_mfma_f32_16x16x32_bf16 v[122:125], v[164:167], v[188:191], v[122:125]
	v_mfma_f32_16x16x32_bf16 v[110:113], v[156:159], v[196:199], v[110:113]
	v_mfma_f32_16x16x32_bf16 v[106:109], v[164:167], v[196:199], v[106:109]
	v_mfma_f32_16x16x32_bf16 v[94:97], v[156:159], v[208:211], v[94:97]
	v_mfma_f32_16x16x32_bf16 v[90:93], v[164:167], v[208:211], v[90:93]
	v_mfma_f32_16x16x32_bf16 v[78:81], v[156:159], v[216:219], v[78:81]
	v_mfma_f32_16x16x32_bf16 v[74:77], v[164:167], v[216:219], v[74:77]
	s_setprio 0
	s_setprio 1
	v_mfma_f32_16x16x32_bf16 v[118:121], v[168:171], v[184:187], v[118:121]
	v_mfma_f32_16x16x32_bf16 v[114:117], v[176:179], v[184:187], v[114:117]
	v_mfma_f32_16x16x32_bf16 v[102:105], v[168:171], v[192:195], v[102:105]
	v_mfma_f32_16x16x32_bf16 v[98:101], v[176:179], v[192:195], v[98:101]
	v_mfma_f32_16x16x32_bf16 v[86:89], v[168:171], v[200:203], v[86:89]
	v_mfma_f32_16x16x32_bf16 v[82:85], v[176:179], v[200:203], v[82:85]
	v_mfma_f32_16x16x32_bf16 v[70:73], v[168:171], v[212:215], v[70:73]
	v_mfma_f32_16x16x32_bf16 v[66:69], v[176:179], v[212:215], v[66:69]
	v_mfma_f32_16x16x32_bf16 v[118:121], v[172:175], v[188:191], v[118:121]
	v_mfma_f32_16x16x32_bf16 v[114:117], v[180:183], v[188:191], v[114:117]
	v_mfma_f32_16x16x32_bf16 v[102:105], v[172:175], v[196:199], v[102:105]
	v_mfma_f32_16x16x32_bf16 v[98:101], v[180:183], v[196:199], v[98:101]
	v_mfma_f32_16x16x32_bf16 v[86:89], v[172:175], v[208:211], v[86:89]
	v_mfma_f32_16x16x32_bf16 v[82:85], v[180:183], v[208:211], v[82:85]
	v_mfma_f32_16x16x32_bf16 v[70:73], v[172:175], v[216:219], v[70:73]
	v_mfma_f32_16x16x32_bf16 v[66:69], v[180:183], v[216:219], v[66:69]
	s_setprio 0
	s_barrier
	s_add_i32 s74, s68, s30
	s_mov_b32 m0, s74
	ds_read_b128 v[184:187], v154 offset:16384
	ds_read_b128 v[188:191], v154 offset:17408
	ds_read_b128 v[192:195], v154 offset:18432
	ds_read_b128 v[196:199], v154 offset:19456
	ds_read_b128 v[200:203], v154 offset:20480
	ds_read_b128 v[208:211], v154 offset:21504
	ds_read_b128 v[212:215], v154 offset:22528
	ds_read_b128 v[216:219], v154 offset:23552
	global_load_lds_dwordx4 v132, s[46:47]
	s_add_i32 m0, s74, 0x2000
	s_add_u32 s74, s46, 0x40000
	v_lshl_add_u64 v[220:221], s[46:47], 0, v[136:137]
	s_addc_u32 s75, s47, 0
	s_add_i32 s76, s69, s30
	global_load_lds_dwordx4 v136, s[46:47]
	s_mov_b32 m0, s76
	v_lshl_add_u64 v[224:225], s[48:49], 0, v[134:135]
	global_load_lds_dwordx4 v132, s[74:75]
	s_add_i32 m0, s76, 0x2000
	s_nop 0
	global_load_lds_dwordx4 v136, s[74:75]
	v_lshl_add_u64 v[222:223], s[48:49], 0, v[130:131]
	s_mov_b32 m0, s31
	s_nop 0
	global_load_lds_dwordx4 v130, s[48:49]
	s_mov_b32 m0, s50
	s_nop 0
	global_load_lds_dwordx4 v134, s[48:49]
	s_waitcnt vmcnt(8)
	s_waitcnt lgkmcnt(0)
	s_barrier
; #define PG8_STAGE(bufoff, gbase, voff) do { _Pragma("unroll") for (int _i = 0; _i < 2; ++_i) \
;         __builtin_amdgcn_global_load_lds((const unsigned*)((const char*)(gbase) + (voff)[_i]), (PG8_LAS unsigned*)(lds + (bufoff) + ldsw + _i * 8192), 16, 0, 0); } while (0)
; #define PG8_LDA(dst, b, h) do { _Pragma("unroll") for (int m = 0; m < 4; ++m) _Pragma("unroll") for (int k = 0; k < 2; ++k) dst[m][k] = *(const PG8_LAS bf16x8*)(lds + PG8_SA(b, h) + aoff + m * 2048 + k * 1024); } while (0)
; #define PG8_LDB(dst, b, h) do { _Pragma("unroll") for (int n = 0; n < 2; ++n) _Pragma("unroll") for (int k = 0; k < 2; ++k) dst[n][k] = *(const PG8_LAS bf16x8*)(lds + PG8_SB(b, h) + boff + n * 2048 + k * 1024); } while (0)
; #define PG8_MMA(ai, bj, At, Bt) do { __builtin_amdgcn_s_setprio(1); _Pragma("unroll") for (int m = 0; m < 4; ++m) _Pragma("unroll") for (int n = 0; n < 2; ++n) _Pragma("unroll") for (int k = 0; k < 2; ++k) \
;         acc[ai][bj][m][n] = __builtin_amdgcn_mfma_f32_16x16x32_bf16(Bt[n][k], At[m][k], acc[ai][bj][m][n], 0, 0, 0); __builtin_amdgcn_s_setprio(0); } while (0)
; #define PG8_WAIT_V(n) asm volatile("s_waitcnt vmcnt(" #n ")" ::: "memory")
; #define PG8_WAIT_L(n) asm volatile("s_waitcnt lgkmcnt(" #n ")" ::: "memory")
; #define PG8_BAR __builtin_amdgcn_s_barrier()
; #define PG8_SCHED __builtin_amdgcn_sched_barrier(0)
; template <class Epi, class Sched, bool ALIGN_EPI = false, bool SP2 = false>
; __device__ __forceinline__ void gemm_phase(PG8_LAS unsigned char* lds, const Gemm g, const Sched& S, const Epi& E) {
;     ...
;             PG8_WAIT_V(8); PG8_WAIT_L(0); PG8_BAR; PG8_MMA(1, 0, At, B0); PG8_MMA(1, 1, At, B1); PG8_BAR; PG8_SCHED;
;             PG8_LDB(B0, 1, 0); PG8_LDB(B1, 1, 1); PG8_SCHED; PG8_LDA(At, 1, 0); PG8_STAGE(PG8_SA(0, 1), a2 + hstep, voffA);
;             PG8_WAIT_V(8); PG8_WAIT_L(0); PG8_BAR; PG8_MMA(0, 0, At, B0); PG8_MMA(0, 1, At, B1); PG8_BAR; PG8_SCHED;
	s_setprio 1
	s_waitcnt lgkmcnt(0)
	v_mfma_f32_16x16x32_bf16 v[62:65], v[148:151], v[184:187], v[62:65]
	v_mfma_f32_16x16x32_bf16 v[58:61], v[160:163], v[184:187], v[58:61]
	v_mfma_f32_16x16x32_bf16 v[46:49], v[148:151], v[192:195], v[46:49]
	v_mfma_f32_16x16x32_bf16 v[42:45], v[160:163], v[192:195], v[42:45]
	v_mfma_f32_16x16x32_bf16 v[30:33], v[148:151], v[200:203], v[30:33]
	v_mfma_f32_16x16x32_bf16 v[26:29], v[160:163], v[200:203], v[26:29]
	v_mfma_f32_16x16x32_bf16 v[14:17], v[148:151], v[212:215], v[14:17]
	v_mfma_f32_16x16x32_bf16 v[10:13], v[160:163], v[212:215], v[10:13]
	v_mfma_f32_16x16x32_bf16 v[62:65], v[156:159], v[188:191], v[62:65]
	v_mfma_f32_16x16x32_bf16 v[58:61], v[164:167], v[188:191], v[58:61]
	v_mfma_f32_16x16x32_bf16 v[46:49], v[156:159], v[196:199], v[46:49]
	v_mfma_f32_16x16x32_bf16 v[42:45], v[164:167], v[196:199], v[42:45]
	v_mfma_f32_16x16x32_bf16 v[30:33], v[156:159], v[208:211], v[30:33]
	v_mfma_f32_16x16x32_bf16 v[26:29], v[164:167], v[208:211], v[26:29]
	v_mfma_f32_16x16x32_bf16 v[14:17], v[156:159], v[216:219], v[14:17]
	v_mfma_f32_16x16x32_bf16 v[10:13], v[164:167], v[216:219], v[10:13]
	s_setprio 0
	s_setprio 1
	v_mfma_f32_16x16x32_bf16 v[54:57], v[168:171], v[184:187], v[54:57]
	v_mfma_f32_16x16x32_bf16 v[50:53], v[176:179], v[184:187], v[50:53]
	v_mfma_f32_16x16x32_bf16 v[38:41], v[168:171], v[192:195], v[38:41]
	v_mfma_f32_16x16x32_bf16 v[34:37], v[176:179], v[192:195], v[34:37]
	v_mfma_f32_16x16x32_bf16 v[22:25], v[168:171], v[200:203], v[22:25]
	v_mfma_f32_16x16x32_bf16 v[18:21], v[176:179], v[200:203], v[18:21]
	v_mfma_f32_16x16x32_bf16 v[6:9], v[168:171], v[212:215], v[6:9]
	v_mfma_f32_16x16x32_bf16 v[2:5], v[176:179], v[212:215], v[2:5]
	v_mfma_f32_16x16x32_bf16 v[54:57], v[172:175], v[188:191], v[54:57]
	v_mfma_f32_16x16x32_bf16 v[50:53], v[180:183], v[188:191], v[50:53]
	v_mfma_f32_16x16x32_bf16 v[38:41], v[172:175], v[196:199], v[38:41]
	v_mfma_f32_16x16x32_bf16 v[34:37], v[180:183], v[196:199], v[34:37]
	v_mfma_f32_16x16x32_bf16 v[22:25], v[172:175], v[208:211], v[22:25]
	v_mfma_f32_16x16x32_bf16 v[18:21], v[180:183], v[208:211], v[18:21]
	v_mfma_f32_16x16x32_bf16 v[6:9], v[172:175], v[216:219], v[6:9]
	v_mfma_f32_16x16x32_bf16 v[2:5], v[180:183], v[216:219], v[2:5]
	s_setprio 0
	s_barrier
	s_add_i32 s74, 0, 0x18000
	s_add_i32 s75, 0, 0x1c000
	v_add_u32_e32 v164, s74, v139
	v_add_u32_e32 v180, s75, v139
	ds_read_b128 v[148:151], v164
	ds_read_b128 v[156:159], v164 offset:1024
	ds_read_b128 v[160:163], v164 offset:2048
	ds_read_b128 v[164:167], v164 offset:3072
	ds_read_b128 v[168:171], v180
	ds_read_b128 v[172:175], v180 offset:1024
	ds_read_b128 v[176:179], v180 offset:2048
	ds_read_b128 v[180:183], v180 offset:3072
	s_add_u32 s48, s48, 0x40000
	s_addc_u32 s49, s49, 0
	s_mov_b32 m0, s51
	ds_read_b128 v[184:187], v154 offset:32768
	ds_read_b128 v[188:191], v154 offset:33792
	ds_read_b128 v[192:195], v154 offset:34816
	ds_read_b128 v[196:199], v154 offset:35840
	ds_read_b128 v[200:203], v154 offset:36864
	ds_read_b128 v[208:211], v154 offset:37888
	ds_read_b128 v[212:215], v154 offset:38912
	ds_read_b128 v[216:219], v154 offset:39936
	global_load_lds_dwordx4 v130, s[48:49]
	s_mov_b32 m0, s60
	s_nop 0
	global_load_lds_dwordx4 v134, s[48:49]
	s_waitcnt vmcnt(8)
	s_waitcnt lgkmcnt(0)
	s_barrier
	s_setprio 1
	s_waitcnt lgkmcnt(0)
	v_mfma_f32_16x16x32_bf16 v[126:129], v[148:151], v[184:187], v[126:129]
	v_mfma_f32_16x16x32_bf16 v[122:125], v[160:163], v[184:187], v[122:125]
	v_mfma_f32_16x16x32_bf16 v[110:113], v[148:151], v[192:195], v[110:113]
	v_mfma_f32_16x16x32_bf16 v[106:109], v[160:163], v[192:195], v[106:109]
	v_mfma_f32_16x16x32_bf16 v[94:97], v[148:151], v[200:203], v[94:97]
	v_mfma_f32_16x16x32_bf16 v[90:93], v[160:163], v[200:203], v[90:93]
	v_mfma_f32_16x16x32_bf16 v[78:81], v[148:151], v[212:215], v[78:81]
	v_mfma_f32_16x16x32_bf16 v[74:77], v[160:163], v[212:215], v[74:77]
	v_mfma_f32_16x16x32_bf16 v[126:129], v[156:159], v[188:191], v[126:129]
	v_mfma_f32_16x16x32_bf16 v[122:125], v[164:167], v[188:191], v[122:125]
	v_mfma_f32_16x16x32_bf16 v[110:113], v[156:159], v[196:199], v[110:113]
	v_mfma_f32_16x16x32_bf16 v[106:109], v[164:167], v[196:199], v[106:109]
	v_mfma_f32_16x16x32_bf16 v[94:97], v[156:159], v[208:211], v[94:97]
	v_mfma_f32_16x16x32_bf16 v[90:93], v[164:167], v[208:211], v[90:93]
	v_mfma_f32_16x16x32_bf16 v[78:81], v[156:159], v[216:219], v[78:81]
	v_mfma_f32_16x16x32_bf16 v[74:77], v[164:167], v[216:219], v[74:77]
	s_setprio 0
	s_setprio 1
	v_mfma_f32_16x16x32_bf16 v[118:121], v[168:171], v[184:187], v[118:121]
	v_mfma_f32_16x16x32_bf16 v[114:117], v[176:179], v[184:187], v[114:117]
	v_mfma_f32_16x16x32_bf16 v[102:105], v[168:171], v[192:195], v[102:105]
	v_mfma_f32_16x16x32_bf16 v[98:101], v[176:179], v[192:195], v[98:101]
	v_mfma_f32_16x16x32_bf16 v[86:89], v[168:171], v[200:203], v[86:89]
	v_mfma_f32_16x16x32_bf16 v[82:85], v[176:179], v[200:203], v[82:85]
	v_mfma_f32_16x16x32_bf16 v[70:73], v[168:171], v[212:215], v[70:73]
	v_mfma_f32_16x16x32_bf16 v[66:69], v[176:179], v[212:215], v[66:69]
	v_mfma_f32_16x16x32_bf16 v[118:121], v[172:175], v[188:191], v[118:121]
	v_mfma_f32_16x16x32_bf16 v[114:117], v[180:183], v[188:191], v[114:117]
	v_mfma_f32_16x16x32_bf16 v[102:105], v[172:175], v[196:199], v[102:105]
	v_mfma_f32_16x16x32_bf16 v[98:101], v[180:183], v[196:199], v[98:101]
	v_mfma_f32_16x16x32_bf16 v[86:89], v[172:175], v[208:211], v[86:89]
	v_mfma_f32_16x16x32_bf16 v[82:85], v[180:183], v[208:211], v[82:85]
	v_mfma_f32_16x16x32_bf16 v[70:73], v[172:175], v[216:219], v[70:73]
	v_mfma_f32_16x16x32_bf16 v[66:69], v[180:183], v[216:219], v[66:69]
	s_setprio 0
	s_barrier
; #define PG8_STAGE(bufoff, gbase, voff) do { _Pragma("unroll") for (int _i = 0; _i < 2; ++_i) \
;         __builtin_amdgcn_global_load_lds((const unsigned*)((const char*)(gbase) + (voff)[_i]), (PG8_LAS unsigned*)(lds + (bufoff) + ldsw + _i * 8192), 16, 0, 0); } while (0)
; #define PG8_LDA(dst, b, h) do { _Pragma("unroll") for (int m = 0; m < 4; ++m) _Pragma("unroll") for (int k = 0; k < 2; ++k) dst[m][k] = *(const PG8_LAS bf16x8*)(lds + PG8_SA(b, h) + aoff + m * 2048 + k * 1024); } while (0)
; #define PG8_MMA(ai, bj, At, Bt) do { __builtin_amdgcn_s_setprio(1); _Pragma("unroll") for (int m = 0; m < 4; ++m) _Pragma("unroll") for (int n = 0; n < 2; ++n) _Pragma("unroll") for (int k = 0; k < 2; ++k) \
;         acc[ai][bj][m][n] = __builtin_amdgcn_mfma_f32_16x16x32_bf16(Bt[n][k], At[m][k], acc[ai][bj][m][n], 0, 0, 0); __builtin_amdgcn_s_setprio(0); } while (0)
; #define PG8_WAIT_V(n) asm volatile("s_waitcnt vmcnt(" #n ")" ::: "memory")
; #define PG8_WAIT_L(n) asm volatile("s_waitcnt lgkmcnt(" #n ")" ::: "memory")
; #define PG8_BAR __builtin_amdgcn_s_barrier()
; #define PG8_SCHED __builtin_amdgcn_sched_barrier(0)
; template <class Epi, class Sched, bool ALIGN_EPI = false, bool SP2 = false>
; __device__ __forceinline__ void gemm_phase(PG8_LAS unsigned char* lds, const Gemm g, const Sched& S, const Epi& E) {
;     ...
;         for (int t = 0; t < nt; t += 2) {
;             const bool last = (t == nt - 2);
;     ...
;             PG8_LDA(At, 1, 1); PG8_STAGE(PG8_SB(1, 0), b3, voffB); PG8_STAGE(PG8_SB(1, 1), b3 + hstep, voffB); PG8_STAGE(PG8_SA(1, 0), a3, voffA);
;             PG8_WAIT_V(8); PG8_WAIT_L(0); PG8_BAR; PG8_MMA(1, 0, At, B0); PG8_MMA(1, 1, At, B1); PG8_BAR; PG8_SCHED;
	s_add_i32 s48, s74, s30
	s_mov_b32 m0, s48
	ds_read_b128 v[184:187], v154 offset:49152
	ds_read_b128 v[188:191], v154 offset:50176
	ds_read_b128 v[192:195], v154 offset:51200
	ds_read_b128 v[196:199], v154 offset:52224
	ds_read_b128 v[200:203], v154 offset:53248
	ds_read_b128 v[208:211], v154 offset:54272
	ds_read_b128 v[212:215], v154 offset:55296
	ds_read_b128 v[216:219], v154 offset:56320
	s_add_u32 s98, s46, s14
	s_addc_u32 s99, s47, s15
	global_load_lds_dwordx4 v132, s[98:99]
	s_add_i32 m0, s48, 0x2000
	s_add_u32 s46, s46, 0x40080
	v_lshl_add_u64 v[204:205], v[220:221], 0, s[14:15]
	s_addc_u32 s47, s47, 0
	s_add_i32 s48, s75, s30
	global_load_lds_dwordx4 v[204:205], off
	s_mov_b32 m0, s48
	s_nop 0
	global_load_lds_dwordx4 v132, s[46:47]
	s_add_i32 m0, s48, 0x2000
	s_nop 0
	global_load_lds_dwordx4 v136, s[46:47]
	v_lshl_add_u64 v[204:205], v[222:223], 0, s[14:15]
	s_mov_b32 m0, s62
	s_nop 0
	global_load_lds_dwordx4 v[204:205], off
	v_lshl_add_u64 v[204:205], v[224:225], 0, s[14:15]
	s_mov_b32 m0, s63
	s_nop 0
	global_load_lds_dwordx4 v[204:205], off
	s_waitcnt vmcnt(8)
	s_waitcnt lgkmcnt(0)
	s_barrier
	s_setprio 1
	s_waitcnt lgkmcnt(0)
	v_mfma_f32_16x16x32_bf16 v[62:65], v[148:151], v[184:187], v[62:65]
	v_mfma_f32_16x16x32_bf16 v[58:61], v[160:163], v[184:187], v[58:61]
	v_mfma_f32_16x16x32_bf16 v[46:49], v[148:151], v[192:195], v[46:49]
	v_mfma_f32_16x16x32_bf16 v[42:45], v[160:163], v[192:195], v[42:45]
	v_mfma_f32_16x16x32_bf16 v[30:33], v[148:151], v[200:203], v[30:33]
	v_mfma_f32_16x16x32_bf16 v[26:29], v[160:163], v[200:203], v[26:29]
	v_mfma_f32_16x16x32_bf16 v[14:17], v[148:151], v[212:215], v[14:17]
	v_mfma_f32_16x16x32_bf16 v[10:13], v[160:163], v[212:215], v[10:13]
	v_mfma_f32_16x16x32_bf16 v[62:65], v[156:159], v[188:191], v[62:65]
	v_mfma_f32_16x16x32_bf16 v[58:61], v[164:167], v[188:191], v[58:61]
	v_mfma_f32_16x16x32_bf16 v[46:49], v[156:159], v[196:199], v[46:49]
	v_mfma_f32_16x16x32_bf16 v[42:45], v[164:167], v[196:199], v[42:45]
	v_mfma_f32_16x16x32_bf16 v[30:33], v[156:159], v[208:211], v[30:33]
	v_mfma_f32_16x16x32_bf16 v[26:29], v[164:167], v[208:211], v[26:29]
	v_mfma_f32_16x16x32_bf16 v[14:17], v[156:159], v[216:219], v[14:17]
	v_mfma_f32_16x16x32_bf16 v[10:13], v[164:167], v[216:219], v[10:13]
	s_setprio 0
	s_setprio 1
	v_mfma_f32_16x16x32_bf16 v[54:57], v[168:171], v[184:187], v[54:57]
	v_mfma_f32_16x16x32_bf16 v[50:53], v[176:179], v[184:187], v[50:53]
	v_mfma_f32_16x16x32_bf16 v[38:41], v[168:171], v[192:195], v[38:41]
	v_mfma_f32_16x16x32_bf16 v[34:37], v[176:179], v[192:195], v[34:37]
	v_mfma_f32_16x16x32_bf16 v[22:25], v[168:171], v[200:203], v[22:25]
	v_mfma_f32_16x16x32_bf16 v[18:21], v[176:179], v[200:203], v[18:21]
	v_mfma_f32_16x16x32_bf16 v[6:9], v[168:171], v[212:215], v[6:9]
	v_mfma_f32_16x16x32_bf16 v[2:5], v[176:179], v[212:215], v[2:5]
	v_mfma_f32_16x16x32_bf16 v[54:57], v[172:175], v[188:191], v[54:57]
	v_mfma_f32_16x16x32_bf16 v[50:53], v[180:183], v[188:191], v[50:53]
	v_mfma_f32_16x16x32_bf16 v[38:41], v[172:175], v[196:199], v[38:41]
	v_mfma_f32_16x16x32_bf16 v[34:37], v[180:183], v[196:199], v[34:37]
	v_mfma_f32_16x16x32_bf16 v[22:25], v[172:175], v[208:211], v[22:25]
	v_mfma_f32_16x16x32_bf16 v[18:21], v[180:183], v[208:211], v[18:21]
	v_mfma_f32_16x16x32_bf16 v[6:9], v[172:175], v[216:219], v[6:9]
	v_mfma_f32_16x16x32_bf16 v[2:5], v[180:183], v[216:219], v[2:5]
	s_setprio 0
	s_add_i32 s73, s73, 2
	s_add_u32 s44, s44, 0x100
	s_addc_u32 s45, s45, 0
	s_add_u32 s71, s71, 0x100
	s_addc_u32 s72, s72, 0
	s_cmp_gt_u32 s73, 13
	s_barrier
	s_cbranch_scc0 .LBB0_646
	s_and_b64 vcc, exec, s[16:17]
	s_cbranch_vccz .LBB0_649
	s_barrier

; template <bool COOP>
; __global__ void __launch_bounds__(NWAVES * 64, 2) fwd(Args args) {
;     ...
;         if (rs_cached) {
;             for (int r = F.tid; r < 2048; r += NWAVES * 64) {
;                 const f32x4* pp = (const f32x4*)(F.PART + (size_t)(rbase + r) * 16);
;                 const f32x4 p0 = pp[0], p1 = pp[1], p2 = pp[2], p3 = pp[3];
;                 const float ssq = ((p0[0] + p0[1]) + (p0[2] + p0[3])) + ((p1[0] + p1[1]) + (p1[2] + p1[3])) + ((p2[0] + p2[1]) + (p2[2] + p2[3])) + ((p3[0] + p3[1]) + (p3[2] + p3[3]));
;                 rsc[r] = __builtin_amdgcn_rsqf(ssq * (1.0f / 1024.0f) + 1e-6f);
;             }
;             __syncthreads();
;         }
.LBB0_727:
	v_lshl_add_u64 v[26:27], v[2:3], 0, s[4:5]
	v_lshl_add_u64 v[28:29], v[26:27], 0, s[4:5]
	global_load_dwordx4 v[30:33], v[2:3], off
	global_load_dwordx4 v[34:37], v[2:3], off offset:16
	global_load_dwordx4 v[38:41], v[2:3], off offset:32
	global_load_dwordx4 v[42:45], v[2:3], off offset:48
	global_load_dwordx4 v[46:49], v[26:27], off
	global_load_dwordx4 v[50:53], v[26:27], off offset:16
	global_load_dwordx4 v[54:57], v[26:27], off offset:32
	global_load_dwordx4 v[58:61], v[26:27], off offset:48
	global_load_dwordx4 v[62:65], v[28:29], off
	global_load_dwordx4 v[66:69], v[28:29], off offset:16
	global_load_dwordx4 v[70:73], v[28:29], off offset:32
	global_load_dwordx4 v[74:77], v[28:29], off offset:48
	v_lshl_add_u64 v[26:27], v[28:29], 0, s[4:5]
	global_load_dwordx4 v[78:81], v[26:27], off
	global_load_dwordx4 v[82:85], v[26:27], off offset:16
	global_load_dwordx4 v[86:89], v[26:27], off offset:32
	global_load_dwordx4 v[90:93], v[26:27], off offset:48
	s_waitcnt vmcnt(12)
	v_mov_b32_e32 v6, v30
	v_mov_b32_e32 v7, v31
	v_mov_b32_e32 v8, v32
	v_mov_b32_e32 v9, v33
	v_mov_b32_e32 v14, v34
	v_mov_b32_e32 v15, v35
	v_mov_b32_e32 v16, v36
	v_mov_b32_e32 v17, v37
	v_mov_b32_e32 v18, v38
	v_mov_b32_e32 v19, v39
	v_mov_b32_e32 v20, v40
	v_mov_b32_e32 v21, v41
	v_mov_b32_e32 v22, v42
	v_mov_b32_e32 v23, v43
	v_mov_b32_e32 v24, v44
	v_mov_b32_e32 v25, v45
	v_mov_b32_e32 v10, v7
	v_mov_b32_e32 v11, v8
	v_mov_b32_e32 v7, v9
	v_mov_b32_e32 v8, v15
	v_mov_b32_e32 v9, v16
	v_mov_b32_e32 v15, v17
	v_pk_add_f32 v[6:7], v[10:11], v[6:7]
	v_pk_add_f32 v[8:9], v[8:9], v[14:15]
	v_pk_add_f32 v[6:7], v[6:7], v[6:7] op_sel:[0,1] op_sel_hi:[1,0]
	v_pk_add_f32 v[8:9], v[8:9], v[8:9] op_sel:[0,1] op_sel_hi:[1,0]
	v_add_f32_e32 v16, v18, v19
	v_add_f32_e32 v18, v20, v21
	v_mov_b32_e32 v17, v24
	v_mov_b32_e32 v19, v25
	v_mov_b32_e32 v7, v22
	v_mov_b32_e32 v9, v23
	v_pk_add_f32 v[10:11], v[16:17], v[18:19]
	v_pk_add_f32 v[6:7], v[6:7], v[8:9]
	s_nop 0
	v_pk_add_f32 v[6:7], v[6:7], v[10:11]
	s_nop 0
	v_add_f32_e32 v6, v6, v7
	v_fmamk_f32 v6, v6, 0x3a800000, v5
	v_rsq_f32_e32 v6, v6
	s_nop 0
	ds_write_b32 v4, v6 offset:0
	s_waitcnt vmcnt(8)
	v_mov_b32_e32 v6, v46
	v_mov_b32_e32 v7, v47
	v_mov_b32_e32 v8, v48
	v_mov_b32_e32 v9, v49
	v_mov_b32_e32 v14, v50
	v_mov_b32_e32 v15, v51
	v_mov_b32_e32 v16, v52
	v_mov_b32_e32 v17, v53
	v_mov_b32_e32 v18, v54
	v_mov_b32_e32 v19, v55
	v_mov_b32_e32 v20, v56
	v_mov_b32_e32 v21, v57
	v_mov_b32_e32 v22, v58
	v_mov_b32_e32 v23, v59
	v_mov_b32_e32 v24, v60
	v_mov_b32_e32 v25, v61
	v_mov_b32_e32 v10, v7
	v_mov_b32_e32 v11, v8
	v_mov_b32_e32 v7, v9
	v_mov_b32_e32 v8, v15
	v_mov_b32_e32 v9, v16
	v_mov_b32_e32 v15, v17
	v_pk_add_f32 v[6:7], v[10:11], v[6:7]
	v_pk_add_f32 v[8:9], v[8:9], v[14:15]
	v_pk_add_f32 v[6:7], v[6:7], v[6:7] op_sel:[0,1] op_sel_hi:[1,0]
	v_pk_add_f32 v[8:9], v[8:9], v[8:9] op_sel:[0,1] op_sel_hi:[1,0]
	v_add_f32_e32 v16, v18, v19
	v_add_f32_e32 v18, v20, v21
	v_mov_b32_e32 v17, v24
	v_mov_b32_e32 v19, v25
	v_mov_b32_e32 v7, v22
	v_mov_b32_e32 v9, v23
	v_pk_add_f32 v[10:11], v[16:17], v[18:19]
	v_pk_add_f32 v[6:7], v[6:7], v[8:9]
	s_nop 0
	v_pk_add_f32 v[6:7], v[6:7], v[10:11]
	s_nop 0
	v_add_f32_e32 v6, v6, v7
	v_fmamk_f32 v6, v6, 0x3a800000, v5
	v_rsq_f32_e32 v6, v6
	s_nop 0
	ds_write_b32 v4, v6 offset:2048
	s_waitcnt vmcnt(4)
	v_mov_b32_e32 v6, v62
	v_mov_b32_e32 v7, v63
	v_mov_b32_e32 v8, v64
	v_mov_b32_e32 v9, v65
	v_mov_b32_e32 v14, v66
	v_mov_b32_e32 v15, v67
	v_mov_b32_e32 v16, v68
	v_mov_b32_e32 v17, v69
	v_mov_b32_e32 v18, v70
	v_mov_b32_e32 v19, v71
	v_mov_b32_e32 v20, v72
	v_mov_b32_e32 v21, v73
	v_mov_b32_e32 v22, v74
	v_mov_b32_e32 v23, v75
	v_mov_b32_e32 v24, v76
	v_mov_b32_e32 v25, v77
	v_mov_b32_e32 v10, v7
	v_mov_b32_e32 v11, v8
	v_mov_b32_e32 v7, v9
	v_mov_b32_e32 v8, v15
	v_mov_b32_e32 v9, v16
	v_mov_b32_e32 v15, v17
	v_pk_add_f32 v[6:7], v[10:11], v[6:7]
	v_pk_add_f32 v[8:9], v[8:9], v[14:15]
	v_pk_add_f32 v[6:7], v[6:7], v[6:7] op_sel:[0,1] op_sel_hi:[1,0]
	v_pk_add_f32 v[8:9], v[8:9], v[8:9] op_sel:[0,1] op_sel_hi:[1,0]
	v_add_f32_e32 v16, v18, v19
	v_add_f32_e32 v18, v20, v21
	v_mov_b32_e32 v17, v24
	v_mov_b32_e32 v19, v25
	v_mov_b32_e32 v7, v22
	v_mov_b32_e32 v9, v23
	v_pk_add_f32 v[10:11], v[16:17], v[18:19]
	v_pk_add_f32 v[6:7], v[6:7], v[8:9]
	s_nop 0
	v_pk_add_f32 v[6:7], v[6:7], v[10:11]
	s_nop 0
	v_add_f32_e32 v6, v6, v7
	v_fmamk_f32 v6, v6, 0x3a800000, v5
	v_rsq_f32_e32 v6, v6
	s_nop 0
	ds_write_b32 v4, v6 offset:4096
	s_waitcnt vmcnt(0)
	v_mov_b32_e32 v6, v78
	v_mov_b32_e32 v7, v79
	v_mov_b32_e32 v8, v80
	v_mov_b32_e32 v9, v81
	v_mov_b32_e32 v14, v82
	v_mov_b32_e32 v15, v83
	v_mov_b32_e32 v16, v84
	v_mov_b32_e32 v17, v85
	v_mov_b32_e32 v18, v86
	v_mov_b32_e32 v19, v87
	v_mov_b32_e32 v20, v88
	v_mov_b32_e32 v21, v89
	v_mov_b32_e32 v22, v90
	v_mov_b32_e32 v23, v91
	v_mov_b32_e32 v24, v92
	v_mov_b32_e32 v25, v93
	v_mov_b32_e32 v10, v7
	v_mov_b32_e32 v11, v8
	v_mov_b32_e32 v7, v9
	v_mov_b32_e32 v8, v15
	v_mov_b32_e32 v9, v16
	v_mov_b32_e32 v15, v17
	v_pk_add_f32 v[6:7], v[10:11], v[6:7]
	v_pk_add_f32 v[8:9], v[8:9], v[14:15]
	v_pk_add_f32 v[6:7], v[6:7], v[6:7] op_sel:[0,1] op_sel_hi:[1,0]
	v_pk_add_f32 v[8:9], v[8:9], v[8:9] op_sel:[0,1] op_sel_hi:[1,0]
	v_add_f32_e32 v16, v18, v19
	v_add_f32_e32 v18, v20, v21
	v_mov_b32_e32 v17, v24
	v_mov_b32_e32 v19, v25
	v_mov_b32_e32 v7, v22
	v_mov_b32_e32 v9, v23
	v_pk_add_f32 v[10:11], v[16:17], v[18:19]
	v_pk_add_f32 v[6:7], v[6:7], v[8:9]
	s_nop 0
	v_pk_add_f32 v[6:7], v[6:7], v[10:11]
	s_nop 0
	v_add_f32_e32 v6, v6, v7
	v_fmamk_f32 v6, v6, 0x3a800000, v5
	v_rsq_f32_e32 v6, v6
	s_nop 0
	ds_write_b32 v4, v6 offset:6144
	s_or_b64 exec, exec, s[0:1]
	s_add_i32 s46, 0, 0x20400
	s_waitcnt lgkmcnt(0)
	s_barrier

; #define PG8_STAGE(bufoff, gbase, voff) do { _Pragma("unroll") for (int _i = 0; _i < 2; ++_i) \
;         __builtin_amdgcn_global_load_lds((const unsigned*)((const char*)(gbase) + (voff)[_i]), (PG8_LAS unsigned*)(lds + (bufoff) + ldsw + _i * 8192), 16, 0, 0); } while (0)
; #define PG8_LDA(dst, b, h) do { _Pragma("unroll") for (int m = 0; m < 4; ++m) _Pragma("unroll") for (int k = 0; k < 2; ++k) dst[m][k] = *(const PG8_LAS bf16x8*)(lds + PG8_SA(b, h) + aoff + m * 2048 + k * 1024); } while (0)
; #define PG8_LDB(dst, b, h) do { _Pragma("unroll") for (int n = 0; n < 2; ++n) _Pragma("unroll") for (int k = 0; k < 2; ++k) dst[n][k] = *(const PG8_LAS bf16x8*)(lds + PG8_SB(b, h) + boff + n * 2048 + k * 1024); } while (0)
; #define PG8_MMA(ai, bj, At, Bt) do { __builtin_amdgcn_s_setprio(1); _Pragma("unroll") for (int m = 0; m < 4; ++m) _Pragma("unroll") for (int n = 0; n < 2; ++n) _Pragma("unroll") for (int k = 0; k < 2; ++k) \
;         acc[ai][bj][m][n] = __builtin_amdgcn_mfma_f32_16x16x32_bf16(Bt[n][k], At[m][k], acc[ai][bj][m][n], 0, 0, 0); __builtin_amdgcn_s_setprio(0); } while (0)
; #define PG8_WAIT_V(n) asm volatile("s_waitcnt vmcnt(" #n ")" ::: "memory")
; #define PG8_WAIT_L(n) asm volatile("s_waitcnt lgkmcnt(" #n ")" ::: "memory")
; #define PG8_BAR __builtin_amdgcn_s_barrier()
; #define PG8_SCHED __builtin_amdgcn_sched_barrier(0)
; template <class Epi, class Sched, bool ALIGN_EPI = false, bool SP2 = false>
; __device__ __forceinline__ void gemm_phase(PG8_LAS unsigned char* lds, const Gemm g, const Sched& S, const Epi& E) {
;     ...
;             PG8_LDB(B0, 0, 0); PG8_LDB(B1, 0, 1); PG8_SCHED; PG8_LDA(At, 0, 0); PG8_STAGE(PG8_SA(1, 1), a1 + hstep, voffA);
;             PG8_WAIT_V(8); PG8_WAIT_L(0); PG8_BAR; PG8_MMA(0, 0, At, B0); PG8_MMA(0, 1, At, B1); PG8_BAR; PG8_SCHED;
;             PG8_LDA(At, 0, 1); PG8_STAGE(PG8_SB(0, 0), b2, voffB); PG8_STAGE(PG8_SB(0, 1), b2 + hstep, voffB); PG8_STAGE(PG8_SA(0, 0), a2, voffA);
;             PG8_WAIT_V(8); PG8_WAIT_L(0); PG8_BAR; PG8_MMA(1, 0, At, B0); PG8_MMA(1, 1, At, B1); PG8_BAR; PG8_SCHED;
.LBB0_740:
	ds_read_b128 v[156:159], v152
	ds_read_b128 v[160:163], v152 offset:1024
	ds_read_b128 v[164:167], v152 offset:2048
	ds_read_b128 v[168:171], v152 offset:3072
	ds_read_b128 v[172:175], v153
	ds_read_b128 v[176:179], v153 offset:1024
	ds_read_b128 v[180:183], v153 offset:2048
	ds_read_b128 v[184:187], v153 offset:3072
	s_add_u32 s40, s30, 0xfffc0080
	s_addc_u32 s41, s31, -1
	s_cmp_eq_u32 s71, 12
	s_cselect_b32 s45, s19, s41
	s_cselect_b32 s44, s25, s40
	s_cselect_b32 s41, s17, s70
	s_cselect_b32 s40, s27, s33
	v_lshl_add_u64 v[148:149], s[30:31], 0, v[140:141]
	s_add_i32 m0, s48, 0xc000
	ds_read_b128 v[188:191], v154
	ds_read_b128 v[192:195], v154 offset:1024
	ds_read_b128 v[196:199], v154 offset:2048
	ds_read_b128 v[200:203], v154 offset:3072
	ds_read_b128 v[208:211], v154 offset:4096
	ds_read_b128 v[212:215], v154 offset:5120
	ds_read_b128 v[216:219], v154 offset:6144
	ds_read_b128 v[220:223], v154 offset:7168
	global_load_lds_dwordx4 v[148:149], off
	v_lshl_add_u64 v[148:149], s[30:31], 0, v[142:143]
	s_add_i32 m0, s48, 0xe000
	s_nop 0
	global_load_lds_dwordx4 v[148:149], off
	s_waitcnt vmcnt(8)
	s_waitcnt lgkmcnt(0)
	s_barrier
	s_setprio 1
	s_waitcnt lgkmcnt(0)
	v_mfma_f32_16x16x32_bf16 v[126:129], v[156:159], v[188:191], v[126:129]
	v_mfma_f32_16x16x32_bf16 v[122:125], v[164:167], v[188:191], v[122:125]
	v_mfma_f32_16x16x32_bf16 v[110:113], v[156:159], v[196:199], v[110:113]
	v_mfma_f32_16x16x32_bf16 v[106:109], v[164:167], v[196:199], v[106:109]
	v_mfma_f32_16x16x32_bf16 v[94:97], v[156:159], v[208:211], v[94:97]
	v_mfma_f32_16x16x32_bf16 v[90:93], v[164:167], v[208:211], v[90:93]
	v_mfma_f32_16x16x32_bf16 v[78:81], v[156:159], v[216:219], v[78:81]
	v_mfma_f32_16x16x32_bf16 v[74:77], v[164:167], v[216:219], v[74:77]
	v_mfma_f32_16x16x32_bf16 v[126:129], v[160:163], v[192:195], v[126:129]
	v_mfma_f32_16x16x32_bf16 v[122:125], v[168:171], v[192:195], v[122:125]
	v_mfma_f32_16x16x32_bf16 v[110:113], v[160:163], v[200:203], v[110:113]
	v_mfma_f32_16x16x32_bf16 v[106:109], v[168:171], v[200:203], v[106:109]
	v_mfma_f32_16x16x32_bf16 v[94:97], v[160:163], v[212:215], v[94:97]
	v_mfma_f32_16x16x32_bf16 v[90:93], v[168:171], v[212:215], v[90:93]
	v_mfma_f32_16x16x32_bf16 v[78:81], v[160:163], v[220:223], v[78:81]
	v_mfma_f32_16x16x32_bf16 v[74:77], v[168:171], v[220:223], v[74:77]
	s_setprio 0
	s_setprio 1
	v_mfma_f32_16x16x32_bf16 v[118:121], v[172:175], v[188:191], v[118:121]
	v_mfma_f32_16x16x32_bf16 v[114:117], v[180:183], v[188:191], v[114:117]
	v_mfma_f32_16x16x32_bf16 v[102:105], v[172:175], v[196:199], v[102:105]
	v_mfma_f32_16x16x32_bf16 v[98:101], v[180:183], v[196:199], v[98:101]
	v_mfma_f32_16x16x32_bf16 v[86:89], v[172:175], v[208:211], v[86:89]
	v_mfma_f32_16x16x32_bf16 v[82:85], v[180:183], v[208:211], v[82:85]
	v_mfma_f32_16x16x32_bf16 v[70:73], v[172:175], v[216:219], v[70:73]
	v_mfma_f32_16x16x32_bf16 v[66:69], v[180:183], v[216:219], v[66:69]
	v_mfma_f32_16x16x32_bf16 v[118:121], v[176:179], v[192:195], v[118:121]
	v_mfma_f32_16x16x32_bf16 v[114:117], v[184:187], v[192:195], v[114:117]
	v_mfma_f32_16x16x32_bf16 v[102:105], v[176:179], v[200:203], v[102:105]
	v_mfma_f32_16x16x32_bf16 v[98:101], v[184:187], v[200:203], v[98:101]
	v_mfma_f32_16x16x32_bf16 v[86:89], v[176:179], v[212:215], v[86:89]
	v_mfma_f32_16x16x32_bf16 v[82:85], v[184:187], v[212:215], v[82:85]
	v_mfma_f32_16x16x32_bf16 v[70:73], v[176:179], v[220:223], v[70:73]
	v_mfma_f32_16x16x32_bf16 v[66:69], v[184:187], v[220:223], v[66:69]
	s_setprio 0
	s_barrier
	s_add_i32 s72, s66, s47
	s_mov_b32 m0, s72
	ds_read_b128 v[188:191], v154 offset:16384
	ds_read_b128 v[192:195], v154 offset:17408
	ds_read_b128 v[196:199], v154 offset:18432
	ds_read_b128 v[200:203], v154 offset:19456
	ds_read_b128 v[208:211], v154 offset:20480
	ds_read_b128 v[212:215], v154 offset:21504
	ds_read_b128 v[216:219], v154 offset:22528
	ds_read_b128 v[220:223], v154 offset:23552
	global_load_lds_dwordx4 v132, s[40:41]
	s_add_i32 m0, s72, 0x2000
	s_add_u32 s72, s40, 0x40000
	v_lshl_add_u64 v[204:205], s[40:41], 0, v[136:137]
	s_addc_u32 s73, s41, 0
	s_add_i32 s74, s67, s47
	global_load_lds_dwordx4 v136, s[40:41]
	s_mov_b32 m0, s74
	v_lshl_add_u64 v[226:227], s[44:45], 0, v[134:135]
	global_load_lds_dwordx4 v132, s[72:73]
	s_add_i32 m0, s74, 0x2000
	s_nop 0
	global_load_lds_dwordx4 v136, s[72:73]
	v_lshl_add_u64 v[224:225], s[44:45], 0, v[130:131]
	s_mov_b32 m0, s48
	s_nop 0
	global_load_lds_dwordx4 v130, s[44:45]
	s_mov_b32 m0, s49
	s_nop 0
	global_load_lds_dwordx4 v134, s[44:45]
	s_waitcnt vmcnt(8)
	s_waitcnt lgkmcnt(0)
	s_barrier
; #define PG8_STAGE(bufoff, gbase, voff) do { _Pragma("unroll") for (int _i = 0; _i < 2; ++_i) \
;         __builtin_amdgcn_global_load_lds((const unsigned*)((const char*)(gbase) + (voff)[_i]), (PG8_LAS unsigned*)(lds + (bufoff) + ldsw + _i * 8192), 16, 0, 0); } while (0)
; #define PG8_LDA(dst, b, h) do { _Pragma("unroll") for (int m = 0; m < 4; ++m) _Pragma("unroll") for (int k = 0; k < 2; ++k) dst[m][k] = *(const PG8_LAS bf16x8*)(lds + PG8_SA(b, h) + aoff + m * 2048 + k * 1024); } while (0)
; #define PG8_LDB(dst, b, h) do { _Pragma("unroll") for (int n = 0; n < 2; ++n) _Pragma("unroll") for (int k = 0; k < 2; ++k) dst[n][k] = *(const PG8_LAS bf16x8*)(lds + PG8_SB(b, h) + boff + n * 2048 + k * 1024); } while (0)
; #define PG8_MMA(ai, bj, At, Bt) do { __builtin_amdgcn_s_setprio(1); _Pragma("unroll") for (int m = 0; m < 4; ++m) _Pragma("unroll") for (int n = 0; n < 2; ++n) _Pragma("unroll") for (int k = 0; k < 2; ++k) \
;         acc[ai][bj][m][n] = __builtin_amdgcn_mfma_f32_16x16x32_bf16(Bt[n][k], At[m][k], acc[ai][bj][m][n], 0, 0, 0); __builtin_amdgcn_s_setprio(0); } while (0)
; #define PG8_WAIT_V(n) asm volatile("s_waitcnt vmcnt(" #n ")" ::: "memory")
; #define PG8_WAIT_L(n) asm volatile("s_waitcnt lgkmcnt(" #n ")" ::: "memory")
; #define PG8_BAR __builtin_amdgcn_s_barrier()
; #define PG8_SCHED __builtin_amdgcn_sched_barrier(0)
; template <class Epi, class Sched, bool ALIGN_EPI = false, bool SP2 = false>
; __device__ __forceinline__ void gemm_phase(PG8_LAS unsigned char* lds, const Gemm g, const Sched& S, const Epi& E) {
;     ...
;             PG8_WAIT_V(8); PG8_WAIT_L(0); PG8_BAR; PG8_MMA(1, 0, At, B0); PG8_MMA(1, 1, At, B1); PG8_BAR; PG8_SCHED;
;             PG8_LDB(B0, 1, 0); PG8_LDB(B1, 1, 1); PG8_SCHED; PG8_LDA(At, 1, 0); PG8_STAGE(PG8_SA(0, 1), a2 + hstep, voffA);
;             PG8_WAIT_V(8); PG8_WAIT_L(0); PG8_BAR; PG8_MMA(0, 0, At, B0); PG8_MMA(0, 1, At, B1); PG8_BAR; PG8_SCHED;
	s_setprio 1
	s_waitcnt lgkmcnt(0)
	v_mfma_f32_16x16x32_bf16 v[62:65], v[156:159], v[188:191], v[62:65]
	v_mfma_f32_16x16x32_bf16 v[58:61], v[164:167], v[188:191], v[58:61]
	v_mfma_f32_16x16x32_bf16 v[46:49], v[156:159], v[196:199], v[46:49]
	v_mfma_f32_16x16x32_bf16 v[42:45], v[164:167], v[196:199], v[42:45]
	v_mfma_f32_16x16x32_bf16 v[30:33], v[156:159], v[208:211], v[30:33]
	v_mfma_f32_16x16x32_bf16 v[26:29], v[164:167], v[208:211], v[26:29]
	v_mfma_f32_16x16x32_bf16 v[14:17], v[156:159], v[216:219], v[14:17]
	v_mfma_f32_16x16x32_bf16 v[10:13], v[164:167], v[216:219], v[10:13]
	v_mfma_f32_16x16x32_bf16 v[62:65], v[160:163], v[192:195], v[62:65]
	v_mfma_f32_16x16x32_bf16 v[58:61], v[168:171], v[192:195], v[58:61]
	v_mfma_f32_16x16x32_bf16 v[46:49], v[160:163], v[200:203], v[46:49]
	v_mfma_f32_16x16x32_bf16 v[42:45], v[168:171], v[200:203], v[42:45]
	v_mfma_f32_16x16x32_bf16 v[30:33], v[160:163], v[212:215], v[30:33]
	v_mfma_f32_16x16x32_bf16 v[26:29], v[168:171], v[212:215], v[26:29]
	v_mfma_f32_16x16x32_bf16 v[14:17], v[160:163], v[220:223], v[14:17]
	v_mfma_f32_16x16x32_bf16 v[10:13], v[168:171], v[220:223], v[10:13]
	s_setprio 0
	s_setprio 1
	v_mfma_f32_16x16x32_bf16 v[54:57], v[172:175], v[188:191], v[54:57]
	v_mfma_f32_16x16x32_bf16 v[50:53], v[180:183], v[188:191], v[50:53]
	v_mfma_f32_16x16x32_bf16 v[38:41], v[172:175], v[196:199], v[38:41]
	v_mfma_f32_16x16x32_bf16 v[34:37], v[180:183], v[196:199], v[34:37]
	v_mfma_f32_16x16x32_bf16 v[22:25], v[172:175], v[208:211], v[22:25]
	v_mfma_f32_16x16x32_bf16 v[18:21], v[180:183], v[208:211], v[18:21]
	v_mfma_f32_16x16x32_bf16 v[6:9], v[172:175], v[216:219], v[6:9]
	v_mfma_f32_16x16x32_bf16 v[2:5], v[180:183], v[216:219], v[2:5]
	v_mfma_f32_16x16x32_bf16 v[54:57], v[176:179], v[192:195], v[54:57]
	v_mfma_f32_16x16x32_bf16 v[50:53], v[184:187], v[192:195], v[50:53]
	v_mfma_f32_16x16x32_bf16 v[38:41], v[176:179], v[200:203], v[38:41]
	v_mfma_f32_16x16x32_bf16 v[34:37], v[184:187], v[200:203], v[34:37]
	v_mfma_f32_16x16x32_bf16 v[22:25], v[176:179], v[212:215], v[22:25]
	v_mfma_f32_16x16x32_bf16 v[18:21], v[184:187], v[212:215], v[18:21]
	v_mfma_f32_16x16x32_bf16 v[6:9], v[176:179], v[220:223], v[6:9]
	v_mfma_f32_16x16x32_bf16 v[2:5], v[184:187], v[220:223], v[2:5]
	s_setprio 0
	s_barrier
	s_add_i32 s72, 0, 0x18000
	v_add_u32_e32 v150, s72, v151
	s_add_i32 s73, 0, 0x1c000
	ds_read_b128 v[156:159], v150
	ds_read_b128 v[160:163], v150 offset:1024
	ds_read_b128 v[164:167], v150 offset:2048
	ds_read_b128 v[168:171], v150 offset:3072
	v_add_u32_e32 v150, s73, v151
	ds_read_b128 v[172:175], v150
	ds_read_b128 v[176:179], v150 offset:1024
	ds_read_b128 v[180:183], v150 offset:2048
	ds_read_b128 v[184:187], v150 offset:3072
	s_add_u32 s44, s44, 0x40000
	s_addc_u32 s45, s45, 0
	s_mov_b32 m0, s50
	ds_read_b128 v[188:191], v154 offset:32768
	ds_read_b128 v[192:195], v154 offset:33792
	ds_read_b128 v[196:199], v154 offset:34816
	ds_read_b128 v[200:203], v154 offset:35840
	ds_read_b128 v[208:211], v154 offset:36864
	ds_read_b128 v[212:215], v154 offset:37888
	ds_read_b128 v[216:219], v154 offset:38912
	ds_read_b128 v[220:223], v154 offset:39936
	global_load_lds_dwordx4 v130, s[44:45]
	s_mov_b32 m0, s51
	s_nop 0
	global_load_lds_dwordx4 v134, s[44:45]
	s_waitcnt vmcnt(8)
	s_waitcnt lgkmcnt(0)
	s_barrier
	s_setprio 1
	s_waitcnt lgkmcnt(0)
	v_mfma_f32_16x16x32_bf16 v[126:129], v[156:159], v[188:191], v[126:129]
	v_mfma_f32_16x16x32_bf16 v[122:125], v[164:167], v[188:191], v[122:125]
	v_mfma_f32_16x16x32_bf16 v[110:113], v[156:159], v[196:199], v[110:113]
	v_mfma_f32_16x16x32_bf16 v[106:109], v[164:167], v[196:199], v[106:109]
	v_mfma_f32_16x16x32_bf16 v[94:97], v[156:159], v[208:211], v[94:97]
	v_mfma_f32_16x16x32_bf16 v[90:93], v[164:167], v[208:211], v[90:93]
	v_mfma_f32_16x16x32_bf16 v[78:81], v[156:159], v[216:219], v[78:81]
	v_mfma_f32_16x16x32_bf16 v[74:77], v[164:167], v[216:219], v[74:77]
	v_mfma_f32_16x16x32_bf16 v[126:129], v[160:163], v[192:195], v[126:129]
	v_mfma_f32_16x16x32_bf16 v[122:125], v[168:171], v[192:195], v[122:125]
	v_mfma_f32_16x16x32_bf16 v[110:113], v[160:163], v[200:203], v[110:113]
	v_mfma_f32_16x16x32_bf16 v[106:109], v[168:171], v[200:203], v[106:109]
	v_mfma_f32_16x16x32_bf16 v[94:97], v[160:163], v[212:215], v[94:97]
	v_mfma_f32_16x16x32_bf16 v[90:93], v[168:171], v[212:215], v[90:93]
	v_mfma_f32_16x16x32_bf16 v[78:81], v[160:163], v[220:223], v[78:81]
	v_mfma_f32_16x16x32_bf16 v[74:77], v[168:171], v[220:223], v[74:77]
	s_setprio 0
	s_setprio 1
	v_mfma_f32_16x16x32_bf16 v[118:121], v[172:175], v[188:191], v[118:121]
	v_mfma_f32_16x16x32_bf16 v[114:117], v[180:183], v[188:191], v[114:117]
	v_mfma_f32_16x16x32_bf16 v[102:105], v[172:175], v[196:199], v[102:105]
	v_mfma_f32_16x16x32_bf16 v[98:101], v[180:183], v[196:199], v[98:101]
	v_mfma_f32_16x16x32_bf16 v[86:89], v[172:175], v[208:211], v[86:89]
	v_mfma_f32_16x16x32_bf16 v[82:85], v[180:183], v[208:211], v[82:85]
	v_mfma_f32_16x16x32_bf16 v[70:73], v[172:175], v[216:219], v[70:73]
	v_mfma_f32_16x16x32_bf16 v[66:69], v[180:183], v[216:219], v[66:69]
	v_mfma_f32_16x16x32_bf16 v[118:121], v[176:179], v[192:195], v[118:121]
	v_mfma_f32_16x16x32_bf16 v[114:117], v[184:187], v[192:195], v[114:117]
	v_mfma_f32_16x16x32_bf16 v[102:105], v[176:179], v[200:203], v[102:105]
	v_mfma_f32_16x16x32_bf16 v[98:101], v[184:187], v[200:203], v[98:101]
	v_mfma_f32_16x16x32_bf16 v[86:89], v[176:179], v[212:215], v[86:89]
	v_mfma_f32_16x16x32_bf16 v[82:85], v[184:187], v[212:215], v[82:85]
	v_mfma_f32_16x16x32_bf16 v[70:73], v[176:179], v[220:223], v[70:73]
	v_mfma_f32_16x16x32_bf16 v[66:69], v[184:187], v[220:223], v[66:69]
	s_setprio 0
	s_barrier
; #define PG8_STAGE(bufoff, gbase, voff) do { _Pragma("unroll") for (int _i = 0; _i < 2; ++_i) \
;         __builtin_amdgcn_global_load_lds((const unsigned*)((const char*)(gbase) + (voff)[_i]), (PG8_LAS unsigned*)(lds + (bufoff) + ldsw + _i * 8192), 16, 0, 0); } while (0)
; #define PG8_LDA(dst, b, h) do { _Pragma("unroll") for (int m = 0; m < 4; ++m) _Pragma("unroll") for (int k = 0; k < 2; ++k) dst[m][k] = *(const PG8_LAS bf16x8*)(lds + PG8_SA(b, h) + aoff + m * 2048 + k * 1024); } while (0)
; #define PG8_MMA(ai, bj, At, Bt) do { __builtin_amdgcn_s_setprio(1); _Pragma("unroll") for (int m = 0; m < 4; ++m) _Pragma("unroll") for (int n = 0; n < 2; ++n) _Pragma("unroll") for (int k = 0; k < 2; ++k) \
;         acc[ai][bj][m][n] = __builtin_amdgcn_mfma_f32_16x16x32_bf16(Bt[n][k], At[m][k], acc[ai][bj][m][n], 0, 0, 0); __builtin_amdgcn_s_setprio(0); } while (0)
; #define PG8_WAIT_V(n) asm volatile("s_waitcnt vmcnt(" #n ")" ::: "memory")
; #define PG8_WAIT_L(n) asm volatile("s_waitcnt lgkmcnt(" #n ")" ::: "memory")
; #define PG8_BAR __builtin_amdgcn_s_barrier()
; #define PG8_SCHED __builtin_amdgcn_sched_barrier(0)
; template <class Epi, class Sched, bool ALIGN_EPI = false, bool SP2 = false>
; __device__ __forceinline__ void gemm_phase(PG8_LAS unsigned char* lds, const Gemm g, const Sched& S, const Epi& E) {
;     ...
;             PG8_LDA(At, 1, 1); PG8_STAGE(PG8_SB(1, 0), b3, voffB); PG8_STAGE(PG8_SB(1, 1), b3 + hstep, voffB); PG8_STAGE(PG8_SA(1, 0), a3, voffA);
;             PG8_WAIT_V(8); PG8_WAIT_L(0); PG8_BAR; PG8_MMA(1, 0, At, B0); PG8_MMA(1, 1, At, B1); PG8_BAR; PG8_SCHED;
	s_add_i32 s44, s72, s47
	s_mov_b32 m0, s44
	ds_read_b128 v[188:191], v154 offset:49152
	ds_read_b128 v[192:195], v154 offset:50176
	ds_read_b128 v[196:199], v154 offset:51200
	ds_read_b128 v[200:203], v154 offset:52224
	ds_read_b128 v[208:211], v154 offset:53248
	ds_read_b128 v[212:215], v154 offset:54272
	ds_read_b128 v[216:219], v154 offset:55296
	ds_read_b128 v[220:223], v154 offset:56320
	s_add_u32 s98, s40, s12
	s_addc_u32 s99, s41, s13
	global_load_lds_dwordx4 v132, s[98:99]
	s_add_i32 m0, s44, 0x2000
	s_add_u32 s40, s40, 0x40080
	v_lshl_add_u64 v[148:149], v[204:205], 0, s[12:13]
	s_addc_u32 s41, s41, 0
	s_add_i32 s44, s73, s47
	global_load_lds_dwordx4 v[148:149], off
	s_mov_b32 m0, s44
	s_nop 0
	global_load_lds_dwordx4 v132, s[40:41]
	s_add_i32 m0, s44, 0x2000
	s_nop 0
	global_load_lds_dwordx4 v136, s[40:41]
	v_lshl_add_u64 v[148:149], v[224:225], 0, s[12:13]
	s_mov_b32 m0, s61
	s_nop 0
	global_load_lds_dwordx4 v[148:149], off
	v_lshl_add_u64 v[148:149], v[226:227], 0, s[12:13]
	s_mov_b32 m0, s62
	s_nop 0
	global_load_lds_dwordx4 v[148:149], off
	s_waitcnt vmcnt(8)
	s_waitcnt lgkmcnt(0)
	s_barrier
	s_setprio 1
	s_waitcnt lgkmcnt(0)
	v_mfma_f32_16x16x32_bf16 v[62:65], v[156:159], v[188:191], v[62:65]
	v_mfma_f32_16x16x32_bf16 v[58:61], v[164:167], v[188:191], v[58:61]
	v_mfma_f32_16x16x32_bf16 v[46:49], v[156:159], v[196:199], v[46:49]
	v_mfma_f32_16x16x32_bf16 v[42:45], v[164:167], v[196:199], v[42:45]
	v_mfma_f32_16x16x32_bf16 v[30:33], v[156:159], v[208:211], v[30:33]
	v_mfma_f32_16x16x32_bf16 v[26:29], v[164:167], v[208:211], v[26:29]
	v_mfma_f32_16x16x32_bf16 v[14:17], v[156:159], v[216:219], v[14:17]
	v_mfma_f32_16x16x32_bf16 v[10:13], v[164:167], v[216:219], v[10:13]
	v_mfma_f32_16x16x32_bf16 v[62:65], v[160:163], v[192:195], v[62:65]
	v_mfma_f32_16x16x32_bf16 v[58:61], v[168:171], v[192:195], v[58:61]
	v_mfma_f32_16x16x32_bf16 v[46:49], v[160:163], v[200:203], v[46:49]
	v_mfma_f32_16x16x32_bf16 v[42:45], v[168:171], v[200:203], v[42:45]
	v_mfma_f32_16x16x32_bf16 v[30:33], v[160:163], v[212:215], v[30:33]
	v_mfma_f32_16x16x32_bf16 v[26:29], v[168:171], v[212:215], v[26:29]
	v_mfma_f32_16x16x32_bf16 v[14:17], v[160:163], v[220:223], v[14:17]
	v_mfma_f32_16x16x32_bf16 v[10:13], v[168:171], v[220:223], v[10:13]
	s_setprio 0
	s_setprio 1
	v_mfma_f32_16x16x32_bf16 v[54:57], v[172:175], v[188:191], v[54:57]
	v_mfma_f32_16x16x32_bf16 v[50:53], v[180:183], v[188:191], v[50:53]
	v_mfma_f32_16x16x32_bf16 v[38:41], v[172:175], v[196:199], v[38:41]
	v_mfma_f32_16x16x32_bf16 v[34:37], v[180:183], v[196:199], v[34:37]
	v_mfma_f32_16x16x32_bf16 v[22:25], v[172:175], v[208:211], v[22:25]
	v_mfma_f32_16x16x32_bf16 v[18:21], v[180:183], v[208:211], v[18:21]
	v_mfma_f32_16x16x32_bf16 v[6:9], v[172:175], v[216:219], v[6:9]
	v_mfma_f32_16x16x32_bf16 v[2:5], v[180:183], v[216:219], v[2:5]
	v_mfma_f32_16x16x32_bf16 v[54:57], v[176:179], v[192:195], v[54:57]
	v_mfma_f32_16x16x32_bf16 v[50:53], v[184:187], v[192:195], v[50:53]
	v_mfma_f32_16x16x32_bf16 v[38:41], v[176:179], v[200:203], v[38:41]
	v_mfma_f32_16x16x32_bf16 v[34:37], v[184:187], v[200:203], v[34:37]
	v_mfma_f32_16x16x32_bf16 v[22:25], v[176:179], v[212:215], v[22:25]
	v_mfma_f32_16x16x32_bf16 v[18:21], v[184:187], v[212:215], v[18:21]
	v_mfma_f32_16x16x32_bf16 v[6:9], v[176:179], v[220:223], v[6:9]
	v_mfma_f32_16x16x32_bf16 v[2:5], v[184:187], v[220:223], v[2:5]
	s_setprio 0
	s_add_i32 s71, s71, 2
	s_add_u32 s30, s30, 0x100
	s_addc_u32 s31, s31, 0
	s_add_u32 s33, s33, 0x100
	s_addc_u32 s70, s70, 0
	s_cmp_gt_u32 s71, 13
	s_barrier
	s_cbranch_scc0 .LBB0_740
	s_and_b64 vcc, exec, s[14:15]
	s_cbranch_vccz .LBB0_743
	s_barrier

; #define PG8_STAGE(bufoff, gbase, voff) do { _Pragma("unroll") for (int _i = 0; _i < 2; ++_i) \
;         __builtin_amdgcn_global_load_lds((const unsigned*)((const char*)(gbase) + (voff)[_i]), (PG8_LAS unsigned*)(lds + (bufoff) + ldsw + _i * 8192), 16, 0, 0); } while (0)
; #define PG8_LDA(dst, b, h) do { _Pragma("unroll") for (int m = 0; m < 4; ++m) _Pragma("unroll") for (int k = 0; k < 2; ++k) dst[m][k] = *(const PG8_LAS bf16x8*)(lds + PG8_SA(b, h) + aoff + m * 2048 + k * 1024); } while (0)
; #define PG8_LDB(dst, b, h) do { _Pragma("unroll") for (int n = 0; n < 2; ++n) _Pragma("unroll") for (int k = 0; k < 2; ++k) dst[n][k] = *(const PG8_LAS bf16x8*)(lds + PG8_SB(b, h) + boff + n * 2048 + k * 1024); } while (0)
; #define PG8_MMA(ai, bj, At, Bt) do { __builtin_amdgcn_s_setprio(1); _Pragma("unroll") for (int m = 0; m < 4; ++m) _Pragma("unroll") for (int n = 0; n < 2; ++n) _Pragma("unroll") for (int k = 0; k < 2; ++k) \
;         acc[ai][bj][m][n] = __builtin_amdgcn_mfma_f32_16x16x32_bf16(Bt[n][k], At[m][k], acc[ai][bj][m][n], 0, 0, 0); __builtin_amdgcn_s_setprio(0); } while (0)
; #define PG8_WAIT_V(n) asm volatile("s_waitcnt vmcnt(" #n ")" ::: "memory")
; #define PG8_WAIT_L(n) asm volatile("s_waitcnt lgkmcnt(" #n ")" ::: "memory")
; #define PG8_BAR __builtin_amdgcn_s_barrier()
; #define PG8_SCHED __builtin_amdgcn_sched_barrier(0)
; template <class Epi, class Sched, bool ALIGN_EPI = false, bool SP2 = false>
; __device__ __forceinline__ void gemm_phase(PG8_LAS unsigned char* lds, const Gemm g, const Sched& S, const Epi& E) {
;     ...
;             PG8_LDB(B0, 0, 0); PG8_LDB(B1, 0, 1); PG8_SCHED; PG8_LDA(At, 0, 0); PG8_STAGE(PG8_SA(1, 1), a1 + hstep, voffA);
;             PG8_WAIT_V(8); PG8_WAIT_L(0); PG8_BAR; PG8_MMA(0, 0, At, B0); PG8_MMA(0, 1, At, B1); PG8_BAR; PG8_SCHED;
;             PG8_LDA(At, 0, 1); PG8_STAGE(PG8_SB(0, 0), b2, voffB); PG8_STAGE(PG8_SB(0, 1), b2 + hstep, voffB); PG8_STAGE(PG8_SA(0, 0), a2, voffA);
.LBB0_861:
	ds_read_b128 v[146:149], v153
	ds_read_b128 v[156:159], v153 offset:1024
	ds_read_b128 v[160:163], v153 offset:2048
	ds_read_b128 v[164:167], v153 offset:3072
	ds_read_b128 v[168:171], v154
	ds_read_b128 v[172:175], v154 offset:1024
	ds_read_b128 v[176:179], v154 offset:2048
	ds_read_b128 v[180:183], v154 offset:3072
	s_add_u32 s26, s24, 0xfff50080
	s_addc_u32 s27, s25, -1
	s_cmp_eq_u32 s53, 40
	s_cselect_b32 s29, s5, s27
	s_cselect_b32 s28, s4, s26
	s_cselect_b32 s27, s23, s52
	s_cselect_b32 s26, s22, s51
	v_lshl_add_u64 v[150:151], s[24:25], 0, v[138:139]
	s_add_i32 m0, s33, 0xc000
	ds_read_b128 v[184:187], v155
	ds_read_b128 v[188:191], v155 offset:1024
	ds_read_b128 v[192:195], v155 offset:2048
	ds_read_b128 v[196:199], v155 offset:3072
	ds_read_b128 v[200:203], v155 offset:4096
	ds_read_b128 v[204:207], v155 offset:5120
	ds_read_b128 v[208:211], v155 offset:6144
	ds_read_b128 v[212:215], v155 offset:7168
	global_load_lds_dwordx4 v[150:151], off
	v_lshl_add_u64 v[150:151], s[24:25], 0, v[140:141]
	s_add_i32 m0, s33, 0xe000
	s_nop 0
	global_load_lds_dwordx4 v[150:151], off
	s_waitcnt vmcnt(8)
	s_waitcnt lgkmcnt(0)
	s_barrier
	s_setprio 1
	s_waitcnt lgkmcnt(0)
	v_mfma_f32_16x16x32_bf16 v[124:127], v[146:149], v[184:187], v[124:127]
	v_mfma_f32_16x16x32_bf16 v[120:123], v[160:163], v[184:187], v[120:123]
	v_mfma_f32_16x16x32_bf16 v[108:111], v[146:149], v[192:195], v[108:111]
	v_mfma_f32_16x16x32_bf16 v[104:107], v[160:163], v[192:195], v[104:107]
	v_mfma_f32_16x16x32_bf16 v[92:95], v[146:149], v[200:203], v[92:95]
	v_mfma_f32_16x16x32_bf16 v[88:91], v[160:163], v[200:203], v[88:91]
	v_mfma_f32_16x16x32_bf16 v[76:79], v[146:149], v[208:211], v[76:79]
	v_mfma_f32_16x16x32_bf16 v[72:75], v[160:163], v[208:211], v[72:75]
	v_mfma_f32_16x16x32_bf16 v[124:127], v[156:159], v[188:191], v[124:127]
	v_mfma_f32_16x16x32_bf16 v[120:123], v[164:167], v[188:191], v[120:123]
	v_mfma_f32_16x16x32_bf16 v[108:111], v[156:159], v[196:199], v[108:111]
	v_mfma_f32_16x16x32_bf16 v[104:107], v[164:167], v[196:199], v[104:107]
	v_mfma_f32_16x16x32_bf16 v[92:95], v[156:159], v[204:207], v[92:95]
	v_mfma_f32_16x16x32_bf16 v[88:91], v[164:167], v[204:207], v[88:91]
	v_mfma_f32_16x16x32_bf16 v[76:79], v[156:159], v[212:215], v[76:79]
	v_mfma_f32_16x16x32_bf16 v[72:75], v[164:167], v[212:215], v[72:75]
	s_setprio 0
	s_setprio 1
	v_mfma_f32_16x16x32_bf16 v[116:119], v[168:171], v[184:187], v[116:119]
	v_mfma_f32_16x16x32_bf16 v[112:115], v[176:179], v[184:187], v[112:115]
	v_mfma_f32_16x16x32_bf16 v[100:103], v[168:171], v[192:195], v[100:103]
	v_mfma_f32_16x16x32_bf16 v[96:99], v[176:179], v[192:195], v[96:99]
	v_mfma_f32_16x16x32_bf16 v[84:87], v[168:171], v[200:203], v[84:87]
	v_mfma_f32_16x16x32_bf16 v[80:83], v[176:179], v[200:203], v[80:83]
	v_mfma_f32_16x16x32_bf16 v[68:71], v[168:171], v[208:211], v[68:71]
	v_mfma_f32_16x16x32_bf16 v[64:67], v[176:179], v[208:211], v[64:67]
	v_mfma_f32_16x16x32_bf16 v[116:119], v[172:175], v[188:191], v[116:119]
	v_mfma_f32_16x16x32_bf16 v[112:115], v[180:183], v[188:191], v[112:115]
	v_mfma_f32_16x16x32_bf16 v[100:103], v[172:175], v[196:199], v[100:103]
	v_mfma_f32_16x16x32_bf16 v[96:99], v[180:183], v[196:199], v[96:99]
	v_mfma_f32_16x16x32_bf16 v[84:87], v[172:175], v[204:207], v[84:87]
	v_mfma_f32_16x16x32_bf16 v[80:83], v[180:183], v[204:207], v[80:83]
	v_mfma_f32_16x16x32_bf16 v[68:71], v[172:175], v[212:215], v[68:71]
	v_mfma_f32_16x16x32_bf16 v[64:67], v[180:183], v[212:215], v[64:67]
	s_setprio 0
	s_barrier
	s_add_i32 s56, s45, s31
	s_mov_b32 m0, s56
	ds_read_b128 v[184:187], v155 offset:16384
	ds_read_b128 v[188:191], v155 offset:17408
	ds_read_b128 v[192:195], v155 offset:18432
	ds_read_b128 v[196:199], v155 offset:19456
	ds_read_b128 v[200:203], v155 offset:20480
	ds_read_b128 v[204:207], v155 offset:21504
	ds_read_b128 v[208:211], v155 offset:22528
	ds_read_b128 v[212:215], v155 offset:23552
	global_load_lds_dwordx4 v130, s[26:27]
	s_add_i32 m0, s56, 0x2000
	s_add_u32 s56, s26, 0xb0000
	v_lshl_add_u64 v[216:217], s[26:27], 0, v[134:135]
	s_addc_u32 s57, s27, 0
	s_add_i32 s58, s46, s31
	global_load_lds_dwordx4 v134, s[26:27]
	s_mov_b32 m0, s58
	v_lshl_add_u64 v[220:221], s[28:29], 0, v[132:133]
	global_load_lds_dwordx4 v130, s[56:57]
	s_add_i32 m0, s58, 0x2000
	s_nop 0
	global_load_lds_dwordx4 v134, s[56:57]
	v_lshl_add_u64 v[218:219], s[28:29], 0, v[128:129]
	s_mov_b32 m0, s33
	s_nop 0
	global_load_lds_dwordx4 v128, s[28:29]
	s_mov_b32 m0, s36
	s_nop 0
	global_load_lds_dwordx4 v132, s[28:29]
	s_waitcnt vmcnt(8)
	s_waitcnt lgkmcnt(0)
	s_barrier
; #define PG8_STAGE(bufoff, gbase, voff) do { _Pragma("unroll") for (int _i = 0; _i < 2; ++_i) \
;         __builtin_amdgcn_global_load_lds((const unsigned*)((const char*)(gbase) + (voff)[_i]), (PG8_LAS unsigned*)(lds + (bufoff) + ldsw + _i * 8192), 16, 0, 0); } while (0)
; #define PG8_LDA(dst, b, h) do { _Pragma("unroll") for (int m = 0; m < 4; ++m) _Pragma("unroll") for (int k = 0; k < 2; ++k) dst[m][k] = *(const PG8_LAS bf16x8*)(lds + PG8_SA(b, h) + aoff + m * 2048 + k * 1024); } while (0)
; #define PG8_LDB(dst, b, h) do { _Pragma("unroll") for (int n = 0; n < 2; ++n) _Pragma("unroll") for (int k = 0; k < 2; ++k) dst[n][k] = *(const PG8_LAS bf16x8*)(lds + PG8_SB(b, h) + boff + n * 2048 + k * 1024); } while (0)
; #define PG8_MMA(ai, bj, At, Bt) do { __builtin_amdgcn_s_setprio(1); _Pragma("unroll") for (int m = 0; m < 4; ++m) _Pragma("unroll") for (int n = 0; n < 2; ++n) _Pragma("unroll") for (int k = 0; k < 2; ++k) \
;         acc[ai][bj][m][n] = __builtin_amdgcn_mfma_f32_16x16x32_bf16(Bt[n][k], At[m][k], acc[ai][bj][m][n], 0, 0, 0); __builtin_amdgcn_s_setprio(0); } while (0)
; #define PG8_WAIT_V(n) asm volatile("s_waitcnt vmcnt(" #n ")" ::: "memory")
; #define PG8_WAIT_L(n) asm volatile("s_waitcnt lgkmcnt(" #n ")" ::: "memory")
; #define PG8_BAR __builtin_amdgcn_s_barrier()
; #define PG8_SCHED __builtin_amdgcn_sched_barrier(0)
; template <class Epi, class Sched, bool ALIGN_EPI = false, bool SP2 = false>
; __device__ __forceinline__ void gemm_phase(PG8_LAS unsigned char* lds, const Gemm g, const Sched& S, const Epi& E) {
;     ...
;             PG8_WAIT_V(8); PG8_WAIT_L(0); PG8_BAR; PG8_MMA(1, 0, At, B0); PG8_MMA(1, 1, At, B1); PG8_BAR; PG8_SCHED;
;             PG8_LDB(B0, 1, 0); PG8_LDB(B1, 1, 1); PG8_SCHED; PG8_LDA(At, 1, 0); PG8_STAGE(PG8_SA(0, 1), a2 + hstep, voffA);
;             PG8_WAIT_V(8); PG8_WAIT_L(0); PG8_BAR; PG8_MMA(0, 0, At, B0); PG8_MMA(0, 1, At, B1); PG8_BAR; PG8_SCHED;
	s_setprio 1
	s_waitcnt lgkmcnt(0)
	v_mfma_f32_16x16x32_bf16 v[60:63], v[146:149], v[184:187], v[60:63]
	v_mfma_f32_16x16x32_bf16 v[56:59], v[160:163], v[184:187], v[56:59]
	v_mfma_f32_16x16x32_bf16 v[44:47], v[146:149], v[192:195], v[44:47]
	v_mfma_f32_16x16x32_bf16 v[40:43], v[160:163], v[192:195], v[40:43]
	v_mfma_f32_16x16x32_bf16 v[28:31], v[146:149], v[200:203], v[28:31]
	v_mfma_f32_16x16x32_bf16 v[24:27], v[160:163], v[200:203], v[24:27]
	v_mfma_f32_16x16x32_bf16 v[12:15], v[146:149], v[208:211], v[12:15]
	v_mfma_f32_16x16x32_bf16 v[8:11], v[160:163], v[208:211], v[8:11]
	v_mfma_f32_16x16x32_bf16 v[60:63], v[156:159], v[188:191], v[60:63]
	v_mfma_f32_16x16x32_bf16 v[56:59], v[164:167], v[188:191], v[56:59]
	v_mfma_f32_16x16x32_bf16 v[44:47], v[156:159], v[196:199], v[44:47]
	v_mfma_f32_16x16x32_bf16 v[40:43], v[164:167], v[196:199], v[40:43]
	v_mfma_f32_16x16x32_bf16 v[28:31], v[156:159], v[204:207], v[28:31]
	v_mfma_f32_16x16x32_bf16 v[24:27], v[164:167], v[204:207], v[24:27]
	v_mfma_f32_16x16x32_bf16 v[12:15], v[156:159], v[212:215], v[12:15]
	v_mfma_f32_16x16x32_bf16 v[8:11], v[164:167], v[212:215], v[8:11]
	s_setprio 0
	s_setprio 1
	v_mfma_f32_16x16x32_bf16 v[52:55], v[168:171], v[184:187], v[52:55]
	v_mfma_f32_16x16x32_bf16 v[48:51], v[176:179], v[184:187], v[48:51]
	v_mfma_f32_16x16x32_bf16 v[36:39], v[168:171], v[192:195], v[36:39]
	v_mfma_f32_16x16x32_bf16 v[32:35], v[176:179], v[192:195], v[32:35]
	v_mfma_f32_16x16x32_bf16 v[20:23], v[168:171], v[200:203], v[20:23]
	v_mfma_f32_16x16x32_bf16 v[16:19], v[176:179], v[200:203], v[16:19]
	v_mfma_f32_16x16x32_bf16 v[4:7], v[168:171], v[208:211], v[4:7]
	v_mfma_f32_16x16x32_bf16 v[0:3], v[176:179], v[208:211], v[0:3]
	v_mfma_f32_16x16x32_bf16 v[52:55], v[172:175], v[188:191], v[52:55]
	v_mfma_f32_16x16x32_bf16 v[48:51], v[180:183], v[188:191], v[48:51]
	v_mfma_f32_16x16x32_bf16 v[36:39], v[172:175], v[196:199], v[36:39]
	v_mfma_f32_16x16x32_bf16 v[32:35], v[180:183], v[196:199], v[32:35]
	v_mfma_f32_16x16x32_bf16 v[20:23], v[172:175], v[204:207], v[20:23]
	v_mfma_f32_16x16x32_bf16 v[16:19], v[180:183], v[204:207], v[16:19]
	v_mfma_f32_16x16x32_bf16 v[4:7], v[172:175], v[212:215], v[4:7]
	v_mfma_f32_16x16x32_bf16 v[0:3], v[180:183], v[212:215], v[0:3]
	s_setprio 0
	s_barrier
	s_add_i32 s56, 0, 0x18000
	s_add_i32 s57, 0, 0x1c000
	v_add_u32_e32 v164, s56, v152
	v_add_u32_e32 v180, s57, v152
	ds_read_b128 v[146:149], v164
	ds_read_b128 v[156:159], v164 offset:1024
	ds_read_b128 v[160:163], v164 offset:2048
	ds_read_b128 v[164:167], v164 offset:3072
	ds_read_b128 v[168:171], v180
	ds_read_b128 v[172:175], v180 offset:1024
	ds_read_b128 v[176:179], v180 offset:2048
	ds_read_b128 v[180:183], v180 offset:3072
	s_add_u32 s28, s28, 0xb0000
	s_addc_u32 s29, s29, 0
	s_mov_b32 m0, s37
	ds_read_b128 v[184:187], v155 offset:32768
	ds_read_b128 v[188:191], v155 offset:33792
	ds_read_b128 v[192:195], v155 offset:34816
	ds_read_b128 v[196:199], v155 offset:35840
	ds_read_b128 v[200:203], v155 offset:36864
	ds_read_b128 v[204:207], v155 offset:37888
	ds_read_b128 v[208:211], v155 offset:38912
	ds_read_b128 v[212:215], v155 offset:39936
	global_load_lds_dwordx4 v128, s[28:29]
	s_mov_b32 m0, s38
	s_nop 0
	global_load_lds_dwordx4 v132, s[28:29]
	s_waitcnt vmcnt(8)
	s_waitcnt lgkmcnt(0)
	s_barrier
	s_setprio 1
	s_waitcnt lgkmcnt(0)
	v_mfma_f32_16x16x32_bf16 v[124:127], v[146:149], v[184:187], v[124:127]
	v_mfma_f32_16x16x32_bf16 v[120:123], v[160:163], v[184:187], v[120:123]
	v_mfma_f32_16x16x32_bf16 v[108:111], v[146:149], v[192:195], v[108:111]
	v_mfma_f32_16x16x32_bf16 v[104:107], v[160:163], v[192:195], v[104:107]
	v_mfma_f32_16x16x32_bf16 v[92:95], v[146:149], v[200:203], v[92:95]
	v_mfma_f32_16x16x32_bf16 v[88:91], v[160:163], v[200:203], v[88:91]
	v_mfma_f32_16x16x32_bf16 v[76:79], v[146:149], v[208:211], v[76:79]
	v_mfma_f32_16x16x32_bf16 v[72:75], v[160:163], v[208:211], v[72:75]
	v_mfma_f32_16x16x32_bf16 v[124:127], v[156:159], v[188:191], v[124:127]
	v_mfma_f32_16x16x32_bf16 v[120:123], v[164:167], v[188:191], v[120:123]
	v_mfma_f32_16x16x32_bf16 v[108:111], v[156:159], v[196:199], v[108:111]
	v_mfma_f32_16x16x32_bf16 v[104:107], v[164:167], v[196:199], v[104:107]
	v_mfma_f32_16x16x32_bf16 v[92:95], v[156:159], v[204:207], v[92:95]
	v_mfma_f32_16x16x32_bf16 v[88:91], v[164:167], v[204:207], v[88:91]
	v_mfma_f32_16x16x32_bf16 v[76:79], v[156:159], v[212:215], v[76:79]
	v_mfma_f32_16x16x32_bf16 v[72:75], v[164:167], v[212:215], v[72:75]
	s_setprio 0
	s_setprio 1
	v_mfma_f32_16x16x32_bf16 v[116:119], v[168:171], v[184:187], v[116:119]
	v_mfma_f32_16x16x32_bf16 v[112:115], v[176:179], v[184:187], v[112:115]
	v_mfma_f32_16x16x32_bf16 v[100:103], v[168:171], v[192:195], v[100:103]
	v_mfma_f32_16x16x32_bf16 v[96:99], v[176:179], v[192:195], v[96:99]
	v_mfma_f32_16x16x32_bf16 v[84:87], v[168:171], v[200:203], v[84:87]
	v_mfma_f32_16x16x32_bf16 v[80:83], v[176:179], v[200:203], v[80:83]
	v_mfma_f32_16x16x32_bf16 v[68:71], v[168:171], v[208:211], v[68:71]
	v_mfma_f32_16x16x32_bf16 v[64:67], v[176:179], v[208:211], v[64:67]
	v_mfma_f32_16x16x32_bf16 v[116:119], v[172:175], v[188:191], v[116:119]
	v_mfma_f32_16x16x32_bf16 v[112:115], v[180:183], v[188:191], v[112:115]
	v_mfma_f32_16x16x32_bf16 v[100:103], v[172:175], v[196:199], v[100:103]
	v_mfma_f32_16x16x32_bf16 v[96:99], v[180:183], v[196:199], v[96:99]
	v_mfma_f32_16x16x32_bf16 v[84:87], v[172:175], v[204:207], v[84:87]
	v_mfma_f32_16x16x32_bf16 v[80:83], v[180:183], v[204:207], v[80:83]
	v_mfma_f32_16x16x32_bf16 v[68:71], v[172:175], v[212:215], v[68:71]
	v_mfma_f32_16x16x32_bf16 v[64:67], v[180:183], v[212:215], v[64:67]
	s_setprio 0
	s_barrier
; #define PG8_STAGE(bufoff, gbase, voff) do { _Pragma("unroll") for (int _i = 0; _i < 2; ++_i) \
;         __builtin_amdgcn_global_load_lds((const unsigned*)((const char*)(gbase) + (voff)[_i]), (PG8_LAS unsigned*)(lds + (bufoff) + ldsw + _i * 8192), 16, 0, 0); } while (0)
; #define PG8_LDA(dst, b, h) do { _Pragma("unroll") for (int m = 0; m < 4; ++m) _Pragma("unroll") for (int k = 0; k < 2; ++k) dst[m][k] = *(const PG8_LAS bf16x8*)(lds + PG8_SA(b, h) + aoff + m * 2048 + k * 1024); } while (0)
; #define PG8_MMA(ai, bj, At, Bt) do { __builtin_amdgcn_s_setprio(1); _Pragma("unroll") for (int m = 0; m < 4; ++m) _Pragma("unroll") for (int n = 0; n < 2; ++n) _Pragma("unroll") for (int k = 0; k < 2; ++k) \
;         acc[ai][bj][m][n] = __builtin_amdgcn_mfma_f32_16x16x32_bf16(Bt[n][k], At[m][k], acc[ai][bj][m][n], 0, 0, 0); __builtin_amdgcn_s_setprio(0); } while (0)
; #define PG8_WAIT_V(n) asm volatile("s_waitcnt vmcnt(" #n ")" ::: "memory")
; #define PG8_WAIT_L(n) asm volatile("s_waitcnt lgkmcnt(" #n ")" ::: "memory")
; #define PG8_BAR __builtin_amdgcn_s_barrier()
; #define PG8_SCHED __builtin_amdgcn_sched_barrier(0)
; template <class Epi, class Sched, bool ALIGN_EPI = false, bool SP2 = false>
; __device__ __forceinline__ void gemm_phase(PG8_LAS unsigned char* lds, const Gemm g, const Sched& S, const Epi& E) {
;     ...
;             PG8_LDA(At, 1, 1); PG8_STAGE(PG8_SB(1, 0), b3, voffB); PG8_STAGE(PG8_SB(1, 1), b3 + hstep, voffB); PG8_STAGE(PG8_SA(1, 0), a3, voffA);
;             PG8_WAIT_V(8); PG8_WAIT_L(0); PG8_BAR; PG8_MMA(1, 0, At, B0); PG8_MMA(1, 1, At, B1); PG8_BAR; PG8_SCHED;
	s_add_i32 s28, s56, s31
	s_mov_b32 m0, s28
	ds_read_b128 v[184:187], v155 offset:49152
	ds_read_b128 v[188:191], v155 offset:50176
	ds_read_b128 v[192:195], v155 offset:51200
	ds_read_b128 v[196:199], v155 offset:52224
	ds_read_b128 v[200:203], v155 offset:53248
	ds_read_b128 v[204:207], v155 offset:54272
	ds_read_b128 v[208:211], v155 offset:55296
	ds_read_b128 v[212:215], v155 offset:56320
	s_add_u32 s98, s26, s10
	s_addc_u32 s99, s27, s11
	global_load_lds_dwordx4 v130, s[98:99]
	s_add_i32 m0, s28, 0x2000
	s_add_u32 s26, s26, 0xb0080
	v_lshl_add_u64 v[150:151], v[216:217], 0, s[10:11]
	s_addc_u32 s27, s27, 0
	s_add_i32 s28, s57, s31
	global_load_lds_dwordx4 v[150:151], off
	s_mov_b32 m0, s28
	s_nop 0
	global_load_lds_dwordx4 v130, s[26:27]
	s_add_i32 m0, s28, 0x2000
	s_nop 0
	global_load_lds_dwordx4 v134, s[26:27]
	v_lshl_add_u64 v[150:151], v[218:219], 0, s[10:11]
	s_mov_b32 m0, s40
	s_nop 0
	global_load_lds_dwordx4 v[150:151], off
	v_lshl_add_u64 v[150:151], v[220:221], 0, s[10:11]
	s_mov_b32 m0, s41
	s_nop 0
	global_load_lds_dwordx4 v[150:151], off
	s_waitcnt vmcnt(8)
	s_waitcnt lgkmcnt(0)
	s_barrier
	s_setprio 1
	s_waitcnt lgkmcnt(0)
	v_mfma_f32_16x16x32_bf16 v[60:63], v[146:149], v[184:187], v[60:63]
	v_mfma_f32_16x16x32_bf16 v[56:59], v[160:163], v[184:187], v[56:59]
	v_mfma_f32_16x16x32_bf16 v[44:47], v[146:149], v[192:195], v[44:47]
	v_mfma_f32_16x16x32_bf16 v[40:43], v[160:163], v[192:195], v[40:43]
	v_mfma_f32_16x16x32_bf16 v[28:31], v[146:149], v[200:203], v[28:31]
	v_mfma_f32_16x16x32_bf16 v[24:27], v[160:163], v[200:203], v[24:27]
	v_mfma_f32_16x16x32_bf16 v[12:15], v[146:149], v[208:211], v[12:15]
	v_mfma_f32_16x16x32_bf16 v[8:11], v[160:163], v[208:211], v[8:11]
	v_mfma_f32_16x16x32_bf16 v[60:63], v[156:159], v[188:191], v[60:63]
	v_mfma_f32_16x16x32_bf16 v[56:59], v[164:167], v[188:191], v[56:59]
	v_mfma_f32_16x16x32_bf16 v[44:47], v[156:159], v[196:199], v[44:47]
	v_mfma_f32_16x16x32_bf16 v[40:43], v[164:167], v[196:199], v[40:43]
	v_mfma_f32_16x16x32_bf16 v[28:31], v[156:159], v[204:207], v[28:31]
	v_mfma_f32_16x16x32_bf16 v[24:27], v[164:167], v[204:207], v[24:27]
	v_mfma_f32_16x16x32_bf16 v[12:15], v[156:159], v[212:215], v[12:15]
	v_mfma_f32_16x16x32_bf16 v[8:11], v[164:167], v[212:215], v[8:11]
	s_setprio 0
	s_setprio 1
	v_mfma_f32_16x16x32_bf16 v[52:55], v[168:171], v[184:187], v[52:55]
	v_mfma_f32_16x16x32_bf16 v[48:51], v[176:179], v[184:187], v[48:51]
	v_mfma_f32_16x16x32_bf16 v[36:39], v[168:171], v[192:195], v[36:39]
	v_mfma_f32_16x16x32_bf16 v[32:35], v[176:179], v[192:195], v[32:35]
	v_mfma_f32_16x16x32_bf16 v[20:23], v[168:171], v[200:203], v[20:23]
	v_mfma_f32_16x16x32_bf16 v[16:19], v[176:179], v[200:203], v[16:19]
	v_mfma_f32_16x16x32_bf16 v[4:7], v[168:171], v[208:211], v[4:7]
	v_mfma_f32_16x16x32_bf16 v[0:3], v[176:179], v[208:211], v[0:3]
	v_mfma_f32_16x16x32_bf16 v[52:55], v[172:175], v[188:191], v[52:55]
	v_mfma_f32_16x16x32_bf16 v[48:51], v[180:183], v[188:191], v[48:51]
	v_mfma_f32_16x16x32_bf16 v[36:39], v[172:175], v[196:199], v[36:39]
	v_mfma_f32_16x16x32_bf16 v[32:35], v[180:183], v[196:199], v[32:35]
	v_mfma_f32_16x16x32_bf16 v[20:23], v[172:175], v[204:207], v[20:23]
	v_mfma_f32_16x16x32_bf16 v[16:19], v[180:183], v[204:207], v[16:19]
	v_mfma_f32_16x16x32_bf16 v[4:7], v[172:175], v[212:215], v[4:7]
	v_mfma_f32_16x16x32_bf16 v[0:3], v[180:183], v[212:215], v[0:3]
	s_setprio 0
	s_add_i32 s53, s53, 2
	s_add_u32 s24, s24, 0x100
	s_addc_u32 s25, s25, 0
	s_add_u32 s51, s51, 0x100
	s_addc_u32 s52, s52, 0
	s_cmp_gt_u32 s53, 41
	s_barrier
	s_cbranch_scc0 .LBB0_861
	s_and_b64 vcc, exec, s[12:13]
	s_cbranch_vccz .LBB0_864
	s_barrier

; template <bool COOP>
; __global__ void __launch_bounds__(NWAVES * 64, 2) fwd(Args args) {
	.amdhsa_kernel _Z3fwdILb1EEv4Args
		.amdhsa_group_segment_fixed_size 0
		.amdhsa_private_segment_fixed_size 0
		.amdhsa_kernarg_size 384
		.amdhsa_user_sgpr_count 2
		.amdhsa_user_sgpr_dispatch_ptr 0
		.amdhsa_user_sgpr_queue_ptr 0
		.amdhsa_user_sgpr_kernarg_segment_ptr 1
		.amdhsa_user_sgpr_dispatch_id 0
		.amdhsa_user_sgpr_kernarg_preload_length 0
		.amdhsa_user_sgpr_kernarg_preload_offset 0
		.amdhsa_user_sgpr_private_segment_size 0
		.amdhsa_uses_dynamic_stack 0
		.amdhsa_enable_private_segment 0
		.amdhsa_system_sgpr_workgroup_id_x 1
		.amdhsa_system_sgpr_workgroup_id_y 0
		.amdhsa_system_sgpr_workgroup_id_z 0
		.amdhsa_system_sgpr_workgroup_info 0
		.amdhsa_system_vgpr_workitem_id 0
		.amdhsa_next_free_vgpr 239
		.amdhsa_next_free_sgpr 102
		.amdhsa_accum_offset 240
		.amdhsa_reserve_vcc 1
		.amdhsa_float_round_mode_32 0
		.amdhsa_float_round_mode_16_64 0
		.amdhsa_float_denorm_mode_32 3
		.amdhsa_float_denorm_mode_16_64 3
		.amdhsa_dx10_clamp 1
		.amdhsa_ieee_mode 1
		.amdhsa_fp16_overflow 0
		.amdhsa_tg_split 0
		.amdhsa_exception_fp_ieee_invalid_op 0
		.amdhsa_exception_fp_denorm_src 0
		.amdhsa_exception_fp_ieee_div_zero 0
		.amdhsa_exception_fp_ieee_overflow 0
		.amdhsa_exception_fp_ieee_underflow 0
		.amdhsa_exception_fp_ieee_inexact 0
		.amdhsa_exception_int_div_zero 0
	.end_amdhsa_kernel

; template <bool COOP>
; __global__ void __launch_bounds__(NWAVES * 64, 2) fwd(Args args) {
amdhsa.kernels:
  - .agpr_count:     0
    .args:
      - .offset:         0
        .size:           128
        .value_kind:     by_value
      - .offset:         128
        .size:           4
        .value_kind:     hidden_block_count_x
      - .offset:         132
        .size:           4
        .value_kind:     hidden_block_count_y
      - .offset:         136
        .size:           4
        .value_kind:     hidden_block_count_z
      - .offset:         140
        .size:           2
        .value_kind:     hidden_group_size_x
      - .offset:         142
        .size:           2
        .value_kind:     hidden_group_size_y
      - .offset:         144
        .size:           2
        .value_kind:     hidden_group_size_z
      - .offset:         146
        .size:           2
        .value_kind:     hidden_remainder_x
      - .offset:         148
        .size:           2
        .value_kind:     hidden_remainder_y
      - .offset:         150
        .size:           2
        .value_kind:     hidden_remainder_z
      - .offset:         168
        .size:           8
        .value_kind:     hidden_global_offset_x
      - .offset:         176
        .size:           8
        .value_kind:     hidden_global_offset_y
      - .offset:         184
        .size:           8
        .value_kind:     hidden_global_offset_z
      - .offset:         192
        .size:           2
        .value_kind:     hidden_grid_dims
      - .offset:         248
        .size:           4
        .value_kind:     hidden_dynamic_lds_size
    .group_segment_fixed_size: 0
    .kernarg_segment_align: 8
    .kernarg_segment_size: 384
    .language:       OpenCL C
    .language_version:
      - 2
      - 0
    .max_flat_workgroup_size: 512
    .name:           _Z3fwdILb1EEv4Args
    .private_segment_fixed_size: 0
    .sgpr_count:     108
    .sgpr_spill_count: 16
    .symbol:         _Z3fwdILb1EEv4Args.kd
    .uniform_work_group_size: 1
    .uses_dynamic_stack: false
    .vgpr_count:     239
    .vgpr_spill_count: 0
    .wavefront_size: 64
  - .agpr_count:     0
    .args:
      - .offset:         0
        .size:           128
        .value_kind:     by_value
      - .offset:         128
        .size:           4
        .value_kind:     hidden_block_count_x
      - .offset:         132
        .size:           4
        .value_kind:     hidden_block_count_y
      - .offset:         136
        .size:           4
        .value_kind:     hidden_block_count_z
      - .offset:         140
        .size:           2
        .value_kind:     hidden_group_size_x
      - .offset:         142
        .size:           2
        .value_kind:     hidden_group_size_y
      - .offset:         144
        .size:           2
        .value_kind:     hidden_group_size_z
      - .offset:         146
        .size:           2
        .value_kind:     hidden_remainder_x
      - .offset:         148
        .size:           2
        .value_kind:     hidden_remainder_y
      - .offset:         150
        .size:           2
        .value_kind:     hidden_remainder_z
      - .offset:         168
        .size:           8
        .value_kind:     hidden_global_offset_x
      - .offset:         176
        .size:           8
        .value_kind:     hidden_global_offset_y
      - .offset:         184
        .size:           8
        .value_kind:     hidden_global_offset_z
      - .offset:         192
        .size:           2
        .value_kind:     hidden_grid_dims
      - .offset:         248
        .size:           4
        .value_kind:     hidden_dynamic_lds_size
    .group_segment_fixed_size: 0
    .kernarg_segment_align: 8
    .kernarg_segment_size: 384
    .language:       OpenCL C
    .language_version:
      - 2
      - 0
    .max_flat_workgroup_size: 512
    .name:           _Z3fwdILb0EEv4Args
    .private_segment_fixed_size: 0
    .sgpr_count:     104
    .sgpr_spill_count: 0
    .symbol:         _Z3fwdILb0EEv4Args.kd
    .uniform_work_group_size: 1
    .uses_dynamic_stack: false
    .vgpr_count:     238
    .vgpr_spill_count: 0
    .wavefront_size: 64
